# merged 32-MFMA blocks, accumulator pairs k0 then k1 (bit-identical accumulation order), m-major
# baseline (speedup 1.0000x reference)
.LBB0_142:
	ds_read_b128 v[168:171], v165
	ds_read_b128 v[172:175], v165 offset:1024
	ds_read_b128 v[176:179], v165 offset:2048
	ds_read_b128 v[180:183], v165 offset:3072
	ds_read_b128 v[184:187], v166
	ds_read_b128 v[188:191], v166 offset:1024
	ds_read_b128 v[192:195], v166 offset:2048
	ds_read_b128 v[196:199], v166 offset:3072
	s_add_i32 s54, s22, 2
	s_add_u32 s55, s20, 0x80
	s_addc_u32 s23, s21, 0
	s_cmp_eq_u32 s42, s22
	s_cselect_b32 s22, s4, s55
	s_cselect_b32 s23, s5, s23
	s_cselect_b32 s61, s19, s53
	s_cselect_b32 s60, s18, s52
	v_lshl_add_u64 v[234:235], s[20:21], 0, v[154:155]
	s_add_i32 m0, s31, 0xc000
	ds_read_b128 v[200:203], v167
	ds_read_b128 v[204:207], v167 offset:1024
	ds_read_b128 v[208:211], v167 offset:2048
	ds_read_b128 v[212:215], v167 offset:3072
	ds_read_b128 v[216:219], v167 offset:4096
	ds_read_b128 v[222:225], v167 offset:5120
	ds_read_b128 v[226:229], v167 offset:6144
	ds_read_b128 v[230:233], v167 offset:7168
	global_load_lds_dwordx4 v[234:235], off
	v_lshl_add_u64 v[234:235], s[20:21], 0, v[156:157]
	s_add_i32 m0, s31, 0xe000
	s_nop 0
	global_load_lds_dwordx4 v[234:235], off
	s_waitcnt vmcnt(8)
	s_waitcnt lgkmcnt(0)
	s_barrier
	s_setprio 1
	s_waitcnt lgkmcnt(0)
	v_mfma_f32_16x16x32_bf16 v[120:123], v[168:171], v[200:203], v[120:123]
	v_mfma_f32_16x16x32_bf16 v[120:123], v[172:175], v[204:207], v[120:123]
	v_mfma_f32_16x16x32_bf16 v[116:119], v[176:179], v[200:203], v[116:119]
	v_mfma_f32_16x16x32_bf16 v[116:119], v[180:183], v[204:207], v[116:119]
	v_mfma_f32_16x16x32_bf16 v[124:127], v[184:187], v[200:203], v[124:127]
	v_mfma_f32_16x16x32_bf16 v[124:127], v[188:191], v[204:207], v[124:127]
	v_mfma_f32_16x16x32_bf16 v[112:115], v[192:195], v[200:203], v[112:115]
	v_mfma_f32_16x16x32_bf16 v[112:115], v[196:199], v[204:207], v[112:115]
	v_mfma_f32_16x16x32_bf16 v[96:99], v[192:195], v[208:211], v[96:99]
	v_mfma_f32_16x16x32_bf16 v[96:99], v[196:199], v[212:215], v[96:99]
	v_mfma_f32_16x16x32_bf16 v[104:107], v[184:187], v[208:211], v[104:107]
	v_mfma_f32_16x16x32_bf16 v[104:107], v[188:191], v[212:215], v[104:107]
	v_mfma_f32_16x16x32_bf16 v[100:103], v[176:179], v[208:211], v[100:103]
	v_mfma_f32_16x16x32_bf16 v[100:103], v[180:183], v[212:215], v[100:103]
	v_mfma_f32_16x16x32_bf16 v[108:111], v[168:171], v[208:211], v[108:111]
	v_mfma_f32_16x16x32_bf16 v[108:111], v[172:175], v[212:215], v[108:111]
	v_mfma_f32_16x16x32_bf16 v[92:95], v[168:171], v[216:219], v[92:95]
	v_mfma_f32_16x16x32_bf16 v[92:95], v[172:175], v[222:225], v[92:95]
	v_mfma_f32_16x16x32_bf16 v[84:87], v[176:179], v[216:219], v[84:87]
	v_mfma_f32_16x16x32_bf16 v[84:87], v[180:183], v[222:225], v[84:87]
	v_mfma_f32_16x16x32_bf16 v[88:91], v[184:187], v[216:219], v[88:91]
	v_mfma_f32_16x16x32_bf16 v[88:91], v[188:191], v[222:225], v[88:91]
	v_mfma_f32_16x16x32_bf16 v[80:83], v[192:195], v[216:219], v[80:83]
	v_mfma_f32_16x16x32_bf16 v[80:83], v[196:199], v[222:225], v[80:83]
	v_mfma_f32_16x16x32_bf16 v[64:67], v[192:195], v[226:229], v[64:67]
	v_mfma_f32_16x16x32_bf16 v[64:67], v[196:199], v[230:233], v[64:67]
	v_mfma_f32_16x16x32_bf16 v[72:75], v[184:187], v[226:229], v[72:75]
	v_mfma_f32_16x16x32_bf16 v[72:75], v[188:191], v[230:233], v[72:75]
	v_mfma_f32_16x16x32_bf16 v[68:71], v[176:179], v[226:229], v[68:71]
	v_mfma_f32_16x16x32_bf16 v[68:71], v[180:183], v[230:233], v[68:71]
	v_mfma_f32_16x16x32_bf16 v[76:79], v[168:171], v[226:229], v[76:79]
	v_mfma_f32_16x16x32_bf16 v[76:79], v[172:175], v[230:233], v[76:79]
	s_setprio 0
	s_barrier
	s_add_i32 s55, s46, s28
	v_lshl_add_u64 v[234:235], s[60:61], 0, v[132:133]
	s_mov_b32 m0, s55
	ds_read_b128 v[200:203], v167 offset:16384
	ds_read_b128 v[204:207], v167 offset:17408
	ds_read_b128 v[208:211], v167 offset:18432
	ds_read_b128 v[212:215], v167 offset:19456
	ds_read_b128 v[216:219], v167 offset:20480
	ds_read_b128 v[222:225], v167 offset:21504
	ds_read_b128 v[226:229], v167 offset:22528
	ds_read_b128 v[230:233], v167 offset:23552
	global_load_lds_dwordx4 v[234:235], off
	s_add_i32 m0, s55, 0x2000
	v_lshl_add_u64 v[236:237], s[60:61], 0, v[128:129]
	s_add_u32 s60, s60, s10
	s_addc_u32 s61, s61, s11
	s_add_i32 s55, s47, s28
	global_load_lds_dwordx4 v[236:237], off
	v_lshl_add_u64 v[238:239], s[60:61], 0, v[132:133]
	s_mov_b32 m0, s55
	v_lshl_add_u64 v[240:241], s[60:61], 0, v[128:129]
	global_load_lds_dwordx4 v[238:239], off
	s_add_i32 m0, s55, 0x2000
	v_lshl_add_u64 v[242:243], s[22:23], 0, v[134:135]
	global_load_lds_dwordx4 v[240:241], off
	s_mov_b32 m0, s31
	v_lshl_add_u64 v[244:245], s[22:23], 0, v[130:131]
	global_load_lds_dwordx4 v[242:243], off
	s_mov_b32 m0, s33
	s_nop 0
	global_load_lds_dwordx4 v[244:245], off
	s_waitcnt vmcnt(8)
	s_waitcnt lgkmcnt(0)
	s_barrier
	s_setprio 1
	s_waitcnt lgkmcnt(0)
	v_mfma_f32_16x16x32_bf16 v[60:63], v[168:171], v[200:203], v[60:63]
	v_mfma_f32_16x16x32_bf16 v[60:63], v[172:175], v[204:207], v[60:63]
	v_mfma_f32_16x16x32_bf16 v[52:55], v[176:179], v[200:203], v[52:55]
	v_mfma_f32_16x16x32_bf16 v[52:55], v[180:183], v[204:207], v[52:55]
	v_mfma_f32_16x16x32_bf16 v[56:59], v[184:187], v[200:203], v[56:59]
	v_mfma_f32_16x16x32_bf16 v[56:59], v[188:191], v[204:207], v[56:59]
	v_mfma_f32_16x16x32_bf16 v[48:51], v[192:195], v[200:203], v[48:51]
	v_mfma_f32_16x16x32_bf16 v[48:51], v[196:199], v[204:207], v[48:51]
	v_mfma_f32_16x16x32_bf16 v[32:35], v[192:195], v[208:211], v[32:35]
	v_mfma_f32_16x16x32_bf16 v[32:35], v[196:199], v[212:215], v[32:35]
	v_mfma_f32_16x16x32_bf16 v[40:43], v[184:187], v[208:211], v[40:43]
	v_mfma_f32_16x16x32_bf16 v[40:43], v[188:191], v[212:215], v[40:43]
	v_mfma_f32_16x16x32_bf16 v[36:39], v[176:179], v[208:211], v[36:39]
	v_mfma_f32_16x16x32_bf16 v[36:39], v[180:183], v[212:215], v[36:39]
	v_mfma_f32_16x16x32_bf16 v[44:47], v[168:171], v[208:211], v[44:47]
	v_mfma_f32_16x16x32_bf16 v[44:47], v[172:175], v[212:215], v[44:47]
	v_mfma_f32_16x16x32_bf16 v[28:31], v[168:171], v[216:219], v[28:31]
	v_mfma_f32_16x16x32_bf16 v[28:31], v[172:175], v[222:225], v[28:31]
	v_mfma_f32_16x16x32_bf16 v[20:23], v[176:179], v[216:219], v[20:23]
	v_mfma_f32_16x16x32_bf16 v[20:23], v[180:183], v[222:225], v[20:23]
	v_mfma_f32_16x16x32_bf16 v[24:27], v[184:187], v[216:219], v[24:27]
	v_mfma_f32_16x16x32_bf16 v[24:27], v[188:191], v[222:225], v[24:27]
	v_mfma_f32_16x16x32_bf16 v[16:19], v[192:195], v[216:219], v[16:19]
	v_mfma_f32_16x16x32_bf16 v[16:19], v[196:199], v[222:225], v[16:19]
	v_mfma_f32_16x16x32_bf16 v[0:3], v[192:195], v[226:229], v[0:3]
	v_mfma_f32_16x16x32_bf16 v[0:3], v[196:199], v[230:233], v[0:3]
	v_mfma_f32_16x16x32_bf16 v[8:11], v[184:187], v[226:229], v[8:11]
	v_mfma_f32_16x16x32_bf16 v[8:11], v[188:191], v[230:233], v[8:11]
	v_mfma_f32_16x16x32_bf16 v[4:7], v[176:179], v[226:229], v[4:7]
	v_mfma_f32_16x16x32_bf16 v[4:7], v[180:183], v[230:233], v[4:7]
	v_mfma_f32_16x16x32_bf16 v[12:15], v[168:171], v[226:229], v[12:15]
	v_mfma_f32_16x16x32_bf16 v[12:15], v[172:175], v[230:233], v[12:15]
	s_setprio 0
	s_barrier
	s_add_i32 s55, 0, 0x18000
	s_add_i32 s60, 0, 0x1c000
	v_add_u32_e32 v180, s55, v164
	v_add_u32_e32 v196, s60, v164
	ds_read_b128 v[168:171], v180
	ds_read_b128 v[172:175], v180 offset:1024
	ds_read_b128 v[176:179], v180 offset:2048
	ds_read_b128 v[180:183], v180 offset:3072
	ds_read_b128 v[184:187], v196
	ds_read_b128 v[188:191], v196 offset:1024
	ds_read_b128 v[192:195], v196 offset:2048
	ds_read_b128 v[196:199], v196 offset:3072
	s_add_u32 s22, s22, s10
	s_addc_u32 s23, s23, s11
	s_mov_b32 m0, s34
	v_lshl_add_u64 v[246:247], s[22:23], 0, v[134:135]
	ds_read_b128 v[200:203], v167 offset:32768
	ds_read_b128 v[204:207], v167 offset:33792
	ds_read_b128 v[208:211], v167 offset:34816
	ds_read_b128 v[212:215], v167 offset:35840
	ds_read_b128 v[216:219], v167 offset:36864
	ds_read_b128 v[222:225], v167 offset:37888
	ds_read_b128 v[226:229], v167 offset:38912
	ds_read_b128 v[230:233], v167 offset:39936
	global_load_lds_dwordx4 v[246:247], off
	v_lshl_add_u64 v[246:247], s[22:23], 0, v[130:131]
	s_mov_b32 m0, s35
	s_nop 0
	global_load_lds_dwordx4 v[246:247], off
	s_waitcnt vmcnt(8)
	s_waitcnt lgkmcnt(0)
	s_barrier
	s_setprio 1
	s_waitcnt lgkmcnt(0)
	v_mfma_f32_16x16x32_bf16 v[120:123], v[168:171], v[200:203], v[120:123]
	v_mfma_f32_16x16x32_bf16 v[120:123], v[172:175], v[204:207], v[120:123]
	v_mfma_f32_16x16x32_bf16 v[116:119], v[176:179], v[200:203], v[116:119]
	v_mfma_f32_16x16x32_bf16 v[116:119], v[180:183], v[204:207], v[116:119]
	v_mfma_f32_16x16x32_bf16 v[124:127], v[184:187], v[200:203], v[124:127]
	v_mfma_f32_16x16x32_bf16 v[124:127], v[188:191], v[204:207], v[124:127]
	v_mfma_f32_16x16x32_bf16 v[112:115], v[192:195], v[200:203], v[112:115]
	v_mfma_f32_16x16x32_bf16 v[112:115], v[196:199], v[204:207], v[112:115]
	v_mfma_f32_16x16x32_bf16 v[96:99], v[192:195], v[208:211], v[96:99]
	v_mfma_f32_16x16x32_bf16 v[96:99], v[196:199], v[212:215], v[96:99]
	v_mfma_f32_16x16x32_bf16 v[104:107], v[184:187], v[208:211], v[104:107]
	v_mfma_f32_16x16x32_bf16 v[104:107], v[188:191], v[212:215], v[104:107]
	v_mfma_f32_16x16x32_bf16 v[100:103], v[176:179], v[208:211], v[100:103]
	v_mfma_f32_16x16x32_bf16 v[100:103], v[180:183], v[212:215], v[100:103]
	v_mfma_f32_16x16x32_bf16 v[108:111], v[168:171], v[208:211], v[108:111]
	v_mfma_f32_16x16x32_bf16 v[108:111], v[172:175], v[212:215], v[108:111]
	v_mfma_f32_16x16x32_bf16 v[92:95], v[168:171], v[216:219], v[92:95]
	v_mfma_f32_16x16x32_bf16 v[92:95], v[172:175], v[222:225], v[92:95]
	v_mfma_f32_16x16x32_bf16 v[84:87], v[176:179], v[216:219], v[84:87]
	v_mfma_f32_16x16x32_bf16 v[84:87], v[180:183], v[222:225], v[84:87]
	v_mfma_f32_16x16x32_bf16 v[88:91], v[184:187], v[216:219], v[88:91]
	v_mfma_f32_16x16x32_bf16 v[88:91], v[188:191], v[222:225], v[88:91]
	v_mfma_f32_16x16x32_bf16 v[80:83], v[192:195], v[216:219], v[80:83]
	v_mfma_f32_16x16x32_bf16 v[80:83], v[196:199], v[222:225], v[80:83]
	v_mfma_f32_16x16x32_bf16 v[64:67], v[192:195], v[226:229], v[64:67]
	v_mfma_f32_16x16x32_bf16 v[64:67], v[196:199], v[230:233], v[64:67]
	v_mfma_f32_16x16x32_bf16 v[72:75], v[184:187], v[226:229], v[72:75]
	v_mfma_f32_16x16x32_bf16 v[72:75], v[188:191], v[230:233], v[72:75]
	v_mfma_f32_16x16x32_bf16 v[68:71], v[176:179], v[226:229], v[68:71]
	v_mfma_f32_16x16x32_bf16 v[68:71], v[180:183], v[230:233], v[68:71]
	v_mfma_f32_16x16x32_bf16 v[76:79], v[168:171], v[226:229], v[76:79]
	v_mfma_f32_16x16x32_bf16 v[76:79], v[172:175], v[230:233], v[76:79]
	s_setprio 0
	s_barrier
	s_add_i32 s22, s55, s28
	v_lshl_add_u64 v[234:235], v[234:235], 0, s[14:15]
	s_mov_b32 m0, s22
	ds_read_b128 v[200:203], v167 offset:49152
	ds_read_b128 v[204:207], v167 offset:50176
	ds_read_b128 v[208:211], v167 offset:51200
	ds_read_b128 v[212:215], v167 offset:52224
	ds_read_b128 v[216:219], v167 offset:53248
	ds_read_b128 v[222:225], v167 offset:54272
	ds_read_b128 v[226:229], v167 offset:55296
	ds_read_b128 v[230:233], v167 offset:56320
	global_load_lds_dwordx4 v[234:235], off
	v_lshl_add_u64 v[234:235], v[236:237], 0, s[14:15]
	s_add_i32 m0, s22, 0x2000
	s_add_i32 s22, s60, s28
	global_load_lds_dwordx4 v[234:235], off
	v_lshl_add_u64 v[234:235], v[238:239], 0, s[14:15]
	s_mov_b32 m0, s22
	s_nop 0
	global_load_lds_dwordx4 v[234:235], off
	v_lshl_add_u64 v[234:235], v[240:241], 0, s[14:15]
	s_add_i32 m0, s22, 0x2000
	s_nop 0
	global_load_lds_dwordx4 v[234:235], off
	v_lshl_add_u64 v[234:235], v[242:243], 0, s[14:15]
	s_mov_b32 m0, s39
	s_nop 0
	global_load_lds_dwordx4 v[234:235], off
	v_lshl_add_u64 v[234:235], v[244:245], 0, s[14:15]
	s_mov_b32 m0, s40
	s_nop 0
	global_load_lds_dwordx4 v[234:235], off
	s_waitcnt vmcnt(8)
	s_waitcnt lgkmcnt(0)
	s_barrier
	s_setprio 1
	s_waitcnt lgkmcnt(0)
	v_mfma_f32_16x16x32_bf16 v[60:63], v[168:171], v[200:203], v[60:63]
	v_mfma_f32_16x16x32_bf16 v[60:63], v[172:175], v[204:207], v[60:63]
	v_mfma_f32_16x16x32_bf16 v[52:55], v[176:179], v[200:203], v[52:55]
	v_mfma_f32_16x16x32_bf16 v[52:55], v[180:183], v[204:207], v[52:55]
	v_mfma_f32_16x16x32_bf16 v[56:59], v[184:187], v[200:203], v[56:59]
	v_mfma_f32_16x16x32_bf16 v[56:59], v[188:191], v[204:207], v[56:59]
	v_mfma_f32_16x16x32_bf16 v[48:51], v[192:195], v[200:203], v[48:51]
	v_mfma_f32_16x16x32_bf16 v[48:51], v[196:199], v[204:207], v[48:51]
	v_mfma_f32_16x16x32_bf16 v[32:35], v[192:195], v[208:211], v[32:35]
	v_mfma_f32_16x16x32_bf16 v[32:35], v[196:199], v[212:215], v[32:35]
	v_mfma_f32_16x16x32_bf16 v[40:43], v[184:187], v[208:211], v[40:43]
	v_mfma_f32_16x16x32_bf16 v[40:43], v[188:191], v[212:215], v[40:43]
	v_mfma_f32_16x16x32_bf16 v[36:39], v[176:179], v[208:211], v[36:39]
	v_mfma_f32_16x16x32_bf16 v[36:39], v[180:183], v[212:215], v[36:39]
	v_mfma_f32_16x16x32_bf16 v[44:47], v[168:171], v[208:211], v[44:47]
	v_mfma_f32_16x16x32_bf16 v[44:47], v[172:175], v[212:215], v[44:47]
	v_mfma_f32_16x16x32_bf16 v[28:31], v[168:171], v[216:219], v[28:31]
	v_mfma_f32_16x16x32_bf16 v[28:31], v[172:175], v[222:225], v[28:31]
	v_mfma_f32_16x16x32_bf16 v[20:23], v[176:179], v[216:219], v[20:23]
	v_mfma_f32_16x16x32_bf16 v[20:23], v[180:183], v[222:225], v[20:23]
	v_mfma_f32_16x16x32_bf16 v[24:27], v[184:187], v[216:219], v[24:27]
	v_mfma_f32_16x16x32_bf16 v[24:27], v[188:191], v[222:225], v[24:27]
	v_mfma_f32_16x16x32_bf16 v[16:19], v[192:195], v[216:219], v[16:19]
	v_mfma_f32_16x16x32_bf16 v[16:19], v[196:199], v[222:225], v[16:19]
	v_mfma_f32_16x16x32_bf16 v[0:3], v[192:195], v[226:229], v[0:3]
	v_mfma_f32_16x16x32_bf16 v[0:3], v[196:199], v[230:233], v[0:3]
	v_mfma_f32_16x16x32_bf16 v[8:11], v[184:187], v[226:229], v[8:11]
	v_mfma_f32_16x16x32_bf16 v[8:11], v[188:191], v[230:233], v[8:11]
	v_mfma_f32_16x16x32_bf16 v[4:7], v[176:179], v[226:229], v[4:7]
	v_mfma_f32_16x16x32_bf16 v[4:7], v[180:183], v[230:233], v[4:7]
	v_mfma_f32_16x16x32_bf16 v[12:15], v[168:171], v[226:229], v[12:15]
	v_mfma_f32_16x16x32_bf16 v[12:15], v[172:175], v[230:233], v[12:15]
	s_setprio 0
	s_barrier
	s_add_u32 s20, s20, 0x100
	s_addc_u32 s21, s21, 0
	s_add_u32 s52, s52, 0x100
	s_addc_u32 s53, s53, 0
	s_cmp_ge_i32 s54, s41
	s_mov_b32 s22, s54
	s_cbranch_scc0 .LBB0_142

.LBB0_228:
	ds_read_b128 v[140:143], v219
	ds_read_b128 v[144:147], v219 offset:1024
	ds_read_b128 v[148:151], v219 offset:2048
	ds_read_b128 v[152:155], v219 offset:3072
	ds_read_b128 v[156:159], v221
	ds_read_b128 v[164:167], v221 offset:1024
	ds_read_b128 v[168:171], v221 offset:2048
	ds_read_b128 v[172:175], v221 offset:3072
	s_add_i32 s62, s26, 2
	s_add_u32 s27, s24, 0x4000
	s_addc_u32 s28, s25, 0
	s_cmp_eq_u32 s46, s26
	s_cselect_b32 s30, s0, s27
	s_cselect_b32 s31, s1, s28
	s_cselect_b32 s28, s22, s60
	s_cselect_b32 s29, s23, s61
	s_add_u32 s26, s30, 0x8000
	s_addc_u32 s27, s31, 0
	v_lshl_add_u64 v[160:161], s[24:25], 0, v[132:133]
	s_add_i32 m0, s38, 0xc000
	ds_read_b128 v[176:179], v222
	ds_read_b128 v[180:183], v222 offset:1024
	ds_read_b128 v[184:187], v222 offset:2048
	ds_read_b128 v[188:191], v222 offset:3072
	ds_read_b128 v[192:195], v222 offset:4096
	ds_read_b128 v[196:199], v222 offset:5120
	ds_read_b128 v[200:203], v222 offset:6144
	ds_read_b128 v[204:207], v222 offset:7168
	global_load_lds_dwordx4 v[160:161], off
	v_lshl_add_u64 v[160:161], s[24:25], 0, v[134:135]
	s_add_i32 m0, s38, 0xe000
	s_nop 0
	global_load_lds_dwordx4 v[160:161], off
	s_waitcnt vmcnt(8)
	s_waitcnt lgkmcnt(0)
	s_barrier
	s_setprio 1
	s_waitcnt lgkmcnt(0)
	v_mfma_f32_16x16x32_bf16 v[124:127], v[140:143], v[176:179], v[124:127]
	v_mfma_f32_16x16x32_bf16 v[124:127], v[144:147], v[180:183], v[124:127]
	v_mfma_f32_16x16x32_bf16 v[120:123], v[148:151], v[176:179], v[120:123]
	v_mfma_f32_16x16x32_bf16 v[120:123], v[152:155], v[180:183], v[120:123]
	v_mfma_f32_16x16x32_bf16 v[108:111], v[156:159], v[176:179], v[108:111]
	v_mfma_f32_16x16x32_bf16 v[108:111], v[164:167], v[180:183], v[108:111]
	v_mfma_f32_16x16x32_bf16 v[100:103], v[168:171], v[176:179], v[100:103]
	v_mfma_f32_16x16x32_bf16 v[100:103], v[172:175], v[180:183], v[100:103]
	v_mfma_f32_16x16x32_bf16 v[84:87], v[168:171], v[184:187], v[84:87]
	v_mfma_f32_16x16x32_bf16 v[84:87], v[172:175], v[188:191], v[84:87]
	v_mfma_f32_16x16x32_bf16 v[92:95], v[156:159], v[184:187], v[92:95]
	v_mfma_f32_16x16x32_bf16 v[92:95], v[164:167], v[188:191], v[92:95]
	v_mfma_f32_16x16x32_bf16 v[112:115], v[148:151], v[184:187], v[112:115]
	v_mfma_f32_16x16x32_bf16 v[112:115], v[152:155], v[188:191], v[112:115]
	v_mfma_f32_16x16x32_bf16 v[116:119], v[140:143], v[184:187], v[116:119]
	v_mfma_f32_16x16x32_bf16 v[116:119], v[144:147], v[188:191], v[116:119]
	v_mfma_f32_16x16x32_bf16 v[104:107], v[140:143], v[192:195], v[104:107]
	v_mfma_f32_16x16x32_bf16 v[104:107], v[144:147], v[196:199], v[104:107]
	v_mfma_f32_16x16x32_bf16 v[96:99], v[148:151], v[192:195], v[96:99]
	v_mfma_f32_16x16x32_bf16 v[96:99], v[152:155], v[196:199], v[96:99]
	v_mfma_f32_16x16x32_bf16 v[76:79], v[156:159], v[192:195], v[76:79]
	v_mfma_f32_16x16x32_bf16 v[76:79], v[164:167], v[196:199], v[76:79]
	v_mfma_f32_16x16x32_bf16 v[72:75], v[168:171], v[192:195], v[72:75]
	v_mfma_f32_16x16x32_bf16 v[72:75], v[172:175], v[196:199], v[72:75]
	v_mfma_f32_16x16x32_bf16 v[64:67], v[168:171], v[200:203], v[64:67]
	v_mfma_f32_16x16x32_bf16 v[64:67], v[172:175], v[204:207], v[64:67]
	v_mfma_f32_16x16x32_bf16 v[68:71], v[156:159], v[200:203], v[68:71]
	v_mfma_f32_16x16x32_bf16 v[68:71], v[164:167], v[204:207], v[68:71]
	v_mfma_f32_16x16x32_bf16 v[80:83], v[148:151], v[200:203], v[80:83]
	v_mfma_f32_16x16x32_bf16 v[80:83], v[152:155], v[204:207], v[80:83]
	v_mfma_f32_16x16x32_bf16 v[88:91], v[140:143], v[200:203], v[88:91]
	v_mfma_f32_16x16x32_bf16 v[88:91], v[144:147], v[204:207], v[88:91]
	s_setprio 0
	s_barrier
	s_add_i32 s63, s50, s37
	v_lshl_add_u64 v[160:161], s[28:29], 0, v[128:129]
	s_mov_b32 m0, s63
	ds_read_b128 v[176:179], v222 offset:16384
	ds_read_b128 v[180:183], v222 offset:17408
	ds_read_b128 v[184:187], v222 offset:18432
	ds_read_b128 v[188:191], v222 offset:19456
	ds_read_b128 v[192:195], v222 offset:20480
	ds_read_b128 v[196:199], v222 offset:21504
	ds_read_b128 v[200:203], v222 offset:22528
	ds_read_b128 v[204:207], v222 offset:23552
	global_load_lds_dwordx4 v[160:161], off
	s_add_i32 m0, s63, 0x2000
	s_add_u32 s64, s28, 0x4000
	v_lshl_add_u64 v[160:161], s[28:29], 0, v[130:131]
	s_addc_u32 s65, s29, 0
	s_add_i32 s63, s51, s37
	global_load_lds_dwordx4 v[160:161], off
	v_lshl_add_u64 v[160:161], s[64:65], 0, v[128:129]
	s_mov_b32 m0, s63
	s_nop 0
	global_load_lds_dwordx4 v[160:161], off
	v_lshl_add_u64 v[160:161], s[64:65], 0, v[130:131]
	s_add_i32 m0, s63, 0x2000
	s_nop 0
	global_load_lds_dwordx4 v[160:161], off
	v_lshl_add_u64 v[160:161], s[30:31], 0, v[128:129]
	s_mov_b32 m0, s38
	s_nop 0
	global_load_lds_dwordx4 v[160:161], off
	v_lshl_add_u64 v[160:161], s[30:31], 0, v[130:131]
	s_mov_b32 m0, s39
	s_nop 0
	global_load_lds_dwordx4 v[160:161], off
	s_waitcnt vmcnt(8)
	s_waitcnt lgkmcnt(0)
	s_barrier
	s_setprio 1
	s_waitcnt lgkmcnt(0)
	v_mfma_f32_16x16x32_bf16 v[60:63], v[140:143], v[176:179], v[60:63]
	v_mfma_f32_16x16x32_bf16 v[60:63], v[144:147], v[180:183], v[60:63]
	v_mfma_f32_16x16x32_bf16 v[56:59], v[148:151], v[176:179], v[56:59]
	v_mfma_f32_16x16x32_bf16 v[56:59], v[152:155], v[180:183], v[56:59]
	v_mfma_f32_16x16x32_bf16 v[44:47], v[156:159], v[176:179], v[44:47]
	v_mfma_f32_16x16x32_bf16 v[44:47], v[164:167], v[180:183], v[44:47]
	v_mfma_f32_16x16x32_bf16 v[36:39], v[168:171], v[176:179], v[36:39]
	v_mfma_f32_16x16x32_bf16 v[36:39], v[172:175], v[180:183], v[36:39]
	v_mfma_f32_16x16x32_bf16 v[20:23], v[168:171], v[184:187], v[20:23]
	v_mfma_f32_16x16x32_bf16 v[20:23], v[172:175], v[188:191], v[20:23]
	v_mfma_f32_16x16x32_bf16 v[28:31], v[156:159], v[184:187], v[28:31]
	v_mfma_f32_16x16x32_bf16 v[28:31], v[164:167], v[188:191], v[28:31]
	v_mfma_f32_16x16x32_bf16 v[48:51], v[148:151], v[184:187], v[48:51]
	v_mfma_f32_16x16x32_bf16 v[48:51], v[152:155], v[188:191], v[48:51]
	v_mfma_f32_16x16x32_bf16 v[52:55], v[140:143], v[184:187], v[52:55]
	v_mfma_f32_16x16x32_bf16 v[52:55], v[144:147], v[188:191], v[52:55]
	v_mfma_f32_16x16x32_bf16 v[40:43], v[140:143], v[192:195], v[40:43]
	v_mfma_f32_16x16x32_bf16 v[40:43], v[144:147], v[196:199], v[40:43]
	v_mfma_f32_16x16x32_bf16 v[32:35], v[148:151], v[192:195], v[32:35]
	v_mfma_f32_16x16x32_bf16 v[32:35], v[152:155], v[196:199], v[32:35]
	v_mfma_f32_16x16x32_bf16 v[12:15], v[156:159], v[192:195], v[12:15]
	v_mfma_f32_16x16x32_bf16 v[12:15], v[164:167], v[196:199], v[12:15]
	v_mfma_f32_16x16x32_bf16 v[8:11], v[168:171], v[192:195], v[8:11]
	v_mfma_f32_16x16x32_bf16 v[8:11], v[172:175], v[196:199], v[8:11]
	v_mfma_f32_16x16x32_bf16 v[0:3], v[168:171], v[200:203], v[0:3]
	v_mfma_f32_16x16x32_bf16 v[0:3], v[172:175], v[204:207], v[0:3]
	v_mfma_f32_16x16x32_bf16 v[4:7], v[156:159], v[200:203], v[4:7]
	v_mfma_f32_16x16x32_bf16 v[4:7], v[164:167], v[204:207], v[4:7]
	v_mfma_f32_16x16x32_bf16 v[16:19], v[148:151], v[200:203], v[16:19]
	v_mfma_f32_16x16x32_bf16 v[16:19], v[152:155], v[204:207], v[16:19]
	v_mfma_f32_16x16x32_bf16 v[24:27], v[140:143], v[200:203], v[24:27]
	v_mfma_f32_16x16x32_bf16 v[24:27], v[144:147], v[204:207], v[24:27]
	s_setprio 0
	s_barrier
	s_add_i32 s63, 0, 0x18000
	s_add_i32 s64, 0, 0x1c000
	v_add_u32_e32 v152, s63, v217
	v_add_u32_e32 v160, s64, v217
	ds_read_b128 v[140:143], v152
	ds_read_b128 v[144:147], v152 offset:1024
	ds_read_b128 v[148:151], v152 offset:2048
	ds_read_b128 v[152:155], v152 offset:3072
	ds_read_b128 v[156:159], v160
	ds_read_b128 v[164:167], v160 offset:1024
	ds_read_b128 v[168:171], v160 offset:2048
	ds_read_b128 v[172:175], v160 offset:3072
	s_add_u32 s30, s30, 0x4000
	s_addc_u32 s31, s31, 0
	s_mov_b32 m0, s40
	v_lshl_add_u64 v[160:161], s[30:31], 0, v[128:129]
	ds_read_b128 v[176:179], v222 offset:32768
	ds_read_b128 v[180:183], v222 offset:33792
	ds_read_b128 v[184:187], v222 offset:34816
	ds_read_b128 v[188:191], v222 offset:35840
	ds_read_b128 v[192:195], v222 offset:36864
	ds_read_b128 v[196:199], v222 offset:37888
	ds_read_b128 v[200:203], v222 offset:38912
	ds_read_b128 v[204:207], v222 offset:39936
	global_load_lds_dwordx4 v[160:161], off
	v_lshl_add_u64 v[160:161], s[30:31], 0, v[130:131]
	s_mov_b32 m0, s41
	s_nop 0
	global_load_lds_dwordx4 v[160:161], off
	s_waitcnt vmcnt(8)
	s_waitcnt lgkmcnt(0)
	s_barrier
	s_setprio 1
	s_waitcnt lgkmcnt(0)
	v_mfma_f32_16x16x32_bf16 v[124:127], v[140:143], v[176:179], v[124:127]
	v_mfma_f32_16x16x32_bf16 v[124:127], v[144:147], v[180:183], v[124:127]
	v_mfma_f32_16x16x32_bf16 v[120:123], v[148:151], v[176:179], v[120:123]
	v_mfma_f32_16x16x32_bf16 v[120:123], v[152:155], v[180:183], v[120:123]
	v_mfma_f32_16x16x32_bf16 v[108:111], v[156:159], v[176:179], v[108:111]
	v_mfma_f32_16x16x32_bf16 v[108:111], v[164:167], v[180:183], v[108:111]
	v_mfma_f32_16x16x32_bf16 v[100:103], v[168:171], v[176:179], v[100:103]
	v_mfma_f32_16x16x32_bf16 v[100:103], v[172:175], v[180:183], v[100:103]
	v_mfma_f32_16x16x32_bf16 v[84:87], v[168:171], v[184:187], v[84:87]
	v_mfma_f32_16x16x32_bf16 v[84:87], v[172:175], v[188:191], v[84:87]
	v_mfma_f32_16x16x32_bf16 v[92:95], v[156:159], v[184:187], v[92:95]
	v_mfma_f32_16x16x32_bf16 v[92:95], v[164:167], v[188:191], v[92:95]
	v_mfma_f32_16x16x32_bf16 v[112:115], v[148:151], v[184:187], v[112:115]
	v_mfma_f32_16x16x32_bf16 v[112:115], v[152:155], v[188:191], v[112:115]
	v_mfma_f32_16x16x32_bf16 v[116:119], v[140:143], v[184:187], v[116:119]
	v_mfma_f32_16x16x32_bf16 v[116:119], v[144:147], v[188:191], v[116:119]
	v_mfma_f32_16x16x32_bf16 v[104:107], v[140:143], v[192:195], v[104:107]
	v_mfma_f32_16x16x32_bf16 v[104:107], v[144:147], v[196:199], v[104:107]
	v_mfma_f32_16x16x32_bf16 v[96:99], v[148:151], v[192:195], v[96:99]
	v_mfma_f32_16x16x32_bf16 v[96:99], v[152:155], v[196:199], v[96:99]
	v_mfma_f32_16x16x32_bf16 v[76:79], v[156:159], v[192:195], v[76:79]
	v_mfma_f32_16x16x32_bf16 v[76:79], v[164:167], v[196:199], v[76:79]
	v_mfma_f32_16x16x32_bf16 v[72:75], v[168:171], v[192:195], v[72:75]
	v_mfma_f32_16x16x32_bf16 v[72:75], v[172:175], v[196:199], v[72:75]
	v_mfma_f32_16x16x32_bf16 v[64:67], v[168:171], v[200:203], v[64:67]
	v_mfma_f32_16x16x32_bf16 v[64:67], v[172:175], v[204:207], v[64:67]
	v_mfma_f32_16x16x32_bf16 v[68:71], v[156:159], v[200:203], v[68:71]
	v_mfma_f32_16x16x32_bf16 v[68:71], v[164:167], v[204:207], v[68:71]
	v_mfma_f32_16x16x32_bf16 v[80:83], v[148:151], v[200:203], v[80:83]
	v_mfma_f32_16x16x32_bf16 v[80:83], v[152:155], v[204:207], v[80:83]
	v_mfma_f32_16x16x32_bf16 v[88:91], v[140:143], v[200:203], v[88:91]
	v_mfma_f32_16x16x32_bf16 v[88:91], v[144:147], v[204:207], v[88:91]
	s_setprio 0
	s_barrier
	s_add_u32 s30, s28, 0x8000
	s_addc_u32 s31, s29, 0
	s_add_i32 s63, s63, s37
	v_lshl_add_u64 v[160:161], s[30:31], 0, v[128:129]
	s_mov_b32 m0, s63
	ds_read_b128 v[176:179], v222 offset:49152
	ds_read_b128 v[180:183], v222 offset:50176
	ds_read_b128 v[184:187], v222 offset:51200
	ds_read_b128 v[188:191], v222 offset:52224
	ds_read_b128 v[192:195], v222 offset:53248
	ds_read_b128 v[196:199], v222 offset:54272
	ds_read_b128 v[200:203], v222 offset:55296
	ds_read_b128 v[204:207], v222 offset:56320
	global_load_lds_dwordx4 v[160:161], off
	s_add_i32 m0, s63, 0x2000
	s_add_u32 s28, s28, 0xc000
	v_lshl_add_u64 v[160:161], s[30:31], 0, v[130:131]
	s_addc_u32 s29, s29, 0
	s_add_i32 s30, s64, s37
	global_load_lds_dwordx4 v[160:161], off
	v_lshl_add_u64 v[160:161], s[28:29], 0, v[128:129]
	s_mov_b32 m0, s30
	s_nop 0
	global_load_lds_dwordx4 v[160:161], off
	v_lshl_add_u64 v[160:161], s[28:29], 0, v[130:131]
	s_add_i32 m0, s30, 0x2000
	s_nop 0
	global_load_lds_dwordx4 v[160:161], off
	v_lshl_add_u64 v[160:161], s[26:27], 0, v[128:129]
	s_mov_b32 m0, s44
	s_nop 0
	global_load_lds_dwordx4 v[160:161], off
	v_lshl_add_u64 v[160:161], s[26:27], 0, v[130:131]
	s_mov_b32 m0, s45
	s_nop 0
	global_load_lds_dwordx4 v[160:161], off
	s_waitcnt vmcnt(8)
	s_waitcnt lgkmcnt(0)
	s_barrier
	s_setprio 1
	s_waitcnt lgkmcnt(0)
	v_mfma_f32_16x16x32_bf16 v[60:63], v[140:143], v[176:179], v[60:63]
	v_mfma_f32_16x16x32_bf16 v[60:63], v[144:147], v[180:183], v[60:63]
	v_mfma_f32_16x16x32_bf16 v[56:59], v[148:151], v[176:179], v[56:59]
	v_mfma_f32_16x16x32_bf16 v[56:59], v[152:155], v[180:183], v[56:59]
	v_mfma_f32_16x16x32_bf16 v[44:47], v[156:159], v[176:179], v[44:47]
	v_mfma_f32_16x16x32_bf16 v[44:47], v[164:167], v[180:183], v[44:47]
	v_mfma_f32_16x16x32_bf16 v[36:39], v[168:171], v[176:179], v[36:39]
	v_mfma_f32_16x16x32_bf16 v[36:39], v[172:175], v[180:183], v[36:39]
	v_mfma_f32_16x16x32_bf16 v[20:23], v[168:171], v[184:187], v[20:23]
	v_mfma_f32_16x16x32_bf16 v[20:23], v[172:175], v[188:191], v[20:23]
	v_mfma_f32_16x16x32_bf16 v[28:31], v[156:159], v[184:187], v[28:31]
	v_mfma_f32_16x16x32_bf16 v[28:31], v[164:167], v[188:191], v[28:31]
	v_mfma_f32_16x16x32_bf16 v[48:51], v[148:151], v[184:187], v[48:51]
	v_mfma_f32_16x16x32_bf16 v[48:51], v[152:155], v[188:191], v[48:51]
	v_mfma_f32_16x16x32_bf16 v[52:55], v[140:143], v[184:187], v[52:55]
	v_mfma_f32_16x16x32_bf16 v[52:55], v[144:147], v[188:191], v[52:55]
	v_mfma_f32_16x16x32_bf16 v[40:43], v[140:143], v[192:195], v[40:43]
	v_mfma_f32_16x16x32_bf16 v[40:43], v[144:147], v[196:199], v[40:43]
	v_mfma_f32_16x16x32_bf16 v[32:35], v[148:151], v[192:195], v[32:35]
	v_mfma_f32_16x16x32_bf16 v[32:35], v[152:155], v[196:199], v[32:35]
	v_mfma_f32_16x16x32_bf16 v[12:15], v[156:159], v[192:195], v[12:15]
	v_mfma_f32_16x16x32_bf16 v[12:15], v[164:167], v[196:199], v[12:15]
	v_mfma_f32_16x16x32_bf16 v[8:11], v[168:171], v[192:195], v[8:11]
	v_mfma_f32_16x16x32_bf16 v[8:11], v[172:175], v[196:199], v[8:11]
	v_mfma_f32_16x16x32_bf16 v[0:3], v[168:171], v[200:203], v[0:3]
	v_mfma_f32_16x16x32_bf16 v[0:3], v[172:175], v[204:207], v[0:3]
	v_mfma_f32_16x16x32_bf16 v[4:7], v[156:159], v[200:203], v[4:7]
	v_mfma_f32_16x16x32_bf16 v[4:7], v[164:167], v[204:207], v[4:7]
	v_mfma_f32_16x16x32_bf16 v[16:19], v[148:151], v[200:203], v[16:19]
	v_mfma_f32_16x16x32_bf16 v[16:19], v[152:155], v[204:207], v[16:19]
	v_mfma_f32_16x16x32_bf16 v[24:27], v[140:143], v[200:203], v[24:27]
	v_mfma_f32_16x16x32_bf16 v[24:27], v[144:147], v[204:207], v[24:27]
	s_setprio 0
	s_barrier
	s_add_u32 s24, s24, 0x10000
	s_addc_u32 s25, s25, 0
	s_add_u32 s60, s60, 0x10000
	s_addc_u32 s61, s61, 0
	s_cmp_ge_i32 s62, s43
	s_mov_b32 s26, s62
	s_cbranch_scc0 .LBB0_228
	v_pk_mul_f32 v[200:201], v[126:127], 0.5 op_sel_hi:[1,0]
	v_pk_mul_f32 v[202:203], v[124:125], 0.5 op_sel_hi:[1,0]
	v_pk_mul_f32 v[204:205], v[122:123], 0.5 op_sel_hi:[1,0]
	v_pk_mul_f32 v[206:207], v[120:121], 0.5 op_sel_hi:[1,0]
	v_pk_mul_f32 v[210:211], v[110:111], 0.5 op_sel_hi:[1,0]
	v_pk_mul_f32 v[208:209], v[108:109], 0.5 op_sel_hi:[1,0]
	v_pk_mul_f32 v[198:199], v[102:103], 0.5 op_sel_hi:[1,0]
	v_pk_mul_f32 v[196:197], v[100:101], 0.5 op_sel_hi:[1,0]
	v_pk_mul_f32 v[194:195], v[118:119], 0.5 op_sel_hi:[1,0]
	v_pk_mul_f32 v[192:193], v[116:117], 0.5 op_sel_hi:[1,0]
	v_pk_mul_f32 v[190:191], v[114:115], 0.5 op_sel_hi:[1,0]
	v_pk_mul_f32 v[188:189], v[112:113], 0.5 op_sel_hi:[1,0]
	v_pk_mul_f32 v[186:187], v[94:95], 0.5 op_sel_hi:[1,0]
	v_pk_mul_f32 v[184:185], v[92:93], 0.5 op_sel_hi:[1,0]
	v_pk_mul_f32 v[182:183], v[86:87], 0.5 op_sel_hi:[1,0]
	v_pk_mul_f32 v[180:181], v[84:85], 0.5 op_sel_hi:[1,0]
	v_pk_mul_f32 v[178:179], v[106:107], 0.5 op_sel_hi:[1,0]
	v_pk_mul_f32 v[176:177], v[104:105], 0.5 op_sel_hi:[1,0]
	v_pk_mul_f32 v[174:175], v[98:99], 0.5 op_sel_hi:[1,0]
	v_pk_mul_f32 v[172:173], v[96:97], 0.5 op_sel_hi:[1,0]
	v_pk_mul_f32 v[170:171], v[78:79], 0.5 op_sel_hi:[1,0]
	v_pk_mul_f32 v[168:169], v[76:77], 0.5 op_sel_hi:[1,0]
	v_pk_mul_f32 v[166:167], v[74:75], 0.5 op_sel_hi:[1,0]
	v_pk_mul_f32 v[164:165], v[72:73], 0.5 op_sel_hi:[1,0]
	v_pk_mul_f32 v[160:161], v[90:91], 0.5 op_sel_hi:[1,0]
	v_pk_mul_f32 v[158:159], v[88:89], 0.5 op_sel_hi:[1,0]
	v_pk_mul_f32 v[156:157], v[82:83], 0.5 op_sel_hi:[1,0]
	v_pk_mul_f32 v[154:155], v[80:81], 0.5 op_sel_hi:[1,0]
	v_pk_mul_f32 v[152:153], v[70:71], 0.5 op_sel_hi:[1,0]
	v_pk_mul_f32 v[150:151], v[68:69], 0.5 op_sel_hi:[1,0]
	v_pk_mul_f32 v[148:149], v[66:67], 0.5 op_sel_hi:[1,0]
	v_pk_mul_f32 v[146:147], v[64:65], 0.5 op_sel_hi:[1,0]
	v_pk_mul_f32 v[144:145], v[62:63], 0.5 op_sel_hi:[1,0]
	v_pk_mul_f32 v[142:143], v[60:61], 0.5 op_sel_hi:[1,0]
	v_pk_mul_f32 v[126:127], v[58:59], 0.5 op_sel_hi:[1,0]
	v_pk_mul_f32 v[124:125], v[56:57], 0.5 op_sel_hi:[1,0]
	v_pk_mul_f32 v[122:123], v[46:47], 0.5 op_sel_hi:[1,0]
	v_pk_mul_f32 v[120:121], v[44:45], 0.5 op_sel_hi:[1,0]
	v_pk_mul_f32 v[118:119], v[38:39], 0.5 op_sel_hi:[1,0]
	v_pk_mul_f32 v[116:117], v[36:37], 0.5 op_sel_hi:[1,0]
	v_pk_mul_f32 v[114:115], v[54:55], 0.5 op_sel_hi:[1,0]
	v_pk_mul_f32 v[112:113], v[52:53], 0.5 op_sel_hi:[1,0]
	v_pk_mul_f32 v[110:111], v[50:51], 0.5 op_sel_hi:[1,0]
	v_pk_mul_f32 v[108:109], v[48:49], 0.5 op_sel_hi:[1,0]
	v_pk_mul_f32 v[106:107], v[30:31], 0.5 op_sel_hi:[1,0]
	v_pk_mul_f32 v[104:105], v[28:29], 0.5 op_sel_hi:[1,0]
	v_pk_mul_f32 v[102:103], v[22:23], 0.5 op_sel_hi:[1,0]
	v_pk_mul_f32 v[100:101], v[20:21], 0.5 op_sel_hi:[1,0]
	v_pk_mul_f32 v[98:99], v[42:43], 0.5 op_sel_hi:[1,0]
	v_pk_mul_f32 v[96:97], v[40:41], 0.5 op_sel_hi:[1,0]
	v_pk_mul_f32 v[94:95], v[34:35], 0.5 op_sel_hi:[1,0]
	v_pk_mul_f32 v[92:93], v[32:33], 0.5 op_sel_hi:[1,0]
	v_pk_mul_f32 v[90:91], v[14:15], 0.5 op_sel_hi:[1,0]
	v_pk_mul_f32 v[88:89], v[12:13], 0.5 op_sel_hi:[1,0]
	v_pk_mul_f32 v[86:87], v[10:11], 0.5 op_sel_hi:[1,0]
	v_pk_mul_f32 v[84:85], v[8:9], 0.5 op_sel_hi:[1,0]
	v_pk_mul_f32 v[82:83], v[26:27], 0.5 op_sel_hi:[1,0]
	v_pk_mul_f32 v[80:81], v[24:25], 0.5 op_sel_hi:[1,0]
	v_pk_mul_f32 v[78:79], v[18:19], 0.5 op_sel_hi:[1,0]
	v_pk_mul_f32 v[76:77], v[16:17], 0.5 op_sel_hi:[1,0]
	v_pk_mul_f32 v[74:75], v[6:7], 0.5 op_sel_hi:[1,0]
	v_pk_mul_f32 v[72:73], v[4:5], 0.5 op_sel_hi:[1,0]
	v_pk_mul_f32 v[70:71], v[2:3], 0.5 op_sel_hi:[1,0]
	v_pk_mul_f32 v[68:69], v[0:1], 0.5 op_sel_hi:[1,0]

.LBB0_323:
	ds_read_b128 v[128:131], v222
	ds_read_b128 v[132:135], v222 offset:1024
	ds_read_b128 v[136:139], v222 offset:2048
	ds_read_b128 v[140:143], v222 offset:3072
	ds_read_b128 v[144:147], v223
	ds_read_b128 v[148:151], v223 offset:1024
	ds_read_b128 v[152:155], v223 offset:2048
	ds_read_b128 v[156:159], v223 offset:3072
	s_add_i32 s53, s50, 2
	s_add_u32 s54, s0, 0x80
	s_addc_u32 s51, s1, 0
	s_cmp_eq_u32 s78, s50
	s_cselect_b32 s50, s46, s54
	s_cselect_b32 s51, s47, s51
	s_cselect_b32 s55, s49, s52
	s_cselect_b32 s54, s48, s33
	v_lshl_add_u64 v[160:161], s[0:1], 0, v[176:177]
	s_add_i32 m0, s71, 0xc000
	ds_read_b128 v[184:187], v224
	ds_read_b128 v[188:191], v224 offset:1024
	ds_read_b128 v[192:195], v224 offset:2048
	ds_read_b128 v[196:199], v224 offset:3072
	ds_read_b128 v[200:203], v224 offset:4096
	ds_read_b128 v[204:207], v224 offset:5120
	ds_read_b128 v[208:211], v224 offset:6144
	ds_read_b128 v[212:215], v224 offset:7168
	global_load_lds_dwordx4 v[160:161], off
	v_lshl_add_u64 v[160:161], s[0:1], 0, v[178:179]
	s_add_i32 m0, s71, 0xe000
	s_nop 0
	global_load_lds_dwordx4 v[160:161], off
	s_waitcnt vmcnt(8)
	s_waitcnt lgkmcnt(0)
	s_barrier
	s_setprio 1
	s_waitcnt lgkmcnt(0)
	v_mfma_f32_16x16x32_bf16 v[124:127], v[128:131], v[184:187], v[124:127]
	v_mfma_f32_16x16x32_bf16 v[124:127], v[132:135], v[188:191], v[124:127]
	v_mfma_f32_16x16x32_bf16 v[120:123], v[136:139], v[184:187], v[120:123]
	v_mfma_f32_16x16x32_bf16 v[120:123], v[140:143], v[188:191], v[120:123]
	v_mfma_f32_16x16x32_bf16 v[116:119], v[144:147], v[184:187], v[116:119]
	v_mfma_f32_16x16x32_bf16 v[116:119], v[148:151], v[188:191], v[116:119]
	v_mfma_f32_16x16x32_bf16 v[112:115], v[152:155], v[184:187], v[112:115]
	v_mfma_f32_16x16x32_bf16 v[112:115], v[156:159], v[188:191], v[112:115]
	v_mfma_f32_16x16x32_bf16 v[96:99], v[152:155], v[192:195], v[96:99]
	v_mfma_f32_16x16x32_bf16 v[96:99], v[156:159], v[196:199], v[96:99]
	v_mfma_f32_16x16x32_bf16 v[100:103], v[144:147], v[192:195], v[100:103]
	v_mfma_f32_16x16x32_bf16 v[100:103], v[148:151], v[196:199], v[100:103]
	v_mfma_f32_16x16x32_bf16 v[104:107], v[136:139], v[192:195], v[104:107]
	v_mfma_f32_16x16x32_bf16 v[104:107], v[140:143], v[196:199], v[104:107]
	v_mfma_f32_16x16x32_bf16 v[108:111], v[128:131], v[192:195], v[108:111]
	v_mfma_f32_16x16x32_bf16 v[108:111], v[132:135], v[196:199], v[108:111]
	v_mfma_f32_16x16x32_bf16 v[92:95], v[128:131], v[200:203], v[92:95]
	v_mfma_f32_16x16x32_bf16 v[92:95], v[132:135], v[204:207], v[92:95]
	v_mfma_f32_16x16x32_bf16 v[88:91], v[136:139], v[200:203], v[88:91]
	v_mfma_f32_16x16x32_bf16 v[88:91], v[140:143], v[204:207], v[88:91]
	v_mfma_f32_16x16x32_bf16 v[84:87], v[144:147], v[200:203], v[84:87]
	v_mfma_f32_16x16x32_bf16 v[84:87], v[148:151], v[204:207], v[84:87]
	v_mfma_f32_16x16x32_bf16 v[80:83], v[152:155], v[200:203], v[80:83]
	v_mfma_f32_16x16x32_bf16 v[80:83], v[156:159], v[204:207], v[80:83]
	v_mfma_f32_16x16x32_bf16 v[64:67], v[152:155], v[208:211], v[64:67]
	v_mfma_f32_16x16x32_bf16 v[64:67], v[156:159], v[212:215], v[64:67]
	v_mfma_f32_16x16x32_bf16 v[68:71], v[144:147], v[208:211], v[68:71]
	v_mfma_f32_16x16x32_bf16 v[68:71], v[148:151], v[212:215], v[68:71]
	v_mfma_f32_16x16x32_bf16 v[72:75], v[136:139], v[208:211], v[72:75]
	v_mfma_f32_16x16x32_bf16 v[72:75], v[140:143], v[212:215], v[72:75]
	v_mfma_f32_16x16x32_bf16 v[76:79], v[128:131], v[208:211], v[76:79]
	v_mfma_f32_16x16x32_bf16 v[76:79], v[132:135], v[212:215], v[76:79]
	s_setprio 0
	s_barrier
	s_add_i32 s60, s82, s70
	v_lshl_add_u64 v[160:161], s[54:55], 0, v[166:167]
	s_mov_b32 m0, s60
	ds_read_b128 v[184:187], v224 offset:16384
	ds_read_b128 v[188:191], v224 offset:17408
	ds_read_b128 v[192:195], v224 offset:18432
	ds_read_b128 v[196:199], v224 offset:19456
	ds_read_b128 v[200:203], v224 offset:20480
	ds_read_b128 v[204:207], v224 offset:21504
	ds_read_b128 v[208:211], v224 offset:22528
	ds_read_b128 v[212:215], v224 offset:23552
	global_load_lds_dwordx4 v[160:161], off
	s_add_i32 m0, s60, 0x2000
	v_lshl_add_u64 v[216:217], s[54:55], 0, v[170:171]
	s_add_u32 s54, s54, s10
	s_addc_u32 s55, s55, s11
	s_add_i32 s60, s83, s70
	global_load_lds_dwordx4 v[216:217], off
	v_lshl_add_u64 v[218:219], s[54:55], 0, v[166:167]
	s_mov_b32 m0, s60
	v_lshl_add_u64 v[230:231], s[54:55], 0, v[170:171]
	global_load_lds_dwordx4 v[218:219], off
	s_add_i32 m0, s60, 0x2000
	v_lshl_add_u64 v[232:233], s[50:51], 0, v[164:165]
	global_load_lds_dwordx4 v[230:231], off
	s_mov_b32 m0, s71
	v_lshl_add_u64 v[234:235], s[50:51], 0, v[168:169]
	global_load_lds_dwordx4 v[232:233], off
	s_mov_b32 m0, s72
	s_nop 0
	global_load_lds_dwordx4 v[234:235], off
	s_waitcnt vmcnt(8)
	s_waitcnt lgkmcnt(0)
	s_barrier
	s_setprio 1
	s_waitcnt lgkmcnt(0)
	v_mfma_f32_16x16x32_bf16 v[60:63], v[128:131], v[184:187], v[60:63]
	v_mfma_f32_16x16x32_bf16 v[60:63], v[132:135], v[188:191], v[60:63]
	v_mfma_f32_16x16x32_bf16 v[56:59], v[136:139], v[184:187], v[56:59]
	v_mfma_f32_16x16x32_bf16 v[56:59], v[140:143], v[188:191], v[56:59]
	v_mfma_f32_16x16x32_bf16 v[52:55], v[144:147], v[184:187], v[52:55]
	v_mfma_f32_16x16x32_bf16 v[52:55], v[148:151], v[188:191], v[52:55]
	v_mfma_f32_16x16x32_bf16 v[48:51], v[152:155], v[184:187], v[48:51]
	v_mfma_f32_16x16x32_bf16 v[48:51], v[156:159], v[188:191], v[48:51]
	v_mfma_f32_16x16x32_bf16 v[32:35], v[152:155], v[192:195], v[32:35]
	v_mfma_f32_16x16x32_bf16 v[32:35], v[156:159], v[196:199], v[32:35]
	v_mfma_f32_16x16x32_bf16 v[36:39], v[144:147], v[192:195], v[36:39]
	v_mfma_f32_16x16x32_bf16 v[36:39], v[148:151], v[196:199], v[36:39]
	v_mfma_f32_16x16x32_bf16 v[40:43], v[136:139], v[192:195], v[40:43]
	v_mfma_f32_16x16x32_bf16 v[40:43], v[140:143], v[196:199], v[40:43]
	v_mfma_f32_16x16x32_bf16 v[44:47], v[128:131], v[192:195], v[44:47]
	v_mfma_f32_16x16x32_bf16 v[44:47], v[132:135], v[196:199], v[44:47]
	v_mfma_f32_16x16x32_bf16 v[28:31], v[128:131], v[200:203], v[28:31]
	v_mfma_f32_16x16x32_bf16 v[28:31], v[132:135], v[204:207], v[28:31]
	v_mfma_f32_16x16x32_bf16 v[24:27], v[136:139], v[200:203], v[24:27]
	v_mfma_f32_16x16x32_bf16 v[24:27], v[140:143], v[204:207], v[24:27]
	v_mfma_f32_16x16x32_bf16 v[20:23], v[144:147], v[200:203], v[20:23]
	v_mfma_f32_16x16x32_bf16 v[20:23], v[148:151], v[204:207], v[20:23]
	v_mfma_f32_16x16x32_bf16 v[16:19], v[152:155], v[200:203], v[16:19]
	v_mfma_f32_16x16x32_bf16 v[16:19], v[156:159], v[204:207], v[16:19]
	v_mfma_f32_16x16x32_bf16 v[0:3], v[152:155], v[208:211], v[0:3]
	v_mfma_f32_16x16x32_bf16 v[0:3], v[156:159], v[212:215], v[0:3]
	v_mfma_f32_16x16x32_bf16 v[4:7], v[144:147], v[208:211], v[4:7]
	v_mfma_f32_16x16x32_bf16 v[4:7], v[148:151], v[212:215], v[4:7]
	v_mfma_f32_16x16x32_bf16 v[8:11], v[136:139], v[208:211], v[8:11]
	v_mfma_f32_16x16x32_bf16 v[8:11], v[140:143], v[212:215], v[8:11]
	v_mfma_f32_16x16x32_bf16 v[12:15], v[128:131], v[208:211], v[12:15]
	v_mfma_f32_16x16x32_bf16 v[12:15], v[132:135], v[212:215], v[12:15]
	s_setprio 0
	s_barrier
	s_add_i32 s54, 0, 0x18000
	s_add_i32 s55, 0, 0x1c000
	v_add_u32_e32 v140, s54, v221
	v_add_u32_e32 v156, s55, v221
	ds_read_b128 v[128:131], v140
	ds_read_b128 v[132:135], v140 offset:1024
	ds_read_b128 v[136:139], v140 offset:2048
	ds_read_b128 v[140:143], v140 offset:3072
	ds_read_b128 v[144:147], v156
	ds_read_b128 v[148:151], v156 offset:1024
	ds_read_b128 v[152:155], v156 offset:2048
	ds_read_b128 v[156:159], v156 offset:3072
	s_add_u32 s50, s50, s10
	s_addc_u32 s51, s51, s11
	s_mov_b32 m0, s73
	v_lshl_add_u64 v[236:237], s[50:51], 0, v[164:165]
	ds_read_b128 v[184:187], v224 offset:32768
	ds_read_b128 v[188:191], v224 offset:33792
	ds_read_b128 v[192:195], v224 offset:34816
	ds_read_b128 v[196:199], v224 offset:35840
	ds_read_b128 v[200:203], v224 offset:36864
	ds_read_b128 v[204:207], v224 offset:37888
	ds_read_b128 v[208:211], v224 offset:38912
	ds_read_b128 v[212:215], v224 offset:39936
	global_load_lds_dwordx4 v[236:237], off
	v_lshl_add_u64 v[236:237], s[50:51], 0, v[168:169]
	s_mov_b32 m0, s74
	s_nop 0
	global_load_lds_dwordx4 v[236:237], off
	s_waitcnt vmcnt(8)
	s_waitcnt lgkmcnt(0)
	s_barrier
	s_setprio 1
	s_waitcnt lgkmcnt(0)
	v_mfma_f32_16x16x32_bf16 v[124:127], v[128:131], v[184:187], v[124:127]
	v_mfma_f32_16x16x32_bf16 v[124:127], v[132:135], v[188:191], v[124:127]
	v_mfma_f32_16x16x32_bf16 v[120:123], v[136:139], v[184:187], v[120:123]
	v_mfma_f32_16x16x32_bf16 v[120:123], v[140:143], v[188:191], v[120:123]
	v_mfma_f32_16x16x32_bf16 v[116:119], v[144:147], v[184:187], v[116:119]
	v_mfma_f32_16x16x32_bf16 v[116:119], v[148:151], v[188:191], v[116:119]
	v_mfma_f32_16x16x32_bf16 v[112:115], v[152:155], v[184:187], v[112:115]
	v_mfma_f32_16x16x32_bf16 v[112:115], v[156:159], v[188:191], v[112:115]
	v_mfma_f32_16x16x32_bf16 v[96:99], v[152:155], v[192:195], v[96:99]
	v_mfma_f32_16x16x32_bf16 v[96:99], v[156:159], v[196:199], v[96:99]
	v_mfma_f32_16x16x32_bf16 v[100:103], v[144:147], v[192:195], v[100:103]
	v_mfma_f32_16x16x32_bf16 v[100:103], v[148:151], v[196:199], v[100:103]
	v_mfma_f32_16x16x32_bf16 v[104:107], v[136:139], v[192:195], v[104:107]
	v_mfma_f32_16x16x32_bf16 v[104:107], v[140:143], v[196:199], v[104:107]
	v_mfma_f32_16x16x32_bf16 v[108:111], v[128:131], v[192:195], v[108:111]
	v_mfma_f32_16x16x32_bf16 v[108:111], v[132:135], v[196:199], v[108:111]
	v_mfma_f32_16x16x32_bf16 v[92:95], v[128:131], v[200:203], v[92:95]
	v_mfma_f32_16x16x32_bf16 v[92:95], v[132:135], v[204:207], v[92:95]
	v_mfma_f32_16x16x32_bf16 v[88:91], v[136:139], v[200:203], v[88:91]
	v_mfma_f32_16x16x32_bf16 v[88:91], v[140:143], v[204:207], v[88:91]
	v_mfma_f32_16x16x32_bf16 v[84:87], v[144:147], v[200:203], v[84:87]
	v_mfma_f32_16x16x32_bf16 v[84:87], v[148:151], v[204:207], v[84:87]
	v_mfma_f32_16x16x32_bf16 v[80:83], v[152:155], v[200:203], v[80:83]
	v_mfma_f32_16x16x32_bf16 v[80:83], v[156:159], v[204:207], v[80:83]
	v_mfma_f32_16x16x32_bf16 v[64:67], v[152:155], v[208:211], v[64:67]
	v_mfma_f32_16x16x32_bf16 v[64:67], v[156:159], v[212:215], v[64:67]
	v_mfma_f32_16x16x32_bf16 v[68:71], v[144:147], v[208:211], v[68:71]
	v_mfma_f32_16x16x32_bf16 v[68:71], v[148:151], v[212:215], v[68:71]
	v_mfma_f32_16x16x32_bf16 v[72:75], v[136:139], v[208:211], v[72:75]
	v_mfma_f32_16x16x32_bf16 v[72:75], v[140:143], v[212:215], v[72:75]
	v_mfma_f32_16x16x32_bf16 v[76:79], v[128:131], v[208:211], v[76:79]
	v_mfma_f32_16x16x32_bf16 v[76:79], v[132:135], v[212:215], v[76:79]
	s_setprio 0
	s_barrier
	s_add_i32 s50, s54, s70
	v_lshl_add_u64 v[160:161], v[160:161], 0, s[36:37]
	s_mov_b32 m0, s50
	ds_read_b128 v[184:187], v224 offset:49152
	ds_read_b128 v[188:191], v224 offset:50176
	ds_read_b128 v[192:195], v224 offset:51200
	ds_read_b128 v[196:199], v224 offset:52224
	ds_read_b128 v[200:203], v224 offset:53248
	ds_read_b128 v[204:207], v224 offset:54272
	ds_read_b128 v[208:211], v224 offset:55296
	ds_read_b128 v[212:215], v224 offset:56320
	global_load_lds_dwordx4 v[160:161], off
	v_lshl_add_u64 v[160:161], v[216:217], 0, s[36:37]
	s_add_i32 m0, s50, 0x2000
	s_add_i32 s50, s55, s70
	global_load_lds_dwordx4 v[160:161], off
	v_lshl_add_u64 v[160:161], v[218:219], 0, s[36:37]
	s_mov_b32 m0, s50
	s_nop 0
	global_load_lds_dwordx4 v[160:161], off
	v_lshl_add_u64 v[160:161], v[230:231], 0, s[36:37]
	s_add_i32 m0, s50, 0x2000
	s_nop 0
	global_load_lds_dwordx4 v[160:161], off
	v_lshl_add_u64 v[160:161], v[232:233], 0, s[36:37]
	s_mov_b32 m0, s76
	s_nop 0
	global_load_lds_dwordx4 v[160:161], off
	v_lshl_add_u64 v[160:161], v[234:235], 0, s[36:37]
	s_mov_b32 m0, s77
	s_nop 0
	global_load_lds_dwordx4 v[160:161], off
	s_waitcnt vmcnt(8)
	s_waitcnt lgkmcnt(0)
	s_barrier
	s_setprio 1
	s_waitcnt lgkmcnt(0)
	v_mfma_f32_16x16x32_bf16 v[60:63], v[128:131], v[184:187], v[60:63]
	v_mfma_f32_16x16x32_bf16 v[60:63], v[132:135], v[188:191], v[60:63]
	v_mfma_f32_16x16x32_bf16 v[56:59], v[136:139], v[184:187], v[56:59]
	v_mfma_f32_16x16x32_bf16 v[56:59], v[140:143], v[188:191], v[56:59]
	v_mfma_f32_16x16x32_bf16 v[52:55], v[144:147], v[184:187], v[52:55]
	v_mfma_f32_16x16x32_bf16 v[52:55], v[148:151], v[188:191], v[52:55]
	v_mfma_f32_16x16x32_bf16 v[48:51], v[152:155], v[184:187], v[48:51]
	v_mfma_f32_16x16x32_bf16 v[48:51], v[156:159], v[188:191], v[48:51]
	v_mfma_f32_16x16x32_bf16 v[32:35], v[152:155], v[192:195], v[32:35]
	v_mfma_f32_16x16x32_bf16 v[32:35], v[156:159], v[196:199], v[32:35]
	v_mfma_f32_16x16x32_bf16 v[36:39], v[144:147], v[192:195], v[36:39]
	v_mfma_f32_16x16x32_bf16 v[36:39], v[148:151], v[196:199], v[36:39]
	v_mfma_f32_16x16x32_bf16 v[40:43], v[136:139], v[192:195], v[40:43]
	v_mfma_f32_16x16x32_bf16 v[40:43], v[140:143], v[196:199], v[40:43]
	v_mfma_f32_16x16x32_bf16 v[44:47], v[128:131], v[192:195], v[44:47]
	v_mfma_f32_16x16x32_bf16 v[44:47], v[132:135], v[196:199], v[44:47]
	v_mfma_f32_16x16x32_bf16 v[28:31], v[128:131], v[200:203], v[28:31]
	v_mfma_f32_16x16x32_bf16 v[28:31], v[132:135], v[204:207], v[28:31]
	v_mfma_f32_16x16x32_bf16 v[24:27], v[136:139], v[200:203], v[24:27]
	v_mfma_f32_16x16x32_bf16 v[24:27], v[140:143], v[204:207], v[24:27]
	v_mfma_f32_16x16x32_bf16 v[20:23], v[144:147], v[200:203], v[20:23]
	v_mfma_f32_16x16x32_bf16 v[20:23], v[148:151], v[204:207], v[20:23]
	v_mfma_f32_16x16x32_bf16 v[16:19], v[152:155], v[200:203], v[16:19]
	v_mfma_f32_16x16x32_bf16 v[16:19], v[156:159], v[204:207], v[16:19]
	v_mfma_f32_16x16x32_bf16 v[0:3], v[152:155], v[208:211], v[0:3]
	v_mfma_f32_16x16x32_bf16 v[0:3], v[156:159], v[212:215], v[0:3]
	v_mfma_f32_16x16x32_bf16 v[4:7], v[144:147], v[208:211], v[4:7]
	v_mfma_f32_16x16x32_bf16 v[4:7], v[148:151], v[212:215], v[4:7]
	v_mfma_f32_16x16x32_bf16 v[8:11], v[136:139], v[208:211], v[8:11]
	v_mfma_f32_16x16x32_bf16 v[8:11], v[140:143], v[212:215], v[8:11]
	v_mfma_f32_16x16x32_bf16 v[12:15], v[128:131], v[208:211], v[12:15]
	v_mfma_f32_16x16x32_bf16 v[12:15], v[132:135], v[212:215], v[12:15]
	s_setprio 0
	s_barrier
	s_add_u32 s0, s0, 0x100
	s_addc_u32 s1, s1, 0
	s_add_u32 s33, s33, 0x100
	s_addc_u32 s52, s52, 0
	s_cmp_ge_i32 s53, s75
	s_mov_b32 s50, s53
	s_cbranch_scc0 .LBB0_323

.LBB0_592:
	ds_read_b128 v[144:147], v157
	ds_read_b128 v[148:151], v157 offset:1024
	ds_read_b128 v[164:167], v157 offset:2048
	ds_read_b128 v[168:171], v157 offset:3072
	ds_read_b128 v[172:175], v158
	ds_read_b128 v[176:179], v158 offset:1024
	ds_read_b128 v[180:183], v158 offset:2048
	ds_read_b128 v[184:187], v158 offset:3072
	s_add_i32 s64, s34, 2
	s_add_u32 s65, s30, 0x80
	s_addc_u32 s35, s31, 0
	s_cmp_eq_u32 s49, s34
	s_cselect_b32 s34, s2, s65
	s_cselect_b32 s35, s3, s35
	s_cselect_b32 s67, s29, s63
	s_cselect_b32 s66, s28, s62
	v_lshl_add_u64 v[152:153], s[30:31], 0, v[136:137]
	s_add_i32 m0, s41, 0xc000
	ds_read_b128 v[188:191], v159
	ds_read_b128 v[192:195], v159 offset:1024
	ds_read_b128 v[196:199], v159 offset:2048
	ds_read_b128 v[200:203], v159 offset:3072
	ds_read_b128 v[204:207], v159 offset:4096
	ds_read_b128 v[208:211], v159 offset:5120
	ds_read_b128 v[212:215], v159 offset:6144
	ds_read_b128 v[216:219], v159 offset:7168
	global_load_lds_dwordx4 v[152:153], off
	v_lshl_add_u64 v[152:153], s[30:31], 0, v[138:139]
	s_add_i32 m0, s41, 0xe000
	s_nop 0
	global_load_lds_dwordx4 v[152:153], off
	s_waitcnt vmcnt(8)
	s_waitcnt lgkmcnt(0)
	s_barrier
	s_setprio 1
	s_waitcnt lgkmcnt(0)
	v_mfma_f32_16x16x32_bf16 v[120:123], v[144:147], v[188:191], v[120:123]
	v_mfma_f32_16x16x32_bf16 v[120:123], v[148:151], v[192:195], v[120:123]
	v_mfma_f32_16x16x32_bf16 v[124:127], v[164:167], v[188:191], v[124:127]
	v_mfma_f32_16x16x32_bf16 v[124:127], v[168:171], v[192:195], v[124:127]
	v_mfma_f32_16x16x32_bf16 v[116:119], v[172:175], v[188:191], v[116:119]
	v_mfma_f32_16x16x32_bf16 v[116:119], v[176:179], v[192:195], v[116:119]
	v_mfma_f32_16x16x32_bf16 v[112:115], v[180:183], v[188:191], v[112:115]
	v_mfma_f32_16x16x32_bf16 v[112:115], v[184:187], v[192:195], v[112:115]
	v_mfma_f32_16x16x32_bf16 v[96:99], v[180:183], v[196:199], v[96:99]
	v_mfma_f32_16x16x32_bf16 v[96:99], v[184:187], v[200:203], v[96:99]
	v_mfma_f32_16x16x32_bf16 v[100:103], v[172:175], v[196:199], v[100:103]
	v_mfma_f32_16x16x32_bf16 v[100:103], v[176:179], v[200:203], v[100:103]
	v_mfma_f32_16x16x32_bf16 v[104:107], v[164:167], v[196:199], v[104:107]
	v_mfma_f32_16x16x32_bf16 v[104:107], v[168:171], v[200:203], v[104:107]
	v_mfma_f32_16x16x32_bf16 v[108:111], v[144:147], v[196:199], v[108:111]
	v_mfma_f32_16x16x32_bf16 v[108:111], v[148:151], v[200:203], v[108:111]
	v_mfma_f32_16x16x32_bf16 v[92:95], v[144:147], v[204:207], v[92:95]
	v_mfma_f32_16x16x32_bf16 v[92:95], v[148:151], v[208:211], v[92:95]
	v_mfma_f32_16x16x32_bf16 v[88:91], v[164:167], v[204:207], v[88:91]
	v_mfma_f32_16x16x32_bf16 v[88:91], v[168:171], v[208:211], v[88:91]
	v_mfma_f32_16x16x32_bf16 v[84:87], v[172:175], v[204:207], v[84:87]
	v_mfma_f32_16x16x32_bf16 v[84:87], v[176:179], v[208:211], v[84:87]
	v_mfma_f32_16x16x32_bf16 v[80:83], v[180:183], v[204:207], v[80:83]
	v_mfma_f32_16x16x32_bf16 v[80:83], v[184:187], v[208:211], v[80:83]
	v_mfma_f32_16x16x32_bf16 v[64:67], v[180:183], v[212:215], v[64:67]
	v_mfma_f32_16x16x32_bf16 v[64:67], v[184:187], v[216:219], v[64:67]
	v_mfma_f32_16x16x32_bf16 v[68:71], v[172:175], v[212:215], v[68:71]
	v_mfma_f32_16x16x32_bf16 v[68:71], v[176:179], v[216:219], v[68:71]
	v_mfma_f32_16x16x32_bf16 v[72:75], v[164:167], v[212:215], v[72:75]
	v_mfma_f32_16x16x32_bf16 v[72:75], v[168:171], v[216:219], v[72:75]
	v_mfma_f32_16x16x32_bf16 v[76:79], v[144:147], v[212:215], v[76:79]
	v_mfma_f32_16x16x32_bf16 v[76:79], v[148:151], v[216:219], v[76:79]
	s_setprio 0
	s_barrier
	s_add_i32 s65, s52, s40
	v_lshl_add_u64 v[152:153], s[66:67], 0, v[130:131]
	s_mov_b32 m0, s65
	ds_read_b128 v[188:191], v159 offset:16384
	ds_read_b128 v[192:195], v159 offset:17408
	ds_read_b128 v[196:199], v159 offset:18432
	ds_read_b128 v[200:203], v159 offset:19456
	ds_read_b128 v[204:207], v159 offset:20480
	ds_read_b128 v[208:211], v159 offset:21504
	ds_read_b128 v[212:215], v159 offset:22528
	ds_read_b128 v[216:219], v159 offset:23552
	global_load_lds_dwordx4 v[152:153], off
	s_add_i32 m0, s65, 0x2000
	v_lshl_add_u64 v[160:161], s[66:67], 0, v[134:135]
	s_add_u32 s66, s66, s8
	s_addc_u32 s67, s67, s9
	s_add_i32 s65, s53, s40
	global_load_lds_dwordx4 v[160:161], off
	v_lshl_add_u64 v[222:223], s[66:67], 0, v[130:131]
	s_mov_b32 m0, s65
	v_lshl_add_u64 v[224:225], s[66:67], 0, v[134:135]
	global_load_lds_dwordx4 v[222:223], off
	s_add_i32 m0, s65, 0x2000
	v_lshl_add_u64 v[226:227], s[34:35], 0, v[128:129]
	global_load_lds_dwordx4 v[224:225], off
	s_mov_b32 m0, s41
	v_lshl_add_u64 v[228:229], s[34:35], 0, v[132:133]
	global_load_lds_dwordx4 v[226:227], off
	s_mov_b32 m0, s42
	s_nop 0
	global_load_lds_dwordx4 v[228:229], off
	s_waitcnt vmcnt(8)
	s_waitcnt lgkmcnt(0)
	s_barrier
	s_setprio 1
	s_waitcnt lgkmcnt(0)
	v_mfma_f32_16x16x32_bf16 v[60:63], v[144:147], v[188:191], v[60:63]
	v_mfma_f32_16x16x32_bf16 v[60:63], v[148:151], v[192:195], v[60:63]
	v_mfma_f32_16x16x32_bf16 v[56:59], v[164:167], v[188:191], v[56:59]
	v_mfma_f32_16x16x32_bf16 v[56:59], v[168:171], v[192:195], v[56:59]
	v_mfma_f32_16x16x32_bf16 v[52:55], v[172:175], v[188:191], v[52:55]
	v_mfma_f32_16x16x32_bf16 v[52:55], v[176:179], v[192:195], v[52:55]
	v_mfma_f32_16x16x32_bf16 v[48:51], v[180:183], v[188:191], v[48:51]
	v_mfma_f32_16x16x32_bf16 v[48:51], v[184:187], v[192:195], v[48:51]
	v_mfma_f32_16x16x32_bf16 v[32:35], v[180:183], v[196:199], v[32:35]
	v_mfma_f32_16x16x32_bf16 v[32:35], v[184:187], v[200:203], v[32:35]
	v_mfma_f32_16x16x32_bf16 v[36:39], v[172:175], v[196:199], v[36:39]
	v_mfma_f32_16x16x32_bf16 v[36:39], v[176:179], v[200:203], v[36:39]
	v_mfma_f32_16x16x32_bf16 v[40:43], v[164:167], v[196:199], v[40:43]
	v_mfma_f32_16x16x32_bf16 v[40:43], v[168:171], v[200:203], v[40:43]
	v_mfma_f32_16x16x32_bf16 v[44:47], v[144:147], v[196:199], v[44:47]
	v_mfma_f32_16x16x32_bf16 v[44:47], v[148:151], v[200:203], v[44:47]
	v_mfma_f32_16x16x32_bf16 v[28:31], v[144:147], v[204:207], v[28:31]
	v_mfma_f32_16x16x32_bf16 v[28:31], v[148:151], v[208:211], v[28:31]
	v_mfma_f32_16x16x32_bf16 v[24:27], v[164:167], v[204:207], v[24:27]
	v_mfma_f32_16x16x32_bf16 v[24:27], v[168:171], v[208:211], v[24:27]
	v_mfma_f32_16x16x32_bf16 v[20:23], v[172:175], v[204:207], v[20:23]
	v_mfma_f32_16x16x32_bf16 v[20:23], v[176:179], v[208:211], v[20:23]
	v_mfma_f32_16x16x32_bf16 v[16:19], v[180:183], v[204:207], v[16:19]
	v_mfma_f32_16x16x32_bf16 v[16:19], v[184:187], v[208:211], v[16:19]
	v_mfma_f32_16x16x32_bf16 v[0:3], v[180:183], v[212:215], v[0:3]
	v_mfma_f32_16x16x32_bf16 v[0:3], v[184:187], v[216:219], v[0:3]
	v_mfma_f32_16x16x32_bf16 v[4:7], v[172:175], v[212:215], v[4:7]
	v_mfma_f32_16x16x32_bf16 v[4:7], v[176:179], v[216:219], v[4:7]
	v_mfma_f32_16x16x32_bf16 v[8:11], v[164:167], v[212:215], v[8:11]
	v_mfma_f32_16x16x32_bf16 v[8:11], v[168:171], v[216:219], v[8:11]
	v_mfma_f32_16x16x32_bf16 v[12:15], v[144:147], v[212:215], v[12:15]
	v_mfma_f32_16x16x32_bf16 v[12:15], v[148:151], v[216:219], v[12:15]
	s_setprio 0
	s_barrier
	s_add_i32 s65, 0, 0x18000
	s_add_i32 s66, 0, 0x1c000
	v_add_u32_e32 v168, s65, v155
	v_add_u32_e32 v184, s66, v155
	ds_read_b128 v[144:147], v168
	ds_read_b128 v[148:151], v168 offset:1024
	ds_read_b128 v[164:167], v168 offset:2048
	ds_read_b128 v[168:171], v168 offset:3072
	ds_read_b128 v[172:175], v184
	ds_read_b128 v[176:179], v184 offset:1024
	ds_read_b128 v[180:183], v184 offset:2048
	ds_read_b128 v[184:187], v184 offset:3072
	s_add_u32 s34, s34, s8
	s_addc_u32 s35, s35, s9
	s_mov_b32 m0, s43
	v_lshl_add_u64 v[230:231], s[34:35], 0, v[128:129]
	ds_read_b128 v[188:191], v159 offset:32768
	ds_read_b128 v[192:195], v159 offset:33792
	ds_read_b128 v[196:199], v159 offset:34816
	ds_read_b128 v[200:203], v159 offset:35840
	ds_read_b128 v[204:207], v159 offset:36864
	ds_read_b128 v[208:211], v159 offset:37888
	ds_read_b128 v[212:215], v159 offset:38912
	ds_read_b128 v[216:219], v159 offset:39936
	global_load_lds_dwordx4 v[230:231], off
	v_lshl_add_u64 v[230:231], s[34:35], 0, v[132:133]
	s_mov_b32 m0, s44
	s_nop 0
	global_load_lds_dwordx4 v[230:231], off
	s_waitcnt vmcnt(8)
	s_waitcnt lgkmcnt(0)
	s_barrier
	s_setprio 1
	s_waitcnt lgkmcnt(0)
	v_mfma_f32_16x16x32_bf16 v[120:123], v[144:147], v[188:191], v[120:123]
	v_mfma_f32_16x16x32_bf16 v[120:123], v[148:151], v[192:195], v[120:123]
	v_mfma_f32_16x16x32_bf16 v[124:127], v[164:167], v[188:191], v[124:127]
	v_mfma_f32_16x16x32_bf16 v[124:127], v[168:171], v[192:195], v[124:127]
	v_mfma_f32_16x16x32_bf16 v[116:119], v[172:175], v[188:191], v[116:119]
	v_mfma_f32_16x16x32_bf16 v[116:119], v[176:179], v[192:195], v[116:119]
	v_mfma_f32_16x16x32_bf16 v[112:115], v[180:183], v[188:191], v[112:115]
	v_mfma_f32_16x16x32_bf16 v[112:115], v[184:187], v[192:195], v[112:115]
	v_mfma_f32_16x16x32_bf16 v[96:99], v[180:183], v[196:199], v[96:99]
	v_mfma_f32_16x16x32_bf16 v[96:99], v[184:187], v[200:203], v[96:99]
	v_mfma_f32_16x16x32_bf16 v[100:103], v[172:175], v[196:199], v[100:103]
	v_mfma_f32_16x16x32_bf16 v[100:103], v[176:179], v[200:203], v[100:103]
	v_mfma_f32_16x16x32_bf16 v[104:107], v[164:167], v[196:199], v[104:107]
	v_mfma_f32_16x16x32_bf16 v[104:107], v[168:171], v[200:203], v[104:107]
	v_mfma_f32_16x16x32_bf16 v[108:111], v[144:147], v[196:199], v[108:111]
	v_mfma_f32_16x16x32_bf16 v[108:111], v[148:151], v[200:203], v[108:111]
	v_mfma_f32_16x16x32_bf16 v[92:95], v[144:147], v[204:207], v[92:95]
	v_mfma_f32_16x16x32_bf16 v[92:95], v[148:151], v[208:211], v[92:95]
	v_mfma_f32_16x16x32_bf16 v[88:91], v[164:167], v[204:207], v[88:91]
	v_mfma_f32_16x16x32_bf16 v[88:91], v[168:171], v[208:211], v[88:91]
	v_mfma_f32_16x16x32_bf16 v[84:87], v[172:175], v[204:207], v[84:87]
	v_mfma_f32_16x16x32_bf16 v[84:87], v[176:179], v[208:211], v[84:87]
	v_mfma_f32_16x16x32_bf16 v[80:83], v[180:183], v[204:207], v[80:83]
	v_mfma_f32_16x16x32_bf16 v[80:83], v[184:187], v[208:211], v[80:83]
	v_mfma_f32_16x16x32_bf16 v[64:67], v[180:183], v[212:215], v[64:67]
	v_mfma_f32_16x16x32_bf16 v[64:67], v[184:187], v[216:219], v[64:67]
	v_mfma_f32_16x16x32_bf16 v[68:71], v[172:175], v[212:215], v[68:71]
	v_mfma_f32_16x16x32_bf16 v[68:71], v[176:179], v[216:219], v[68:71]
	v_mfma_f32_16x16x32_bf16 v[72:75], v[164:167], v[212:215], v[72:75]
	v_mfma_f32_16x16x32_bf16 v[72:75], v[168:171], v[216:219], v[72:75]
	v_mfma_f32_16x16x32_bf16 v[76:79], v[144:147], v[212:215], v[76:79]
	v_mfma_f32_16x16x32_bf16 v[76:79], v[148:151], v[216:219], v[76:79]
	s_setprio 0
	s_barrier
	s_add_i32 s34, s65, s40
	v_lshl_add_u64 v[152:153], v[152:153], 0, s[14:15]
	s_mov_b32 m0, s34
	ds_read_b128 v[188:191], v159 offset:49152
	ds_read_b128 v[192:195], v159 offset:50176
	ds_read_b128 v[196:199], v159 offset:51200
	ds_read_b128 v[200:203], v159 offset:52224
	ds_read_b128 v[204:207], v159 offset:53248
	ds_read_b128 v[208:211], v159 offset:54272
	ds_read_b128 v[212:215], v159 offset:55296
	ds_read_b128 v[216:219], v159 offset:56320
	global_load_lds_dwordx4 v[152:153], off
	v_lshl_add_u64 v[152:153], v[160:161], 0, s[14:15]
	s_add_i32 m0, s34, 0x2000
	s_add_i32 s34, s66, s40
	global_load_lds_dwordx4 v[152:153], off
	v_lshl_add_u64 v[152:153], v[222:223], 0, s[14:15]
	s_mov_b32 m0, s34
	s_nop 0
	global_load_lds_dwordx4 v[152:153], off
	v_lshl_add_u64 v[152:153], v[224:225], 0, s[14:15]
	s_add_i32 m0, s34, 0x2000
	s_nop 0
	global_load_lds_dwordx4 v[152:153], off
	v_lshl_add_u64 v[152:153], v[226:227], 0, s[14:15]
	s_mov_b32 m0, s46
	s_nop 0
	global_load_lds_dwordx4 v[152:153], off
	v_lshl_add_u64 v[152:153], v[228:229], 0, s[14:15]
	s_mov_b32 m0, s47
	s_nop 0
	global_load_lds_dwordx4 v[152:153], off
	s_waitcnt vmcnt(8)
	s_waitcnt lgkmcnt(0)
	s_barrier
	s_setprio 1
	s_waitcnt lgkmcnt(0)
	v_mfma_f32_16x16x32_bf16 v[60:63], v[144:147], v[188:191], v[60:63]
	v_mfma_f32_16x16x32_bf16 v[60:63], v[148:151], v[192:195], v[60:63]
	v_mfma_f32_16x16x32_bf16 v[56:59], v[164:167], v[188:191], v[56:59]
	v_mfma_f32_16x16x32_bf16 v[56:59], v[168:171], v[192:195], v[56:59]
	v_mfma_f32_16x16x32_bf16 v[52:55], v[172:175], v[188:191], v[52:55]
	v_mfma_f32_16x16x32_bf16 v[52:55], v[176:179], v[192:195], v[52:55]
	v_mfma_f32_16x16x32_bf16 v[48:51], v[180:183], v[188:191], v[48:51]
	v_mfma_f32_16x16x32_bf16 v[48:51], v[184:187], v[192:195], v[48:51]
	v_mfma_f32_16x16x32_bf16 v[32:35], v[180:183], v[196:199], v[32:35]
	v_mfma_f32_16x16x32_bf16 v[32:35], v[184:187], v[200:203], v[32:35]
	v_mfma_f32_16x16x32_bf16 v[36:39], v[172:175], v[196:199], v[36:39]
	v_mfma_f32_16x16x32_bf16 v[36:39], v[176:179], v[200:203], v[36:39]
	v_mfma_f32_16x16x32_bf16 v[40:43], v[164:167], v[196:199], v[40:43]
	v_mfma_f32_16x16x32_bf16 v[40:43], v[168:171], v[200:203], v[40:43]
	v_mfma_f32_16x16x32_bf16 v[44:47], v[144:147], v[196:199], v[44:47]
	v_mfma_f32_16x16x32_bf16 v[44:47], v[148:151], v[200:203], v[44:47]
	v_mfma_f32_16x16x32_bf16 v[28:31], v[144:147], v[204:207], v[28:31]
	v_mfma_f32_16x16x32_bf16 v[28:31], v[148:151], v[208:211], v[28:31]
	v_mfma_f32_16x16x32_bf16 v[24:27], v[164:167], v[204:207], v[24:27]
	v_mfma_f32_16x16x32_bf16 v[24:27], v[168:171], v[208:211], v[24:27]
	v_mfma_f32_16x16x32_bf16 v[20:23], v[172:175], v[204:207], v[20:23]
	v_mfma_f32_16x16x32_bf16 v[20:23], v[176:179], v[208:211], v[20:23]
	v_mfma_f32_16x16x32_bf16 v[16:19], v[180:183], v[204:207], v[16:19]
	v_mfma_f32_16x16x32_bf16 v[16:19], v[184:187], v[208:211], v[16:19]
	v_mfma_f32_16x16x32_bf16 v[0:3], v[180:183], v[212:215], v[0:3]
	v_mfma_f32_16x16x32_bf16 v[0:3], v[184:187], v[216:219], v[0:3]
	v_mfma_f32_16x16x32_bf16 v[4:7], v[172:175], v[212:215], v[4:7]
	v_mfma_f32_16x16x32_bf16 v[4:7], v[176:179], v[216:219], v[4:7]
	v_mfma_f32_16x16x32_bf16 v[8:11], v[164:167], v[212:215], v[8:11]
	v_mfma_f32_16x16x32_bf16 v[8:11], v[168:171], v[216:219], v[8:11]
	v_mfma_f32_16x16x32_bf16 v[12:15], v[144:147], v[212:215], v[12:15]
	v_mfma_f32_16x16x32_bf16 v[12:15], v[148:151], v[216:219], v[12:15]
	s_setprio 0
	s_barrier
	s_add_u32 s30, s30, 0x100
	s_addc_u32 s31, s31, 0
	s_add_u32 s62, s62, 0x100
	s_addc_u32 s63, s63, 0
	s_cmp_ge_i32 s64, s48
	s_mov_b32 s34, s64
	s_cbranch_scc0 .LBB0_592

.LBB0_763:
	ds_read_b128 v[128:131], v181
	ds_read_b128 v[132:135], v181 offset:1024
	ds_read_b128 v[136:139], v181 offset:2048
	ds_read_b128 v[140:143], v181 offset:3072
	ds_read_b128 v[144:147], v182
	ds_read_b128 v[148:151], v182 offset:1024
	ds_read_b128 v[168:171], v182 offset:2048
	ds_read_b128 v[172:175], v182 offset:3072
	s_add_i32 s54, s26, 2
	s_add_u32 s55, s24, 0x80
	s_addc_u32 s27, s25, 0
	s_cmp_eq_u32 s43, s26
	s_cselect_b32 s26, s2, s55
	s_cselect_b32 s27, s3, s27
	s_cselect_b32 s61, s23, s53
	s_cselect_b32 s60, s22, s52
	v_lshl_add_u64 v[176:177], s[24:25], 0, v[160:161]
	s_add_i32 m0, s35, 0xc000
	ds_read_b128 v[184:187], v183
	ds_read_b128 v[188:191], v183 offset:1024
	ds_read_b128 v[192:195], v183 offset:2048
	ds_read_b128 v[196:199], v183 offset:3072
	ds_read_b128 v[200:203], v183 offset:4096
	ds_read_b128 v[204:207], v183 offset:5120
	ds_read_b128 v[208:211], v183 offset:6144
	ds_read_b128 v[212:215], v183 offset:7168
	global_load_lds_dwordx4 v[176:177], off
	v_lshl_add_u64 v[176:177], s[24:25], 0, v[162:163]
	s_add_i32 m0, s35, 0xe000
	s_nop 0
	global_load_lds_dwordx4 v[176:177], off
	s_waitcnt vmcnt(8)
	s_waitcnt lgkmcnt(0)
	s_barrier
	s_setprio 1
	s_waitcnt lgkmcnt(0)
	v_mfma_f32_16x16x32_bf16 v[120:123], v[128:131], v[184:187], v[120:123]
	v_mfma_f32_16x16x32_bf16 v[120:123], v[132:135], v[188:191], v[120:123]
	v_mfma_f32_16x16x32_bf16 v[124:127], v[136:139], v[184:187], v[124:127]
	v_mfma_f32_16x16x32_bf16 v[124:127], v[140:143], v[188:191], v[124:127]
	v_mfma_f32_16x16x32_bf16 v[116:119], v[144:147], v[184:187], v[116:119]
	v_mfma_f32_16x16x32_bf16 v[116:119], v[148:151], v[188:191], v[116:119]
	v_mfma_f32_16x16x32_bf16 v[112:115], v[168:171], v[184:187], v[112:115]
	v_mfma_f32_16x16x32_bf16 v[112:115], v[172:175], v[188:191], v[112:115]
	v_mfma_f32_16x16x32_bf16 v[96:99], v[168:171], v[192:195], v[96:99]
	v_mfma_f32_16x16x32_bf16 v[96:99], v[172:175], v[196:199], v[96:99]
	v_mfma_f32_16x16x32_bf16 v[100:103], v[144:147], v[192:195], v[100:103]
	v_mfma_f32_16x16x32_bf16 v[100:103], v[148:151], v[196:199], v[100:103]
	v_mfma_f32_16x16x32_bf16 v[104:107], v[136:139], v[192:195], v[104:107]
	v_mfma_f32_16x16x32_bf16 v[104:107], v[140:143], v[196:199], v[104:107]
	v_mfma_f32_16x16x32_bf16 v[108:111], v[128:131], v[192:195], v[108:111]
	v_mfma_f32_16x16x32_bf16 v[108:111], v[132:135], v[196:199], v[108:111]
	v_mfma_f32_16x16x32_bf16 v[92:95], v[128:131], v[200:203], v[92:95]
	v_mfma_f32_16x16x32_bf16 v[92:95], v[132:135], v[204:207], v[92:95]
	v_mfma_f32_16x16x32_bf16 v[88:91], v[136:139], v[200:203], v[88:91]
	v_mfma_f32_16x16x32_bf16 v[88:91], v[140:143], v[204:207], v[88:91]
	v_mfma_f32_16x16x32_bf16 v[84:87], v[144:147], v[200:203], v[84:87]
	v_mfma_f32_16x16x32_bf16 v[84:87], v[148:151], v[204:207], v[84:87]
	v_mfma_f32_16x16x32_bf16 v[80:83], v[168:171], v[200:203], v[80:83]
	v_mfma_f32_16x16x32_bf16 v[80:83], v[172:175], v[204:207], v[80:83]
	v_mfma_f32_16x16x32_bf16 v[64:67], v[168:171], v[208:211], v[64:67]
	v_mfma_f32_16x16x32_bf16 v[64:67], v[172:175], v[212:215], v[64:67]
	v_mfma_f32_16x16x32_bf16 v[68:71], v[144:147], v[208:211], v[68:71]
	v_mfma_f32_16x16x32_bf16 v[68:71], v[148:151], v[212:215], v[68:71]
	v_mfma_f32_16x16x32_bf16 v[72:75], v[136:139], v[208:211], v[72:75]
	v_mfma_f32_16x16x32_bf16 v[72:75], v[140:143], v[212:215], v[72:75]
	v_mfma_f32_16x16x32_bf16 v[76:79], v[128:131], v[208:211], v[76:79]
	v_mfma_f32_16x16x32_bf16 v[76:79], v[132:135], v[212:215], v[76:79]
	s_setprio 0
	s_barrier
	s_add_i32 s55, s46, s34
	v_lshl_add_u64 v[176:177], s[60:61], 0, v[154:155]
	s_mov_b32 m0, s55
	ds_read_b128 v[184:187], v183 offset:16384
	ds_read_b128 v[188:191], v183 offset:17408
	ds_read_b128 v[192:195], v183 offset:18432
	ds_read_b128 v[196:199], v183 offset:19456
	ds_read_b128 v[200:203], v183 offset:20480
	ds_read_b128 v[204:207], v183 offset:21504
	ds_read_b128 v[208:211], v183 offset:22528
	ds_read_b128 v[212:215], v183 offset:23552
	global_load_lds_dwordx4 v[176:177], off
	s_add_i32 m0, s55, 0x2000
	v_lshl_add_u64 v[216:217], s[60:61], 0, v[158:159]
	s_add_u32 s60, s60, s8
	s_addc_u32 s61, s61, s9
	s_add_i32 s55, s47, s34
	global_load_lds_dwordx4 v[216:217], off
	v_lshl_add_u64 v[218:219], s[60:61], 0, v[154:155]
	s_mov_b32 m0, s55
	v_lshl_add_u64 v[222:223], s[60:61], 0, v[158:159]
	global_load_lds_dwordx4 v[218:219], off
	s_add_i32 m0, s55, 0x2000
	v_lshl_add_u64 v[224:225], s[26:27], 0, v[152:153]
	global_load_lds_dwordx4 v[222:223], off
	s_mov_b32 m0, s35
	v_lshl_add_u64 v[226:227], s[26:27], 0, v[156:157]
	global_load_lds_dwordx4 v[224:225], off
	s_mov_b32 m0, s36
	s_nop 0
	global_load_lds_dwordx4 v[226:227], off
	s_waitcnt vmcnt(8)
	s_waitcnt lgkmcnt(0)
	s_barrier
	s_setprio 1
	s_waitcnt lgkmcnt(0)
	v_mfma_f32_16x16x32_bf16 v[60:63], v[128:131], v[184:187], v[60:63]
	v_mfma_f32_16x16x32_bf16 v[60:63], v[132:135], v[188:191], v[60:63]
	v_mfma_f32_16x16x32_bf16 v[56:59], v[136:139], v[184:187], v[56:59]
	v_mfma_f32_16x16x32_bf16 v[56:59], v[140:143], v[188:191], v[56:59]
	v_mfma_f32_16x16x32_bf16 v[52:55], v[144:147], v[184:187], v[52:55]
	v_mfma_f32_16x16x32_bf16 v[52:55], v[148:151], v[188:191], v[52:55]
	v_mfma_f32_16x16x32_bf16 v[48:51], v[168:171], v[184:187], v[48:51]
	v_mfma_f32_16x16x32_bf16 v[48:51], v[172:175], v[188:191], v[48:51]
	v_mfma_f32_16x16x32_bf16 v[32:35], v[168:171], v[192:195], v[32:35]
	v_mfma_f32_16x16x32_bf16 v[32:35], v[172:175], v[196:199], v[32:35]
	v_mfma_f32_16x16x32_bf16 v[36:39], v[144:147], v[192:195], v[36:39]
	v_mfma_f32_16x16x32_bf16 v[36:39], v[148:151], v[196:199], v[36:39]
	v_mfma_f32_16x16x32_bf16 v[40:43], v[136:139], v[192:195], v[40:43]
	v_mfma_f32_16x16x32_bf16 v[40:43], v[140:143], v[196:199], v[40:43]
	v_mfma_f32_16x16x32_bf16 v[44:47], v[128:131], v[192:195], v[44:47]
	v_mfma_f32_16x16x32_bf16 v[44:47], v[132:135], v[196:199], v[44:47]
	v_mfma_f32_16x16x32_bf16 v[28:31], v[128:131], v[200:203], v[28:31]
	v_mfma_f32_16x16x32_bf16 v[28:31], v[132:135], v[204:207], v[28:31]
	v_mfma_f32_16x16x32_bf16 v[24:27], v[136:139], v[200:203], v[24:27]
	v_mfma_f32_16x16x32_bf16 v[24:27], v[140:143], v[204:207], v[24:27]
	v_mfma_f32_16x16x32_bf16 v[20:23], v[144:147], v[200:203], v[20:23]
	v_mfma_f32_16x16x32_bf16 v[20:23], v[148:151], v[204:207], v[20:23]
	v_mfma_f32_16x16x32_bf16 v[16:19], v[168:171], v[200:203], v[16:19]
	v_mfma_f32_16x16x32_bf16 v[16:19], v[172:175], v[204:207], v[16:19]
	v_mfma_f32_16x16x32_bf16 v[0:3], v[168:171], v[208:211], v[0:3]
	v_mfma_f32_16x16x32_bf16 v[0:3], v[172:175], v[212:215], v[0:3]
	v_mfma_f32_16x16x32_bf16 v[4:7], v[144:147], v[208:211], v[4:7]
	v_mfma_f32_16x16x32_bf16 v[4:7], v[148:151], v[212:215], v[4:7]
	v_mfma_f32_16x16x32_bf16 v[8:11], v[136:139], v[208:211], v[8:11]
	v_mfma_f32_16x16x32_bf16 v[8:11], v[140:143], v[212:215], v[8:11]
	v_mfma_f32_16x16x32_bf16 v[12:15], v[128:131], v[208:211], v[12:15]
	v_mfma_f32_16x16x32_bf16 v[12:15], v[132:135], v[212:215], v[12:15]
	s_setprio 0
	s_barrier
	s_add_i32 s55, 0, 0x18000
	s_add_i32 s60, 0, 0x1c000
	v_add_u32_e32 v140, s55, v179
	v_add_u32_e32 v172, s60, v179
	ds_read_b128 v[128:131], v140
	ds_read_b128 v[132:135], v140 offset:1024
	ds_read_b128 v[136:139], v140 offset:2048
	ds_read_b128 v[140:143], v140 offset:3072
	ds_read_b128 v[144:147], v172
	ds_read_b128 v[148:151], v172 offset:1024
	ds_read_b128 v[168:171], v172 offset:2048
	ds_read_b128 v[172:175], v172 offset:3072
	s_add_u32 s26, s26, s8
	s_addc_u32 s27, s27, s9
	s_mov_b32 m0, s37
	v_lshl_add_u64 v[228:229], s[26:27], 0, v[152:153]
	ds_read_b128 v[184:187], v183 offset:32768
	ds_read_b128 v[188:191], v183 offset:33792
	ds_read_b128 v[192:195], v183 offset:34816
	ds_read_b128 v[196:199], v183 offset:35840
	ds_read_b128 v[200:203], v183 offset:36864
	ds_read_b128 v[204:207], v183 offset:37888
	ds_read_b128 v[208:211], v183 offset:38912
	ds_read_b128 v[212:215], v183 offset:39936
	global_load_lds_dwordx4 v[228:229], off
	v_lshl_add_u64 v[228:229], s[26:27], 0, v[156:157]
	s_mov_b32 m0, s38
	s_nop 0
	global_load_lds_dwordx4 v[228:229], off
	s_waitcnt vmcnt(8)
	s_waitcnt lgkmcnt(0)
	s_barrier
	s_setprio 1
	s_waitcnt lgkmcnt(0)
	v_mfma_f32_16x16x32_bf16 v[120:123], v[128:131], v[184:187], v[120:123]
	v_mfma_f32_16x16x32_bf16 v[120:123], v[132:135], v[188:191], v[120:123]
	v_mfma_f32_16x16x32_bf16 v[124:127], v[136:139], v[184:187], v[124:127]
	v_mfma_f32_16x16x32_bf16 v[124:127], v[140:143], v[188:191], v[124:127]
	v_mfma_f32_16x16x32_bf16 v[116:119], v[144:147], v[184:187], v[116:119]
	v_mfma_f32_16x16x32_bf16 v[116:119], v[148:151], v[188:191], v[116:119]
	v_mfma_f32_16x16x32_bf16 v[112:115], v[168:171], v[184:187], v[112:115]
	v_mfma_f32_16x16x32_bf16 v[112:115], v[172:175], v[188:191], v[112:115]
	v_mfma_f32_16x16x32_bf16 v[96:99], v[168:171], v[192:195], v[96:99]
	v_mfma_f32_16x16x32_bf16 v[96:99], v[172:175], v[196:199], v[96:99]
	v_mfma_f32_16x16x32_bf16 v[100:103], v[144:147], v[192:195], v[100:103]
	v_mfma_f32_16x16x32_bf16 v[100:103], v[148:151], v[196:199], v[100:103]
	v_mfma_f32_16x16x32_bf16 v[104:107], v[136:139], v[192:195], v[104:107]
	v_mfma_f32_16x16x32_bf16 v[104:107], v[140:143], v[196:199], v[104:107]
	v_mfma_f32_16x16x32_bf16 v[108:111], v[128:131], v[192:195], v[108:111]
	v_mfma_f32_16x16x32_bf16 v[108:111], v[132:135], v[196:199], v[108:111]
	v_mfma_f32_16x16x32_bf16 v[92:95], v[128:131], v[200:203], v[92:95]
	v_mfma_f32_16x16x32_bf16 v[92:95], v[132:135], v[204:207], v[92:95]
	v_mfma_f32_16x16x32_bf16 v[88:91], v[136:139], v[200:203], v[88:91]
	v_mfma_f32_16x16x32_bf16 v[88:91], v[140:143], v[204:207], v[88:91]
	v_mfma_f32_16x16x32_bf16 v[84:87], v[144:147], v[200:203], v[84:87]
	v_mfma_f32_16x16x32_bf16 v[84:87], v[148:151], v[204:207], v[84:87]
	v_mfma_f32_16x16x32_bf16 v[80:83], v[168:171], v[200:203], v[80:83]
	v_mfma_f32_16x16x32_bf16 v[80:83], v[172:175], v[204:207], v[80:83]
	v_mfma_f32_16x16x32_bf16 v[64:67], v[168:171], v[208:211], v[64:67]
	v_mfma_f32_16x16x32_bf16 v[64:67], v[172:175], v[212:215], v[64:67]
	v_mfma_f32_16x16x32_bf16 v[68:71], v[144:147], v[208:211], v[68:71]
	v_mfma_f32_16x16x32_bf16 v[68:71], v[148:151], v[212:215], v[68:71]
	v_mfma_f32_16x16x32_bf16 v[72:75], v[136:139], v[208:211], v[72:75]
	v_mfma_f32_16x16x32_bf16 v[72:75], v[140:143], v[212:215], v[72:75]
	v_mfma_f32_16x16x32_bf16 v[76:79], v[128:131], v[208:211], v[76:79]
	v_mfma_f32_16x16x32_bf16 v[76:79], v[132:135], v[212:215], v[76:79]
	s_setprio 0
	s_barrier
	s_add_i32 s26, s55, s34
	v_lshl_add_u64 v[176:177], v[176:177], 0, s[16:17]
	s_mov_b32 m0, s26
	ds_read_b128 v[184:187], v183 offset:49152
	ds_read_b128 v[188:191], v183 offset:50176
	ds_read_b128 v[192:195], v183 offset:51200
	ds_read_b128 v[196:199], v183 offset:52224
	ds_read_b128 v[200:203], v183 offset:53248
	ds_read_b128 v[204:207], v183 offset:54272
	ds_read_b128 v[208:211], v183 offset:55296
	ds_read_b128 v[212:215], v183 offset:56320
	global_load_lds_dwordx4 v[176:177], off
	v_lshl_add_u64 v[176:177], v[216:217], 0, s[16:17]
	s_add_i32 m0, s26, 0x2000
	s_add_i32 s26, s60, s34
	global_load_lds_dwordx4 v[176:177], off
	v_lshl_add_u64 v[176:177], v[218:219], 0, s[16:17]
	s_mov_b32 m0, s26
	s_nop 0
	global_load_lds_dwordx4 v[176:177], off
	v_lshl_add_u64 v[176:177], v[222:223], 0, s[16:17]
	s_add_i32 m0, s26, 0x2000
	s_nop 0
	global_load_lds_dwordx4 v[176:177], off
	v_lshl_add_u64 v[176:177], v[224:225], 0, s[16:17]
	s_mov_b32 m0, s40
	s_nop 0
	global_load_lds_dwordx4 v[176:177], off
	v_lshl_add_u64 v[176:177], v[226:227], 0, s[16:17]
	s_mov_b32 m0, s41
	s_nop 0
	global_load_lds_dwordx4 v[176:177], off
	s_waitcnt vmcnt(8)
	s_waitcnt lgkmcnt(0)
	s_barrier
	s_setprio 1
	s_waitcnt lgkmcnt(0)
	v_mfma_f32_16x16x32_bf16 v[60:63], v[128:131], v[184:187], v[60:63]
	v_mfma_f32_16x16x32_bf16 v[60:63], v[132:135], v[188:191], v[60:63]
	v_mfma_f32_16x16x32_bf16 v[56:59], v[136:139], v[184:187], v[56:59]
	v_mfma_f32_16x16x32_bf16 v[56:59], v[140:143], v[188:191], v[56:59]
	v_mfma_f32_16x16x32_bf16 v[52:55], v[144:147], v[184:187], v[52:55]
	v_mfma_f32_16x16x32_bf16 v[52:55], v[148:151], v[188:191], v[52:55]
	v_mfma_f32_16x16x32_bf16 v[48:51], v[168:171], v[184:187], v[48:51]
	v_mfma_f32_16x16x32_bf16 v[48:51], v[172:175], v[188:191], v[48:51]
	v_mfma_f32_16x16x32_bf16 v[32:35], v[168:171], v[192:195], v[32:35]
	v_mfma_f32_16x16x32_bf16 v[32:35], v[172:175], v[196:199], v[32:35]
	v_mfma_f32_16x16x32_bf16 v[36:39], v[144:147], v[192:195], v[36:39]
	v_mfma_f32_16x16x32_bf16 v[36:39], v[148:151], v[196:199], v[36:39]
	v_mfma_f32_16x16x32_bf16 v[40:43], v[136:139], v[192:195], v[40:43]
	v_mfma_f32_16x16x32_bf16 v[40:43], v[140:143], v[196:199], v[40:43]
	v_mfma_f32_16x16x32_bf16 v[44:47], v[128:131], v[192:195], v[44:47]
	v_mfma_f32_16x16x32_bf16 v[44:47], v[132:135], v[196:199], v[44:47]
	v_mfma_f32_16x16x32_bf16 v[28:31], v[128:131], v[200:203], v[28:31]
	v_mfma_f32_16x16x32_bf16 v[28:31], v[132:135], v[204:207], v[28:31]
	v_mfma_f32_16x16x32_bf16 v[24:27], v[136:139], v[200:203], v[24:27]
	v_mfma_f32_16x16x32_bf16 v[24:27], v[140:143], v[204:207], v[24:27]
	v_mfma_f32_16x16x32_bf16 v[20:23], v[144:147], v[200:203], v[20:23]
	v_mfma_f32_16x16x32_bf16 v[20:23], v[148:151], v[204:207], v[20:23]
	v_mfma_f32_16x16x32_bf16 v[16:19], v[168:171], v[200:203], v[16:19]
	v_mfma_f32_16x16x32_bf16 v[16:19], v[172:175], v[204:207], v[16:19]
	v_mfma_f32_16x16x32_bf16 v[0:3], v[168:171], v[208:211], v[0:3]
	v_mfma_f32_16x16x32_bf16 v[0:3], v[172:175], v[212:215], v[0:3]
	v_mfma_f32_16x16x32_bf16 v[4:7], v[144:147], v[208:211], v[4:7]
	v_mfma_f32_16x16x32_bf16 v[4:7], v[148:151], v[212:215], v[4:7]
	v_mfma_f32_16x16x32_bf16 v[8:11], v[136:139], v[208:211], v[8:11]
	v_mfma_f32_16x16x32_bf16 v[8:11], v[140:143], v[212:215], v[8:11]
	v_mfma_f32_16x16x32_bf16 v[12:15], v[128:131], v[208:211], v[12:15]
	v_mfma_f32_16x16x32_bf16 v[12:15], v[132:135], v[212:215], v[12:15]
	s_setprio 0
	s_barrier
	s_add_u32 s24, s24, 0x100
	s_addc_u32 s25, s25, 0
	s_add_u32 s52, s52, 0x100
	s_addc_u32 s53, s53, 0
	s_cmp_ge_i32 s54, s42
	s_mov_b32 s26, s54
	s_cbranch_scc0 .LBB0_763

.LBB0_849:
	ds_read_b128 v[112:115], v209
	ds_read_b128 v[116:119], v209 offset:1024
	ds_read_b128 v[120:123], v209 offset:2048
	ds_read_b128 v[128:131], v209 offset:3072
	ds_read_b128 v[144:147], v210
	ds_read_b128 v[148:151], v210 offset:1024
	ds_read_b128 v[152:155], v210 offset:2048
	ds_read_b128 v[156:159], v210 offset:3072
	s_add_i32 s62, s30, 2
	s_add_u32 s63, s28, 0x80
	s_addc_u32 s31, s29, 0
	s_cmp_eq_u32 s46, s30
	s_cselect_b32 s30, s4, s63
	s_cselect_b32 s31, s5, s31
	s_cselect_b32 s65, s27, s61
	s_cselect_b32 s64, s26, s60
	v_lshl_add_u64 v[204:205], s[28:29], 0, v[180:181]
	s_add_i32 m0, s38, 0xc000
	ds_read_b128 v[160:163], v211
	ds_read_b128 v[164:167], v211 offset:1024
	ds_read_b128 v[168:171], v211 offset:2048
	ds_read_b128 v[172:175], v211 offset:3072
	ds_read_b128 v[188:191], v211 offset:4096
	ds_read_b128 v[192:195], v211 offset:5120
	ds_read_b128 v[196:199], v211 offset:6144
	ds_read_b128 v[200:203], v211 offset:7168
	global_load_lds_dwordx4 v[204:205], off
	v_lshl_add_u64 v[204:205], s[28:29], 0, v[182:183]
	s_add_i32 m0, s38, 0xe000
	s_nop 0
	global_load_lds_dwordx4 v[204:205], off
	s_waitcnt vmcnt(8)
	s_waitcnt lgkmcnt(0)
	s_barrier
	s_setprio 1
	s_waitcnt lgkmcnt(0)
	v_mfma_f32_16x16x32_bf16 v[136:139], v[112:115], v[160:163], v[136:139]
	v_mfma_f32_16x16x32_bf16 v[136:139], v[116:119], v[164:167], v[136:139]
	v_mfma_f32_16x16x32_bf16 v[140:143], v[120:123], v[160:163], v[140:143]
	v_mfma_f32_16x16x32_bf16 v[140:143], v[128:131], v[164:167], v[140:143]
	v_mfma_f32_16x16x32_bf16 v[132:135], v[144:147], v[160:163], v[132:135]
	v_mfma_f32_16x16x32_bf16 v[132:135], v[148:151], v[164:167], v[132:135]
	v_mfma_f32_16x16x32_bf16 v[124:127], v[152:155], v[160:163], v[124:127]
	v_mfma_f32_16x16x32_bf16 v[124:127], v[156:159], v[164:167], v[124:127]
	v_mfma_f32_16x16x32_bf16 v[96:99], v[152:155], v[168:171], v[96:99]
	v_mfma_f32_16x16x32_bf16 v[96:99], v[156:159], v[172:175], v[96:99]
	v_mfma_f32_16x16x32_bf16 v[100:103], v[144:147], v[168:171], v[100:103]
	v_mfma_f32_16x16x32_bf16 v[100:103], v[148:151], v[172:175], v[100:103]
	v_mfma_f32_16x16x32_bf16 v[104:107], v[120:123], v[168:171], v[104:107]
	v_mfma_f32_16x16x32_bf16 v[104:107], v[128:131], v[172:175], v[104:107]
	v_mfma_f32_16x16x32_bf16 v[108:111], v[112:115], v[168:171], v[108:111]
	v_mfma_f32_16x16x32_bf16 v[108:111], v[116:119], v[172:175], v[108:111]
	v_mfma_f32_16x16x32_bf16 v[92:95], v[112:115], v[188:191], v[92:95]
	v_mfma_f32_16x16x32_bf16 v[92:95], v[116:119], v[192:195], v[92:95]
	v_mfma_f32_16x16x32_bf16 v[88:91], v[120:123], v[188:191], v[88:91]
	v_mfma_f32_16x16x32_bf16 v[88:91], v[128:131], v[192:195], v[88:91]
	v_mfma_f32_16x16x32_bf16 v[84:87], v[144:147], v[188:191], v[84:87]
	v_mfma_f32_16x16x32_bf16 v[84:87], v[148:151], v[192:195], v[84:87]
	v_mfma_f32_16x16x32_bf16 v[80:83], v[152:155], v[188:191], v[80:83]
	v_mfma_f32_16x16x32_bf16 v[80:83], v[156:159], v[192:195], v[80:83]
	v_mfma_f32_16x16x32_bf16 v[64:67], v[152:155], v[196:199], v[64:67]
	v_mfma_f32_16x16x32_bf16 v[64:67], v[156:159], v[200:203], v[64:67]
	v_mfma_f32_16x16x32_bf16 v[68:71], v[144:147], v[196:199], v[68:71]
	v_mfma_f32_16x16x32_bf16 v[68:71], v[148:151], v[200:203], v[68:71]
	v_mfma_f32_16x16x32_bf16 v[72:75], v[120:123], v[196:199], v[72:75]
	v_mfma_f32_16x16x32_bf16 v[72:75], v[128:131], v[200:203], v[72:75]
	v_mfma_f32_16x16x32_bf16 v[76:79], v[112:115], v[196:199], v[76:79]
	v_mfma_f32_16x16x32_bf16 v[76:79], v[116:119], v[200:203], v[76:79]
	s_setprio 0
	s_barrier
	s_add_i32 s63, s50, s37
	v_lshl_add_u64 v[204:205], s[64:65], 0, v[176:177]
	s_mov_b32 m0, s63
	ds_read_b128 v[160:163], v211 offset:16384
	ds_read_b128 v[164:167], v211 offset:17408
	ds_read_b128 v[168:171], v211 offset:18432
	ds_read_b128 v[172:175], v211 offset:19456
	ds_read_b128 v[188:191], v211 offset:20480
	ds_read_b128 v[192:195], v211 offset:21504
	ds_read_b128 v[196:199], v211 offset:22528
	ds_read_b128 v[200:203], v211 offset:23552
	global_load_lds_dwordx4 v[204:205], off
	s_add_i32 m0, s63, 0x2000
	v_lshl_add_u64 v[214:215], s[64:65], 0, v[178:179]
	s_add_u32 s64, s64, s10
	s_addc_u32 s65, s65, s11
	s_add_i32 s63, s51, s37
	global_load_lds_dwordx4 v[214:215], off
	v_lshl_add_u64 v[216:217], s[64:65], 0, v[176:177]
	s_mov_b32 m0, s63
	v_lshl_add_u64 v[218:219], s[64:65], 0, v[178:179]
	global_load_lds_dwordx4 v[216:217], off
	s_add_i32 m0, s63, 0x2000
	v_lshl_add_u64 v[222:223], s[30:31], 0, v[176:177]
	global_load_lds_dwordx4 v[218:219], off
	s_mov_b32 m0, s38
	v_lshl_add_u64 v[224:225], s[30:31], 0, v[178:179]
	global_load_lds_dwordx4 v[222:223], off
	s_mov_b32 m0, s39
	s_nop 0
	global_load_lds_dwordx4 v[224:225], off
	s_waitcnt vmcnt(8)
	s_waitcnt lgkmcnt(0)
	s_barrier
	s_setprio 1
	s_waitcnt lgkmcnt(0)
	v_mfma_f32_16x16x32_bf16 v[60:63], v[112:115], v[160:163], v[60:63]
	v_mfma_f32_16x16x32_bf16 v[60:63], v[116:119], v[164:167], v[60:63]
	v_mfma_f32_16x16x32_bf16 v[56:59], v[120:123], v[160:163], v[56:59]
	v_mfma_f32_16x16x32_bf16 v[56:59], v[128:131], v[164:167], v[56:59]
	v_mfma_f32_16x16x32_bf16 v[52:55], v[144:147], v[160:163], v[52:55]
	v_mfma_f32_16x16x32_bf16 v[52:55], v[148:151], v[164:167], v[52:55]
	v_mfma_f32_16x16x32_bf16 v[48:51], v[152:155], v[160:163], v[48:51]
	v_mfma_f32_16x16x32_bf16 v[48:51], v[156:159], v[164:167], v[48:51]
	v_mfma_f32_16x16x32_bf16 v[32:35], v[152:155], v[168:171], v[32:35]
	v_mfma_f32_16x16x32_bf16 v[32:35], v[156:159], v[172:175], v[32:35]
	v_mfma_f32_16x16x32_bf16 v[36:39], v[144:147], v[168:171], v[36:39]
	v_mfma_f32_16x16x32_bf16 v[36:39], v[148:151], v[172:175], v[36:39]
	v_mfma_f32_16x16x32_bf16 v[40:43], v[120:123], v[168:171], v[40:43]
	v_mfma_f32_16x16x32_bf16 v[40:43], v[128:131], v[172:175], v[40:43]
	v_mfma_f32_16x16x32_bf16 v[44:47], v[112:115], v[168:171], v[44:47]
	v_mfma_f32_16x16x32_bf16 v[44:47], v[116:119], v[172:175], v[44:47]
	v_mfma_f32_16x16x32_bf16 v[28:31], v[112:115], v[188:191], v[28:31]
	v_mfma_f32_16x16x32_bf16 v[28:31], v[116:119], v[192:195], v[28:31]
	v_mfma_f32_16x16x32_bf16 v[24:27], v[120:123], v[188:191], v[24:27]
	v_mfma_f32_16x16x32_bf16 v[24:27], v[128:131], v[192:195], v[24:27]
	v_mfma_f32_16x16x32_bf16 v[20:23], v[144:147], v[188:191], v[20:23]
	v_mfma_f32_16x16x32_bf16 v[20:23], v[148:151], v[192:195], v[20:23]
	v_mfma_f32_16x16x32_bf16 v[16:19], v[152:155], v[188:191], v[16:19]
	v_mfma_f32_16x16x32_bf16 v[16:19], v[156:159], v[192:195], v[16:19]
	v_mfma_f32_16x16x32_bf16 v[0:3], v[152:155], v[196:199], v[0:3]
	v_mfma_f32_16x16x32_bf16 v[0:3], v[156:159], v[200:203], v[0:3]
	v_mfma_f32_16x16x32_bf16 v[4:7], v[144:147], v[196:199], v[4:7]
	v_mfma_f32_16x16x32_bf16 v[4:7], v[148:151], v[200:203], v[4:7]
	v_mfma_f32_16x16x32_bf16 v[8:11], v[120:123], v[196:199], v[8:11]
	v_mfma_f32_16x16x32_bf16 v[8:11], v[128:131], v[200:203], v[8:11]
	v_mfma_f32_16x16x32_bf16 v[12:15], v[112:115], v[196:199], v[12:15]
	v_mfma_f32_16x16x32_bf16 v[12:15], v[116:119], v[200:203], v[12:15]
	s_setprio 0
	s_barrier
	s_add_i32 s63, 0, 0x18000
	s_add_i32 s64, 0, 0x1c000
	v_add_u32_e32 v128, s63, v207
	v_add_u32_e32 v156, s64, v207
	ds_read_b128 v[112:115], v128
	ds_read_b128 v[116:119], v128 offset:1024
	ds_read_b128 v[120:123], v128 offset:2048
	ds_read_b128 v[128:131], v128 offset:3072
	ds_read_b128 v[144:147], v156
	ds_read_b128 v[148:151], v156 offset:1024
	ds_read_b128 v[152:155], v156 offset:2048
	ds_read_b128 v[156:159], v156 offset:3072
	s_add_u32 s30, s30, s10
	s_addc_u32 s31, s31, s11
	s_mov_b32 m0, s40
	v_lshl_add_u64 v[226:227], s[30:31], 0, v[176:177]
	ds_read_b128 v[160:163], v211 offset:32768
	ds_read_b128 v[164:167], v211 offset:33792
	ds_read_b128 v[168:171], v211 offset:34816
	ds_read_b128 v[172:175], v211 offset:35840
	ds_read_b128 v[188:191], v211 offset:36864
	ds_read_b128 v[192:195], v211 offset:37888
	ds_read_b128 v[196:199], v211 offset:38912
	ds_read_b128 v[200:203], v211 offset:39936
	global_load_lds_dwordx4 v[226:227], off
	v_lshl_add_u64 v[226:227], s[30:31], 0, v[178:179]
	s_mov_b32 m0, s41
	s_nop 0
	global_load_lds_dwordx4 v[226:227], off
	s_waitcnt vmcnt(8)
	s_waitcnt lgkmcnt(0)
	s_barrier
	s_setprio 1
	s_waitcnt lgkmcnt(0)
	v_mfma_f32_16x16x32_bf16 v[136:139], v[112:115], v[160:163], v[136:139]
	v_mfma_f32_16x16x32_bf16 v[136:139], v[116:119], v[164:167], v[136:139]
	v_mfma_f32_16x16x32_bf16 v[140:143], v[120:123], v[160:163], v[140:143]
	v_mfma_f32_16x16x32_bf16 v[140:143], v[128:131], v[164:167], v[140:143]
	v_mfma_f32_16x16x32_bf16 v[132:135], v[144:147], v[160:163], v[132:135]
	v_mfma_f32_16x16x32_bf16 v[132:135], v[148:151], v[164:167], v[132:135]
	v_mfma_f32_16x16x32_bf16 v[124:127], v[152:155], v[160:163], v[124:127]
	v_mfma_f32_16x16x32_bf16 v[124:127], v[156:159], v[164:167], v[124:127]
	v_mfma_f32_16x16x32_bf16 v[96:99], v[152:155], v[168:171], v[96:99]
	v_mfma_f32_16x16x32_bf16 v[96:99], v[156:159], v[172:175], v[96:99]
	v_mfma_f32_16x16x32_bf16 v[100:103], v[144:147], v[168:171], v[100:103]
	v_mfma_f32_16x16x32_bf16 v[100:103], v[148:151], v[172:175], v[100:103]
	v_mfma_f32_16x16x32_bf16 v[104:107], v[120:123], v[168:171], v[104:107]
	v_mfma_f32_16x16x32_bf16 v[104:107], v[128:131], v[172:175], v[104:107]
	v_mfma_f32_16x16x32_bf16 v[108:111], v[112:115], v[168:171], v[108:111]
	v_mfma_f32_16x16x32_bf16 v[108:111], v[116:119], v[172:175], v[108:111]
	v_mfma_f32_16x16x32_bf16 v[92:95], v[112:115], v[188:191], v[92:95]
	v_mfma_f32_16x16x32_bf16 v[92:95], v[116:119], v[192:195], v[92:95]
	v_mfma_f32_16x16x32_bf16 v[88:91], v[120:123], v[188:191], v[88:91]
	v_mfma_f32_16x16x32_bf16 v[88:91], v[128:131], v[192:195], v[88:91]
	v_mfma_f32_16x16x32_bf16 v[84:87], v[144:147], v[188:191], v[84:87]
	v_mfma_f32_16x16x32_bf16 v[84:87], v[148:151], v[192:195], v[84:87]
	v_mfma_f32_16x16x32_bf16 v[80:83], v[152:155], v[188:191], v[80:83]
	v_mfma_f32_16x16x32_bf16 v[80:83], v[156:159], v[192:195], v[80:83]
	v_mfma_f32_16x16x32_bf16 v[64:67], v[152:155], v[196:199], v[64:67]
	v_mfma_f32_16x16x32_bf16 v[64:67], v[156:159], v[200:203], v[64:67]
	v_mfma_f32_16x16x32_bf16 v[68:71], v[144:147], v[196:199], v[68:71]
	v_mfma_f32_16x16x32_bf16 v[68:71], v[148:151], v[200:203], v[68:71]
	v_mfma_f32_16x16x32_bf16 v[72:75], v[120:123], v[196:199], v[72:75]
	v_mfma_f32_16x16x32_bf16 v[72:75], v[128:131], v[200:203], v[72:75]
	v_mfma_f32_16x16x32_bf16 v[76:79], v[112:115], v[196:199], v[76:79]
	v_mfma_f32_16x16x32_bf16 v[76:79], v[116:119], v[200:203], v[76:79]
	s_setprio 0
	s_barrier
	s_add_i32 s30, s63, s37
	v_lshl_add_u64 v[204:205], v[204:205], 0, s[18:19]
	s_mov_b32 m0, s30
	ds_read_b128 v[160:163], v211 offset:49152
	ds_read_b128 v[164:167], v211 offset:50176
	ds_read_b128 v[168:171], v211 offset:51200
	ds_read_b128 v[172:175], v211 offset:52224
	ds_read_b128 v[188:191], v211 offset:53248
	ds_read_b128 v[192:195], v211 offset:54272
	ds_read_b128 v[196:199], v211 offset:55296
	ds_read_b128 v[200:203], v211 offset:56320
	global_load_lds_dwordx4 v[204:205], off
	v_lshl_add_u64 v[204:205], v[214:215], 0, s[18:19]
	s_add_i32 m0, s30, 0x2000
	s_add_i32 s30, s64, s37
	global_load_lds_dwordx4 v[204:205], off
	v_lshl_add_u64 v[204:205], v[216:217], 0, s[18:19]
	s_mov_b32 m0, s30
	s_nop 0
	global_load_lds_dwordx4 v[204:205], off
	v_lshl_add_u64 v[204:205], v[218:219], 0, s[18:19]
	s_add_i32 m0, s30, 0x2000
	s_nop 0
	global_load_lds_dwordx4 v[204:205], off
	v_lshl_add_u64 v[204:205], v[222:223], 0, s[18:19]
	s_mov_b32 m0, s43
	s_nop 0
	global_load_lds_dwordx4 v[204:205], off
	v_lshl_add_u64 v[204:205], v[224:225], 0, s[18:19]
	s_mov_b32 m0, s44
	s_nop 0
	global_load_lds_dwordx4 v[204:205], off
	s_waitcnt vmcnt(8)
	s_waitcnt lgkmcnt(0)
	s_barrier
	s_setprio 1
	s_waitcnt lgkmcnt(0)
	v_mfma_f32_16x16x32_bf16 v[60:63], v[112:115], v[160:163], v[60:63]
	v_mfma_f32_16x16x32_bf16 v[60:63], v[116:119], v[164:167], v[60:63]
	v_mfma_f32_16x16x32_bf16 v[56:59], v[120:123], v[160:163], v[56:59]
	v_mfma_f32_16x16x32_bf16 v[56:59], v[128:131], v[164:167], v[56:59]
	v_mfma_f32_16x16x32_bf16 v[52:55], v[144:147], v[160:163], v[52:55]
	v_mfma_f32_16x16x32_bf16 v[52:55], v[148:151], v[164:167], v[52:55]
	v_mfma_f32_16x16x32_bf16 v[48:51], v[152:155], v[160:163], v[48:51]
	v_mfma_f32_16x16x32_bf16 v[48:51], v[156:159], v[164:167], v[48:51]
	v_mfma_f32_16x16x32_bf16 v[32:35], v[152:155], v[168:171], v[32:35]
	v_mfma_f32_16x16x32_bf16 v[32:35], v[156:159], v[172:175], v[32:35]
	v_mfma_f32_16x16x32_bf16 v[36:39], v[144:147], v[168:171], v[36:39]
	v_mfma_f32_16x16x32_bf16 v[36:39], v[148:151], v[172:175], v[36:39]
	v_mfma_f32_16x16x32_bf16 v[40:43], v[120:123], v[168:171], v[40:43]
	v_mfma_f32_16x16x32_bf16 v[40:43], v[128:131], v[172:175], v[40:43]
	v_mfma_f32_16x16x32_bf16 v[44:47], v[112:115], v[168:171], v[44:47]
	v_mfma_f32_16x16x32_bf16 v[44:47], v[116:119], v[172:175], v[44:47]
	v_mfma_f32_16x16x32_bf16 v[28:31], v[112:115], v[188:191], v[28:31]
	v_mfma_f32_16x16x32_bf16 v[28:31], v[116:119], v[192:195], v[28:31]
	v_mfma_f32_16x16x32_bf16 v[24:27], v[120:123], v[188:191], v[24:27]
	v_mfma_f32_16x16x32_bf16 v[24:27], v[128:131], v[192:195], v[24:27]
	v_mfma_f32_16x16x32_bf16 v[20:23], v[144:147], v[188:191], v[20:23]
	v_mfma_f32_16x16x32_bf16 v[20:23], v[148:151], v[192:195], v[20:23]
	v_mfma_f32_16x16x32_bf16 v[16:19], v[152:155], v[188:191], v[16:19]
	v_mfma_f32_16x16x32_bf16 v[16:19], v[156:159], v[192:195], v[16:19]
	v_mfma_f32_16x16x32_bf16 v[0:3], v[152:155], v[196:199], v[0:3]
	v_mfma_f32_16x16x32_bf16 v[0:3], v[156:159], v[200:203], v[0:3]
	v_mfma_f32_16x16x32_bf16 v[4:7], v[144:147], v[196:199], v[4:7]
	v_mfma_f32_16x16x32_bf16 v[4:7], v[148:151], v[200:203], v[4:7]
	v_mfma_f32_16x16x32_bf16 v[8:11], v[120:123], v[196:199], v[8:11]
	v_mfma_f32_16x16x32_bf16 v[8:11], v[128:131], v[200:203], v[8:11]
	v_mfma_f32_16x16x32_bf16 v[12:15], v[112:115], v[196:199], v[12:15]
	v_mfma_f32_16x16x32_bf16 v[12:15], v[116:119], v[200:203], v[12:15]
	s_setprio 0
	s_barrier
	s_add_u32 s28, s28, 0x100
	s_addc_u32 s29, s29, 0
	s_add_u32 s60, s60, 0x100
	s_addc_u32 s61, s61, 0
	s_cmp_ge_i32 s62, s45
	s_mov_b32 s30, s62
	s_cbranch_scc0 .LBB0_849

.LBB0_949:
	ds_read_b128 v[164:167], v157
	ds_read_b128 v[168:171], v157 offset:1024
	ds_read_b128 v[172:175], v157 offset:2048
	ds_read_b128 v[176:179], v157 offset:3072
	ds_read_b128 v[180:183], v162
	ds_read_b128 v[184:187], v162 offset:1024
	ds_read_b128 v[188:191], v162 offset:2048
	ds_read_b128 v[192:195], v162 offset:3072
	s_add_i32 s68, s34, 2
	s_add_u32 s69, s30, 0x80
	s_addc_u32 s35, s31, 0
	s_cmp_eq_u32 s49, s34
	s_cselect_b32 s34, s2, s69
	s_cselect_b32 s35, s3, s35
	s_cselect_b32 s71, s29, s67
	s_cselect_b32 s70, s28, s66
	v_lshl_add_u64 v[230:231], s[30:31], 0, v[136:137]
	s_add_i32 m0, s41, 0xc000
	ds_read_b128 v[196:199], v163
	ds_read_b128 v[200:203], v163 offset:1024
	ds_read_b128 v[204:207], v163 offset:2048
	ds_read_b128 v[208:211], v163 offset:3072
	ds_read_b128 v[212:215], v163 offset:4096
	ds_read_b128 v[216:219], v163 offset:5120
	ds_read_b128 v[222:225], v163 offset:6144
	ds_read_b128 v[226:229], v163 offset:7168
	global_load_lds_dwordx4 v[230:231], off
	v_lshl_add_u64 v[230:231], s[30:31], 0, v[138:139]
	s_add_i32 m0, s41, 0xe000
	s_nop 0
	global_load_lds_dwordx4 v[230:231], off
	s_waitcnt vmcnt(8)
	s_waitcnt lgkmcnt(0)
	s_barrier
	s_setprio 1
	s_waitcnt lgkmcnt(0)
	v_mfma_f32_16x16x32_bf16 v[120:123], v[164:167], v[196:199], v[120:123]
	v_mfma_f32_16x16x32_bf16 v[120:123], v[168:171], v[200:203], v[120:123]
	v_mfma_f32_16x16x32_bf16 v[124:127], v[172:175], v[196:199], v[124:127]
	v_mfma_f32_16x16x32_bf16 v[124:127], v[176:179], v[200:203], v[124:127]
	v_mfma_f32_16x16x32_bf16 v[116:119], v[180:183], v[196:199], v[116:119]
	v_mfma_f32_16x16x32_bf16 v[116:119], v[184:187], v[200:203], v[116:119]
	v_mfma_f32_16x16x32_bf16 v[112:115], v[188:191], v[196:199], v[112:115]
	v_mfma_f32_16x16x32_bf16 v[112:115], v[192:195], v[200:203], v[112:115]
	v_mfma_f32_16x16x32_bf16 v[96:99], v[188:191], v[204:207], v[96:99]
	v_mfma_f32_16x16x32_bf16 v[96:99], v[192:195], v[208:211], v[96:99]
	v_mfma_f32_16x16x32_bf16 v[100:103], v[180:183], v[204:207], v[100:103]
	v_mfma_f32_16x16x32_bf16 v[100:103], v[184:187], v[208:211], v[100:103]
	v_mfma_f32_16x16x32_bf16 v[104:107], v[172:175], v[204:207], v[104:107]
	v_mfma_f32_16x16x32_bf16 v[104:107], v[176:179], v[208:211], v[104:107]
	v_mfma_f32_16x16x32_bf16 v[108:111], v[164:167], v[204:207], v[108:111]
	v_mfma_f32_16x16x32_bf16 v[108:111], v[168:171], v[208:211], v[108:111]
	v_mfma_f32_16x16x32_bf16 v[92:95], v[164:167], v[212:215], v[92:95]
	v_mfma_f32_16x16x32_bf16 v[92:95], v[168:171], v[216:219], v[92:95]
	v_mfma_f32_16x16x32_bf16 v[88:91], v[172:175], v[212:215], v[88:91]
	v_mfma_f32_16x16x32_bf16 v[88:91], v[176:179], v[216:219], v[88:91]
	v_mfma_f32_16x16x32_bf16 v[84:87], v[180:183], v[212:215], v[84:87]
	v_mfma_f32_16x16x32_bf16 v[84:87], v[184:187], v[216:219], v[84:87]
	v_mfma_f32_16x16x32_bf16 v[80:83], v[188:191], v[212:215], v[80:83]
	v_mfma_f32_16x16x32_bf16 v[80:83], v[192:195], v[216:219], v[80:83]
	v_mfma_f32_16x16x32_bf16 v[64:67], v[188:191], v[222:225], v[64:67]
	v_mfma_f32_16x16x32_bf16 v[64:67], v[192:195], v[226:229], v[64:67]
	v_mfma_f32_16x16x32_bf16 v[68:71], v[180:183], v[222:225], v[68:71]
	v_mfma_f32_16x16x32_bf16 v[68:71], v[184:187], v[226:229], v[68:71]
	v_mfma_f32_16x16x32_bf16 v[72:75], v[172:175], v[222:225], v[72:75]
	v_mfma_f32_16x16x32_bf16 v[72:75], v[176:179], v[226:229], v[72:75]
	v_mfma_f32_16x16x32_bf16 v[76:79], v[164:167], v[222:225], v[76:79]
	v_mfma_f32_16x16x32_bf16 v[76:79], v[168:171], v[226:229], v[76:79]
	s_setprio 0
	s_barrier
	s_add_i32 s69, s52, s40
	v_lshl_add_u64 v[230:231], s[70:71], 0, v[130:131]
	s_mov_b32 m0, s69
	ds_read_b128 v[196:199], v163 offset:16384
	ds_read_b128 v[200:203], v163 offset:17408
	ds_read_b128 v[204:207], v163 offset:18432
	ds_read_b128 v[208:211], v163 offset:19456
	ds_read_b128 v[212:215], v163 offset:20480
	ds_read_b128 v[216:219], v163 offset:21504
	ds_read_b128 v[222:225], v163 offset:22528
	ds_read_b128 v[226:229], v163 offset:23552
	global_load_lds_dwordx4 v[230:231], off
	s_add_i32 m0, s69, 0x2000
	v_lshl_add_u64 v[232:233], s[70:71], 0, v[134:135]
	s_add_u32 s70, s70, s6
	s_addc_u32 s71, s71, s7
	s_add_i32 s69, s53, s40
	global_load_lds_dwordx4 v[232:233], off
	v_lshl_add_u64 v[234:235], s[70:71], 0, v[130:131]
	s_mov_b32 m0, s69
	v_lshl_add_u64 v[236:237], s[70:71], 0, v[134:135]
	global_load_lds_dwordx4 v[234:235], off
	s_add_i32 m0, s69, 0x2000
	v_lshl_add_u64 v[238:239], s[34:35], 0, v[128:129]
	global_load_lds_dwordx4 v[236:237], off
	s_mov_b32 m0, s41
	v_lshl_add_u64 v[240:241], s[34:35], 0, v[132:133]
	global_load_lds_dwordx4 v[238:239], off
	s_mov_b32 m0, s42
	s_nop 0
	global_load_lds_dwordx4 v[240:241], off
	s_waitcnt vmcnt(8)
	s_waitcnt lgkmcnt(0)
	s_barrier
	s_setprio 1
	s_waitcnt lgkmcnt(0)
	v_mfma_f32_16x16x32_bf16 v[60:63], v[164:167], v[196:199], v[60:63]
	v_mfma_f32_16x16x32_bf16 v[60:63], v[168:171], v[200:203], v[60:63]
	v_mfma_f32_16x16x32_bf16 v[56:59], v[172:175], v[196:199], v[56:59]
	v_mfma_f32_16x16x32_bf16 v[56:59], v[176:179], v[200:203], v[56:59]
	v_mfma_f32_16x16x32_bf16 v[52:55], v[180:183], v[196:199], v[52:55]
	v_mfma_f32_16x16x32_bf16 v[52:55], v[184:187], v[200:203], v[52:55]
	v_mfma_f32_16x16x32_bf16 v[48:51], v[188:191], v[196:199], v[48:51]
	v_mfma_f32_16x16x32_bf16 v[48:51], v[192:195], v[200:203], v[48:51]
	v_mfma_f32_16x16x32_bf16 v[32:35], v[188:191], v[204:207], v[32:35]
	v_mfma_f32_16x16x32_bf16 v[32:35], v[192:195], v[208:211], v[32:35]
	v_mfma_f32_16x16x32_bf16 v[36:39], v[180:183], v[204:207], v[36:39]
	v_mfma_f32_16x16x32_bf16 v[36:39], v[184:187], v[208:211], v[36:39]
	v_mfma_f32_16x16x32_bf16 v[40:43], v[172:175], v[204:207], v[40:43]
	v_mfma_f32_16x16x32_bf16 v[40:43], v[176:179], v[208:211], v[40:43]
	v_mfma_f32_16x16x32_bf16 v[44:47], v[164:167], v[204:207], v[44:47]
	v_mfma_f32_16x16x32_bf16 v[44:47], v[168:171], v[208:211], v[44:47]
	v_mfma_f32_16x16x32_bf16 v[28:31], v[164:167], v[212:215], v[28:31]
	v_mfma_f32_16x16x32_bf16 v[28:31], v[168:171], v[216:219], v[28:31]
	v_mfma_f32_16x16x32_bf16 v[24:27], v[172:175], v[212:215], v[24:27]
	v_mfma_f32_16x16x32_bf16 v[24:27], v[176:179], v[216:219], v[24:27]
	v_mfma_f32_16x16x32_bf16 v[20:23], v[180:183], v[212:215], v[20:23]
	v_mfma_f32_16x16x32_bf16 v[20:23], v[184:187], v[216:219], v[20:23]
	v_mfma_f32_16x16x32_bf16 v[16:19], v[188:191], v[212:215], v[16:19]
	v_mfma_f32_16x16x32_bf16 v[16:19], v[192:195], v[216:219], v[16:19]
	v_mfma_f32_16x16x32_bf16 v[0:3], v[188:191], v[222:225], v[0:3]
	v_mfma_f32_16x16x32_bf16 v[0:3], v[192:195], v[226:229], v[0:3]
	v_mfma_f32_16x16x32_bf16 v[4:7], v[180:183], v[222:225], v[4:7]
	v_mfma_f32_16x16x32_bf16 v[4:7], v[184:187], v[226:229], v[4:7]
	v_mfma_f32_16x16x32_bf16 v[8:11], v[172:175], v[222:225], v[8:11]
	v_mfma_f32_16x16x32_bf16 v[8:11], v[176:179], v[226:229], v[8:11]
	v_mfma_f32_16x16x32_bf16 v[12:15], v[164:167], v[222:225], v[12:15]
	v_mfma_f32_16x16x32_bf16 v[12:15], v[168:171], v[226:229], v[12:15]
	s_setprio 0
	s_barrier
	s_add_i32 s69, 0, 0x18000
	s_add_i32 s70, 0, 0x1c000
	v_add_u32_e32 v176, s69, v154
	v_add_u32_e32 v192, s70, v154
	ds_read_b128 v[164:167], v176
	ds_read_b128 v[168:171], v176 offset:1024
	ds_read_b128 v[172:175], v176 offset:2048
	ds_read_b128 v[176:179], v176 offset:3072
	ds_read_b128 v[180:183], v192
	ds_read_b128 v[184:187], v192 offset:1024
	ds_read_b128 v[188:191], v192 offset:2048
	ds_read_b128 v[192:195], v192 offset:3072
	s_add_u32 s34, s34, s6
	s_addc_u32 s35, s35, s7
	s_mov_b32 m0, s43
	v_lshl_add_u64 v[242:243], s[34:35], 0, v[128:129]
	ds_read_b128 v[196:199], v163 offset:32768
	ds_read_b128 v[200:203], v163 offset:33792
	ds_read_b128 v[204:207], v163 offset:34816
	ds_read_b128 v[208:211], v163 offset:35840
	ds_read_b128 v[212:215], v163 offset:36864
	ds_read_b128 v[216:219], v163 offset:37888
	ds_read_b128 v[222:225], v163 offset:38912
	ds_read_b128 v[226:229], v163 offset:39936
	global_load_lds_dwordx4 v[242:243], off
	v_lshl_add_u64 v[242:243], s[34:35], 0, v[132:133]
	s_mov_b32 m0, s44
	s_nop 0
	global_load_lds_dwordx4 v[242:243], off
	s_waitcnt vmcnt(8)
	s_waitcnt lgkmcnt(0)
	s_barrier
	s_setprio 1
	s_waitcnt lgkmcnt(0)
	v_mfma_f32_16x16x32_bf16 v[120:123], v[164:167], v[196:199], v[120:123]
	v_mfma_f32_16x16x32_bf16 v[120:123], v[168:171], v[200:203], v[120:123]
	v_mfma_f32_16x16x32_bf16 v[124:127], v[172:175], v[196:199], v[124:127]
	v_mfma_f32_16x16x32_bf16 v[124:127], v[176:179], v[200:203], v[124:127]
	v_mfma_f32_16x16x32_bf16 v[116:119], v[180:183], v[196:199], v[116:119]
	v_mfma_f32_16x16x32_bf16 v[116:119], v[184:187], v[200:203], v[116:119]
	v_mfma_f32_16x16x32_bf16 v[112:115], v[188:191], v[196:199], v[112:115]
	v_mfma_f32_16x16x32_bf16 v[112:115], v[192:195], v[200:203], v[112:115]
	v_mfma_f32_16x16x32_bf16 v[96:99], v[188:191], v[204:207], v[96:99]
	v_mfma_f32_16x16x32_bf16 v[96:99], v[192:195], v[208:211], v[96:99]
	v_mfma_f32_16x16x32_bf16 v[100:103], v[180:183], v[204:207], v[100:103]
	v_mfma_f32_16x16x32_bf16 v[100:103], v[184:187], v[208:211], v[100:103]
	v_mfma_f32_16x16x32_bf16 v[104:107], v[172:175], v[204:207], v[104:107]
	v_mfma_f32_16x16x32_bf16 v[104:107], v[176:179], v[208:211], v[104:107]
	v_mfma_f32_16x16x32_bf16 v[108:111], v[164:167], v[204:207], v[108:111]
	v_mfma_f32_16x16x32_bf16 v[108:111], v[168:171], v[208:211], v[108:111]
	v_mfma_f32_16x16x32_bf16 v[92:95], v[164:167], v[212:215], v[92:95]
	v_mfma_f32_16x16x32_bf16 v[92:95], v[168:171], v[216:219], v[92:95]
	v_mfma_f32_16x16x32_bf16 v[88:91], v[172:175], v[212:215], v[88:91]
	v_mfma_f32_16x16x32_bf16 v[88:91], v[176:179], v[216:219], v[88:91]
	v_mfma_f32_16x16x32_bf16 v[84:87], v[180:183], v[212:215], v[84:87]
	v_mfma_f32_16x16x32_bf16 v[84:87], v[184:187], v[216:219], v[84:87]
	v_mfma_f32_16x16x32_bf16 v[80:83], v[188:191], v[212:215], v[80:83]
	v_mfma_f32_16x16x32_bf16 v[80:83], v[192:195], v[216:219], v[80:83]
	v_mfma_f32_16x16x32_bf16 v[64:67], v[188:191], v[222:225], v[64:67]
	v_mfma_f32_16x16x32_bf16 v[64:67], v[192:195], v[226:229], v[64:67]
	v_mfma_f32_16x16x32_bf16 v[68:71], v[180:183], v[222:225], v[68:71]
	v_mfma_f32_16x16x32_bf16 v[68:71], v[184:187], v[226:229], v[68:71]
	v_mfma_f32_16x16x32_bf16 v[72:75], v[172:175], v[222:225], v[72:75]
	v_mfma_f32_16x16x32_bf16 v[72:75], v[176:179], v[226:229], v[72:75]
	v_mfma_f32_16x16x32_bf16 v[76:79], v[164:167], v[222:225], v[76:79]
	v_mfma_f32_16x16x32_bf16 v[76:79], v[168:171], v[226:229], v[76:79]
	s_setprio 0
	s_barrier
	s_add_i32 s34, s69, s40
	v_lshl_add_u64 v[230:231], v[230:231], 0, s[12:13]
	s_mov_b32 m0, s34
	ds_read_b128 v[196:199], v163 offset:49152
	ds_read_b128 v[200:203], v163 offset:50176
	ds_read_b128 v[204:207], v163 offset:51200
	ds_read_b128 v[208:211], v163 offset:52224
	ds_read_b128 v[212:215], v163 offset:53248
	ds_read_b128 v[216:219], v163 offset:54272
	ds_read_b128 v[222:225], v163 offset:55296
	ds_read_b128 v[226:229], v163 offset:56320
	global_load_lds_dwordx4 v[230:231], off
	v_lshl_add_u64 v[230:231], v[232:233], 0, s[12:13]
	s_add_i32 m0, s34, 0x2000
	s_add_i32 s34, s70, s40
	global_load_lds_dwordx4 v[230:231], off
	v_lshl_add_u64 v[230:231], v[234:235], 0, s[12:13]
	s_mov_b32 m0, s34
	s_nop 0
	global_load_lds_dwordx4 v[230:231], off
	v_lshl_add_u64 v[230:231], v[236:237], 0, s[12:13]
	s_add_i32 m0, s34, 0x2000
	s_nop 0
	global_load_lds_dwordx4 v[230:231], off
	v_lshl_add_u64 v[230:231], v[238:239], 0, s[12:13]
	s_mov_b32 m0, s46
	s_nop 0
	global_load_lds_dwordx4 v[230:231], off
	v_lshl_add_u64 v[230:231], v[240:241], 0, s[12:13]
	s_mov_b32 m0, s47
	s_nop 0
	global_load_lds_dwordx4 v[230:231], off
	s_waitcnt vmcnt(8)
	s_waitcnt lgkmcnt(0)
	s_barrier
	s_setprio 1
	s_waitcnt lgkmcnt(0)
	v_mfma_f32_16x16x32_bf16 v[60:63], v[164:167], v[196:199], v[60:63]
	v_mfma_f32_16x16x32_bf16 v[60:63], v[168:171], v[200:203], v[60:63]
	v_mfma_f32_16x16x32_bf16 v[56:59], v[172:175], v[196:199], v[56:59]
	v_mfma_f32_16x16x32_bf16 v[56:59], v[176:179], v[200:203], v[56:59]
	v_mfma_f32_16x16x32_bf16 v[52:55], v[180:183], v[196:199], v[52:55]
	v_mfma_f32_16x16x32_bf16 v[52:55], v[184:187], v[200:203], v[52:55]
	v_mfma_f32_16x16x32_bf16 v[48:51], v[188:191], v[196:199], v[48:51]
	v_mfma_f32_16x16x32_bf16 v[48:51], v[192:195], v[200:203], v[48:51]
	v_mfma_f32_16x16x32_bf16 v[32:35], v[188:191], v[204:207], v[32:35]
	v_mfma_f32_16x16x32_bf16 v[32:35], v[192:195], v[208:211], v[32:35]
	v_mfma_f32_16x16x32_bf16 v[36:39], v[180:183], v[204:207], v[36:39]
	v_mfma_f32_16x16x32_bf16 v[36:39], v[184:187], v[208:211], v[36:39]
	v_mfma_f32_16x16x32_bf16 v[40:43], v[172:175], v[204:207], v[40:43]
	v_mfma_f32_16x16x32_bf16 v[40:43], v[176:179], v[208:211], v[40:43]
	v_mfma_f32_16x16x32_bf16 v[44:47], v[164:167], v[204:207], v[44:47]
	v_mfma_f32_16x16x32_bf16 v[44:47], v[168:171], v[208:211], v[44:47]
	v_mfma_f32_16x16x32_bf16 v[28:31], v[164:167], v[212:215], v[28:31]
	v_mfma_f32_16x16x32_bf16 v[28:31], v[168:171], v[216:219], v[28:31]
	v_mfma_f32_16x16x32_bf16 v[24:27], v[172:175], v[212:215], v[24:27]
	v_mfma_f32_16x16x32_bf16 v[24:27], v[176:179], v[216:219], v[24:27]
	v_mfma_f32_16x16x32_bf16 v[20:23], v[180:183], v[212:215], v[20:23]
	v_mfma_f32_16x16x32_bf16 v[20:23], v[184:187], v[216:219], v[20:23]
	v_mfma_f32_16x16x32_bf16 v[16:19], v[188:191], v[212:215], v[16:19]
	v_mfma_f32_16x16x32_bf16 v[16:19], v[192:195], v[216:219], v[16:19]
	v_mfma_f32_16x16x32_bf16 v[0:3], v[188:191], v[222:225], v[0:3]
	v_mfma_f32_16x16x32_bf16 v[0:3], v[192:195], v[226:229], v[0:3]
	v_mfma_f32_16x16x32_bf16 v[4:7], v[180:183], v[222:225], v[4:7]
	v_mfma_f32_16x16x32_bf16 v[4:7], v[184:187], v[226:229], v[4:7]
	v_mfma_f32_16x16x32_bf16 v[8:11], v[172:175], v[222:225], v[8:11]
	v_mfma_f32_16x16x32_bf16 v[8:11], v[176:179], v[226:229], v[8:11]
	v_mfma_f32_16x16x32_bf16 v[12:15], v[164:167], v[222:225], v[12:15]
	v_mfma_f32_16x16x32_bf16 v[12:15], v[168:171], v[226:229], v[12:15]
	s_setprio 0
	s_barrier
	s_add_u32 s30, s30, 0x100
	s_addc_u32 s31, s31, 0
	s_add_u32 s66, s66, 0x100
	s_addc_u32 s67, s67, 0
	s_cmp_ge_i32 s68, s48
	s_mov_b32 s34, s68
	s_cbranch_scc0 .LBB0_949

.LBB0_970:
	ds_read_b128 v[170:173], v139
	ds_read_b128 v[174:177], v139 offset:1024
	ds_read_b128 v[178:181], v139 offset:2048
	ds_read_b128 v[182:185], v139 offset:3072
	ds_read_b128 v[186:189], v165
	ds_read_b128 v[190:193], v165 offset:1024
	ds_read_b128 v[194:197], v165 offset:2048
	ds_read_b128 v[198:201], v165 offset:3072
	s_add_i32 s8, s4, 2
	s_add_u32 s9, s2, 0x80
	s_addc_u32 s5, s3, 0
	s_cmp_eq_u32 s52, s4
	s_cselect_b32 s4, s30, s9
	s_cselect_b32 s5, s31, s5
	s_cselect_b32 s11, s35, s7
	s_cselect_b32 s10, s34, s6
	v_lshl_add_u64 v[218:219], s[2:3], 0, v[156:157]
	s_add_i32 m0, s42, 0xc000
	ds_read_b128 v[202:205], v166
	ds_read_b128 v[206:209], v166 offset:1024
	ds_read_b128 v[210:213], v166 offset:2048
	ds_read_b128 v[214:217], v166 offset:3072
	ds_read_b128 v[222:225], v166 offset:4096
	ds_read_b128 v[226:229], v166 offset:5120
	ds_read_b128 v[230:233], v166 offset:6144
	ds_read_b128 v[234:237], v166 offset:7168
	global_load_lds_dwordx4 v[218:219], off
	v_lshl_add_u64 v[218:219], s[2:3], 0, v[158:159]
	s_add_i32 m0, s42, 0xe000
	s_nop 0
	global_load_lds_dwordx4 v[218:219], off
	s_waitcnt vmcnt(8)
	s_waitcnt lgkmcnt(0)
	s_barrier
	s_setprio 1
	s_waitcnt lgkmcnt(0)
	v_mfma_f32_16x16x32_bf16 v[124:127], v[170:173], v[202:205], v[124:127]
	v_mfma_f32_16x16x32_bf16 v[124:127], v[174:177], v[206:209], v[124:127]
	v_mfma_f32_16x16x32_bf16 v[120:123], v[178:181], v[202:205], v[120:123]
	v_mfma_f32_16x16x32_bf16 v[120:123], v[182:185], v[206:209], v[120:123]
	v_mfma_f32_16x16x32_bf16 v[116:119], v[186:189], v[202:205], v[116:119]
	v_mfma_f32_16x16x32_bf16 v[116:119], v[190:193], v[206:209], v[116:119]
	v_mfma_f32_16x16x32_bf16 v[112:115], v[194:197], v[202:205], v[112:115]
	v_mfma_f32_16x16x32_bf16 v[112:115], v[198:201], v[206:209], v[112:115]
	v_mfma_f32_16x16x32_bf16 v[96:99], v[194:197], v[210:213], v[96:99]
	v_mfma_f32_16x16x32_bf16 v[96:99], v[198:201], v[214:217], v[96:99]
	v_mfma_f32_16x16x32_bf16 v[100:103], v[186:189], v[210:213], v[100:103]
	v_mfma_f32_16x16x32_bf16 v[100:103], v[190:193], v[214:217], v[100:103]
	v_mfma_f32_16x16x32_bf16 v[104:107], v[178:181], v[210:213], v[104:107]
	v_mfma_f32_16x16x32_bf16 v[104:107], v[182:185], v[214:217], v[104:107]
	v_mfma_f32_16x16x32_bf16 v[108:111], v[170:173], v[210:213], v[108:111]
	v_mfma_f32_16x16x32_bf16 v[108:111], v[174:177], v[214:217], v[108:111]
	v_mfma_f32_16x16x32_bf16 v[92:95], v[170:173], v[222:225], v[92:95]
	v_mfma_f32_16x16x32_bf16 v[92:95], v[174:177], v[226:229], v[92:95]
	v_mfma_f32_16x16x32_bf16 v[88:91], v[178:181], v[222:225], v[88:91]
	v_mfma_f32_16x16x32_bf16 v[88:91], v[182:185], v[226:229], v[88:91]
	v_mfma_f32_16x16x32_bf16 v[84:87], v[186:189], v[222:225], v[84:87]
	v_mfma_f32_16x16x32_bf16 v[84:87], v[190:193], v[226:229], v[84:87]
	v_mfma_f32_16x16x32_bf16 v[80:83], v[194:197], v[222:225], v[80:83]
	v_mfma_f32_16x16x32_bf16 v[80:83], v[198:201], v[226:229], v[80:83]
	v_mfma_f32_16x16x32_bf16 v[64:67], v[194:197], v[230:233], v[64:67]
	v_mfma_f32_16x16x32_bf16 v[64:67], v[198:201], v[234:237], v[64:67]
	v_mfma_f32_16x16x32_bf16 v[68:71], v[186:189], v[230:233], v[68:71]
	v_mfma_f32_16x16x32_bf16 v[68:71], v[190:193], v[234:237], v[68:71]
	v_mfma_f32_16x16x32_bf16 v[72:75], v[178:181], v[230:233], v[72:75]
	v_mfma_f32_16x16x32_bf16 v[72:75], v[182:185], v[234:237], v[72:75]
	v_mfma_f32_16x16x32_bf16 v[76:79], v[170:173], v[230:233], v[76:79]
	v_mfma_f32_16x16x32_bf16 v[76:79], v[174:177], v[234:237], v[76:79]
	s_setprio 0
	s_barrier
	s_add_i32 s9, s60, s39
	v_lshl_add_u64 v[218:219], s[10:11], 0, v[132:133]
	s_mov_b32 m0, s9
	ds_read_b128 v[202:205], v166 offset:16384
	ds_read_b128 v[206:209], v166 offset:17408
	ds_read_b128 v[210:213], v166 offset:18432
	ds_read_b128 v[214:217], v166 offset:19456
	ds_read_b128 v[222:225], v166 offset:20480
	ds_read_b128 v[226:229], v166 offset:21504
	ds_read_b128 v[230:233], v166 offset:22528
	ds_read_b128 v[234:237], v166 offset:23552
	global_load_lds_dwordx4 v[218:219], off
	s_add_i32 m0, s9, 0x2000
	v_lshl_add_u64 v[238:239], s[10:11], 0, v[128:129]
	s_add_u32 s10, s10, s18
	s_addc_u32 s11, s11, s19
	s_add_i32 s9, s61, s39
	global_load_lds_dwordx4 v[238:239], off
	v_lshl_add_u64 v[240:241], s[10:11], 0, v[132:133]
	s_mov_b32 m0, s9
	v_lshl_add_u64 v[242:243], s[10:11], 0, v[128:129]
	global_load_lds_dwordx4 v[240:241], off
	s_add_i32 m0, s9, 0x2000
	v_lshl_add_u64 v[244:245], s[4:5], 0, v[134:135]
	global_load_lds_dwordx4 v[242:243], off
	s_mov_b32 m0, s42
	v_lshl_add_u64 v[246:247], s[4:5], 0, v[130:131]
	global_load_lds_dwordx4 v[244:245], off
	s_mov_b32 m0, s43
	s_nop 0
	global_load_lds_dwordx4 v[246:247], off
	s_waitcnt vmcnt(8)
	s_waitcnt lgkmcnt(0)
	s_barrier
	s_setprio 1
	s_waitcnt lgkmcnt(0)
	v_mfma_f32_16x16x32_bf16 v[60:63], v[170:173], v[202:205], v[60:63]
	v_mfma_f32_16x16x32_bf16 v[60:63], v[174:177], v[206:209], v[60:63]
	v_mfma_f32_16x16x32_bf16 v[56:59], v[178:181], v[202:205], v[56:59]
	v_mfma_f32_16x16x32_bf16 v[56:59], v[182:185], v[206:209], v[56:59]
	v_mfma_f32_16x16x32_bf16 v[52:55], v[186:189], v[202:205], v[52:55]
	v_mfma_f32_16x16x32_bf16 v[52:55], v[190:193], v[206:209], v[52:55]
	v_mfma_f32_16x16x32_bf16 v[48:51], v[194:197], v[202:205], v[48:51]
	v_mfma_f32_16x16x32_bf16 v[48:51], v[198:201], v[206:209], v[48:51]
	v_mfma_f32_16x16x32_bf16 v[32:35], v[194:197], v[210:213], v[32:35]
	v_mfma_f32_16x16x32_bf16 v[32:35], v[198:201], v[214:217], v[32:35]
	v_mfma_f32_16x16x32_bf16 v[36:39], v[186:189], v[210:213], v[36:39]
	v_mfma_f32_16x16x32_bf16 v[36:39], v[190:193], v[214:217], v[36:39]
	v_mfma_f32_16x16x32_bf16 v[40:43], v[178:181], v[210:213], v[40:43]
	v_mfma_f32_16x16x32_bf16 v[40:43], v[182:185], v[214:217], v[40:43]
	v_mfma_f32_16x16x32_bf16 v[44:47], v[170:173], v[210:213], v[44:47]
	v_mfma_f32_16x16x32_bf16 v[44:47], v[174:177], v[214:217], v[44:47]
	v_mfma_f32_16x16x32_bf16 v[28:31], v[170:173], v[222:225], v[28:31]
	v_mfma_f32_16x16x32_bf16 v[28:31], v[174:177], v[226:229], v[28:31]
	v_mfma_f32_16x16x32_bf16 v[24:27], v[178:181], v[222:225], v[24:27]
	v_mfma_f32_16x16x32_bf16 v[24:27], v[182:185], v[226:229], v[24:27]
	v_mfma_f32_16x16x32_bf16 v[20:23], v[186:189], v[222:225], v[20:23]
	v_mfma_f32_16x16x32_bf16 v[20:23], v[190:193], v[226:229], v[20:23]
	v_mfma_f32_16x16x32_bf16 v[16:19], v[194:197], v[222:225], v[16:19]
	v_mfma_f32_16x16x32_bf16 v[16:19], v[198:201], v[226:229], v[16:19]
	v_mfma_f32_16x16x32_bf16 v[0:3], v[194:197], v[230:233], v[0:3]
	v_mfma_f32_16x16x32_bf16 v[0:3], v[198:201], v[234:237], v[0:3]
	v_mfma_f32_16x16x32_bf16 v[4:7], v[186:189], v[230:233], v[4:7]
	v_mfma_f32_16x16x32_bf16 v[4:7], v[190:193], v[234:237], v[4:7]
	v_mfma_f32_16x16x32_bf16 v[8:11], v[178:181], v[230:233], v[8:11]
	v_mfma_f32_16x16x32_bf16 v[8:11], v[182:185], v[234:237], v[8:11]
	v_mfma_f32_16x16x32_bf16 v[12:15], v[170:173], v[230:233], v[12:15]
	v_mfma_f32_16x16x32_bf16 v[12:15], v[174:177], v[234:237], v[12:15]
	s_setprio 0
	s_barrier
	s_add_i32 s9, 0, 0x18000
	v_add_u32_e32 v169, s9, v164
	s_add_i32 s10, 0, 0x1c000
	ds_read_b128 v[170:173], v169
	ds_read_b128 v[174:177], v169 offset:1024
	ds_read_b128 v[178:181], v169 offset:2048
	ds_read_b128 v[182:185], v169 offset:3072
	v_add_u32_e32 v169, s10, v164
	ds_read_b128 v[186:189], v169
	ds_read_b128 v[190:193], v169 offset:1024
	ds_read_b128 v[194:197], v169 offset:2048
	ds_read_b128 v[198:201], v169 offset:3072
	s_add_u32 s4, s4, s18
	s_addc_u32 s5, s5, s19
	s_mov_b32 m0, s44
	v_lshl_add_u64 v[248:249], s[4:5], 0, v[134:135]
	ds_read_b128 v[202:205], v166 offset:32768
	ds_read_b128 v[206:209], v166 offset:33792
	ds_read_b128 v[210:213], v166 offset:34816
	ds_read_b128 v[214:217], v166 offset:35840
	ds_read_b128 v[222:225], v166 offset:36864
	ds_read_b128 v[226:229], v166 offset:37888
	ds_read_b128 v[230:233], v166 offset:38912
	ds_read_b128 v[234:237], v166 offset:39936
	global_load_lds_dwordx4 v[248:249], off
	v_lshl_add_u64 v[248:249], s[4:5], 0, v[130:131]
	s_mov_b32 m0, s45
	s_nop 0
	global_load_lds_dwordx4 v[248:249], off
	s_waitcnt vmcnt(8)
	s_waitcnt lgkmcnt(0)
	s_barrier
	s_setprio 1
	s_waitcnt lgkmcnt(0)
	v_mfma_f32_16x16x32_bf16 v[124:127], v[170:173], v[202:205], v[124:127]
	v_mfma_f32_16x16x32_bf16 v[124:127], v[174:177], v[206:209], v[124:127]
	v_mfma_f32_16x16x32_bf16 v[120:123], v[178:181], v[202:205], v[120:123]
	v_mfma_f32_16x16x32_bf16 v[120:123], v[182:185], v[206:209], v[120:123]
	v_mfma_f32_16x16x32_bf16 v[116:119], v[186:189], v[202:205], v[116:119]
	v_mfma_f32_16x16x32_bf16 v[116:119], v[190:193], v[206:209], v[116:119]
	v_mfma_f32_16x16x32_bf16 v[112:115], v[194:197], v[202:205], v[112:115]
	v_mfma_f32_16x16x32_bf16 v[112:115], v[198:201], v[206:209], v[112:115]
	v_mfma_f32_16x16x32_bf16 v[96:99], v[194:197], v[210:213], v[96:99]
	v_mfma_f32_16x16x32_bf16 v[96:99], v[198:201], v[214:217], v[96:99]
	v_mfma_f32_16x16x32_bf16 v[100:103], v[186:189], v[210:213], v[100:103]
	v_mfma_f32_16x16x32_bf16 v[100:103], v[190:193], v[214:217], v[100:103]
	v_mfma_f32_16x16x32_bf16 v[104:107], v[178:181], v[210:213], v[104:107]
	v_mfma_f32_16x16x32_bf16 v[104:107], v[182:185], v[214:217], v[104:107]
	v_mfma_f32_16x16x32_bf16 v[108:111], v[170:173], v[210:213], v[108:111]
	v_mfma_f32_16x16x32_bf16 v[108:111], v[174:177], v[214:217], v[108:111]
	v_mfma_f32_16x16x32_bf16 v[92:95], v[170:173], v[222:225], v[92:95]
	v_mfma_f32_16x16x32_bf16 v[92:95], v[174:177], v[226:229], v[92:95]
	v_mfma_f32_16x16x32_bf16 v[88:91], v[178:181], v[222:225], v[88:91]
	v_mfma_f32_16x16x32_bf16 v[88:91], v[182:185], v[226:229], v[88:91]
	v_mfma_f32_16x16x32_bf16 v[84:87], v[186:189], v[222:225], v[84:87]
	v_mfma_f32_16x16x32_bf16 v[84:87], v[190:193], v[226:229], v[84:87]
	v_mfma_f32_16x16x32_bf16 v[80:83], v[194:197], v[222:225], v[80:83]
	v_mfma_f32_16x16x32_bf16 v[80:83], v[198:201], v[226:229], v[80:83]
	v_mfma_f32_16x16x32_bf16 v[64:67], v[194:197], v[230:233], v[64:67]
	v_mfma_f32_16x16x32_bf16 v[64:67], v[198:201], v[234:237], v[64:67]
	v_mfma_f32_16x16x32_bf16 v[68:71], v[186:189], v[230:233], v[68:71]
	v_mfma_f32_16x16x32_bf16 v[68:71], v[190:193], v[234:237], v[68:71]
	v_mfma_f32_16x16x32_bf16 v[72:75], v[178:181], v[230:233], v[72:75]
	v_mfma_f32_16x16x32_bf16 v[72:75], v[182:185], v[234:237], v[72:75]
	v_mfma_f32_16x16x32_bf16 v[76:79], v[170:173], v[230:233], v[76:79]
	v_mfma_f32_16x16x32_bf16 v[76:79], v[174:177], v[234:237], v[76:79]
	s_setprio 0
	s_barrier
	s_add_i32 s4, s9, s39
	v_lshl_add_u64 v[218:219], v[218:219], 0, s[24:25]
	s_mov_b32 m0, s4
	ds_read_b128 v[202:205], v166 offset:49152
	ds_read_b128 v[206:209], v166 offset:50176
	ds_read_b128 v[210:213], v166 offset:51200
	ds_read_b128 v[214:217], v166 offset:52224
	ds_read_b128 v[222:225], v166 offset:53248
	ds_read_b128 v[226:229], v166 offset:54272
	ds_read_b128 v[230:233], v166 offset:55296
	ds_read_b128 v[234:237], v166 offset:56320
	global_load_lds_dwordx4 v[218:219], off
	v_lshl_add_u64 v[218:219], v[238:239], 0, s[24:25]
	s_add_i32 m0, s4, 0x2000
	s_add_i32 s4, s10, s39
	global_load_lds_dwordx4 v[218:219], off
	v_lshl_add_u64 v[218:219], v[240:241], 0, s[24:25]
	s_mov_b32 m0, s4
	s_nop 0
	global_load_lds_dwordx4 v[218:219], off
	v_lshl_add_u64 v[218:219], v[242:243], 0, s[24:25]
	s_add_i32 m0, s4, 0x2000
	s_nop 0
	global_load_lds_dwordx4 v[218:219], off
	v_lshl_add_u64 v[218:219], v[244:245], 0, s[24:25]
	s_mov_b32 m0, s49
	s_nop 0
	global_load_lds_dwordx4 v[218:219], off
	v_lshl_add_u64 v[218:219], v[246:247], 0, s[24:25]
	s_mov_b32 m0, s50
	s_nop 0
	global_load_lds_dwordx4 v[218:219], off
	s_waitcnt vmcnt(8)
	s_waitcnt lgkmcnt(0)
	s_barrier
	s_setprio 1
	s_waitcnt lgkmcnt(0)
	v_mfma_f32_16x16x32_bf16 v[60:63], v[170:173], v[202:205], v[60:63]
	v_mfma_f32_16x16x32_bf16 v[60:63], v[174:177], v[206:209], v[60:63]
	v_mfma_f32_16x16x32_bf16 v[56:59], v[178:181], v[202:205], v[56:59]
	v_mfma_f32_16x16x32_bf16 v[56:59], v[182:185], v[206:209], v[56:59]
	v_mfma_f32_16x16x32_bf16 v[52:55], v[186:189], v[202:205], v[52:55]
	v_mfma_f32_16x16x32_bf16 v[52:55], v[190:193], v[206:209], v[52:55]
	v_mfma_f32_16x16x32_bf16 v[48:51], v[194:197], v[202:205], v[48:51]
	v_mfma_f32_16x16x32_bf16 v[48:51], v[198:201], v[206:209], v[48:51]
	v_mfma_f32_16x16x32_bf16 v[32:35], v[194:197], v[210:213], v[32:35]
	v_mfma_f32_16x16x32_bf16 v[32:35], v[198:201], v[214:217], v[32:35]
	v_mfma_f32_16x16x32_bf16 v[36:39], v[186:189], v[210:213], v[36:39]
	v_mfma_f32_16x16x32_bf16 v[36:39], v[190:193], v[214:217], v[36:39]
	v_mfma_f32_16x16x32_bf16 v[40:43], v[178:181], v[210:213], v[40:43]
	v_mfma_f32_16x16x32_bf16 v[40:43], v[182:185], v[214:217], v[40:43]
	v_mfma_f32_16x16x32_bf16 v[44:47], v[170:173], v[210:213], v[44:47]
	v_mfma_f32_16x16x32_bf16 v[44:47], v[174:177], v[214:217], v[44:47]
	v_mfma_f32_16x16x32_bf16 v[28:31], v[170:173], v[222:225], v[28:31]
	v_mfma_f32_16x16x32_bf16 v[28:31], v[174:177], v[226:229], v[28:31]
	v_mfma_f32_16x16x32_bf16 v[24:27], v[178:181], v[222:225], v[24:27]
	v_mfma_f32_16x16x32_bf16 v[24:27], v[182:185], v[226:229], v[24:27]
	v_mfma_f32_16x16x32_bf16 v[20:23], v[186:189], v[222:225], v[20:23]
	v_mfma_f32_16x16x32_bf16 v[20:23], v[190:193], v[226:229], v[20:23]
	v_mfma_f32_16x16x32_bf16 v[16:19], v[194:197], v[222:225], v[16:19]
	v_mfma_f32_16x16x32_bf16 v[16:19], v[198:201], v[226:229], v[16:19]
	v_mfma_f32_16x16x32_bf16 v[0:3], v[194:197], v[230:233], v[0:3]
	v_mfma_f32_16x16x32_bf16 v[0:3], v[198:201], v[234:237], v[0:3]
	v_mfma_f32_16x16x32_bf16 v[4:7], v[186:189], v[230:233], v[4:7]
	v_mfma_f32_16x16x32_bf16 v[4:7], v[190:193], v[234:237], v[4:7]
	v_mfma_f32_16x16x32_bf16 v[8:11], v[178:181], v[230:233], v[8:11]
	v_mfma_f32_16x16x32_bf16 v[8:11], v[182:185], v[234:237], v[8:11]
	v_mfma_f32_16x16x32_bf16 v[12:15], v[170:173], v[230:233], v[12:15]
	v_mfma_f32_16x16x32_bf16 v[12:15], v[174:177], v[234:237], v[12:15]
	s_setprio 0
	s_barrier
	s_add_u32 s2, s2, 0x100
	s_addc_u32 s3, s3, 0
	s_add_u32 s6, s6, 0x100
	s_addc_u32 s7, s7, 0
	s_cmp_ge_i32 s8, s51
	s_mov_b32 s4, s8
	s_cbranch_scc0 .LBB0_970

.LBB0_1056:
	ds_read_b128 v[140:143], v222
	ds_read_b128 v[144:147], v222 offset:1024
	ds_read_b128 v[148:151], v222 offset:2048
	ds_read_b128 v[152:155], v222 offset:3072
	ds_read_b128 v[156:159], v223
	ds_read_b128 v[160:163], v223 offset:1024
	ds_read_b128 v[164:167], v223 offset:2048
	ds_read_b128 v[168:171], v223 offset:3072
	s_add_i32 s62, s26, 2
	s_add_u32 s27, s24, 0x4000
	s_addc_u32 s28, s25, 0
	s_cmp_eq_u32 s46, s26
	s_cselect_b32 s30, s0, s27
	s_cselect_b32 s31, s1, s28
	s_cselect_b32 s28, s22, s60
	s_cselect_b32 s29, s23, s61
	s_add_u32 s26, s30, 0x8000
	s_addc_u32 s27, s31, 0
	v_lshl_add_u64 v[204:205], s[24:25], 0, v[132:133]
	s_add_i32 m0, s38, 0xc000
	ds_read_b128 v[172:175], v224
	ds_read_b128 v[176:179], v224 offset:1024
	ds_read_b128 v[180:183], v224 offset:2048
	ds_read_b128 v[184:187], v224 offset:3072
	ds_read_b128 v[188:191], v224 offset:4096
	ds_read_b128 v[192:195], v224 offset:5120
	ds_read_b128 v[196:199], v224 offset:6144
	ds_read_b128 v[200:203], v224 offset:7168
	global_load_lds_dwordx4 v[204:205], off
	v_lshl_add_u64 v[204:205], s[24:25], 0, v[134:135]
	s_add_i32 m0, s38, 0xe000
	s_nop 0
	global_load_lds_dwordx4 v[204:205], off
	s_waitcnt vmcnt(8)
	s_waitcnt lgkmcnt(0)
	s_barrier
	s_setprio 1
	s_waitcnt lgkmcnt(0)
	v_mfma_f32_16x16x32_bf16 v[124:127], v[140:143], v[172:175], v[124:127]
	v_mfma_f32_16x16x32_bf16 v[124:127], v[144:147], v[176:179], v[124:127]
	v_mfma_f32_16x16x32_bf16 v[120:123], v[148:151], v[172:175], v[120:123]
	v_mfma_f32_16x16x32_bf16 v[120:123], v[152:155], v[176:179], v[120:123]
	v_mfma_f32_16x16x32_bf16 v[108:111], v[156:159], v[172:175], v[108:111]
	v_mfma_f32_16x16x32_bf16 v[108:111], v[160:163], v[176:179], v[108:111]
	v_mfma_f32_16x16x32_bf16 v[100:103], v[164:167], v[172:175], v[100:103]
	v_mfma_f32_16x16x32_bf16 v[100:103], v[168:171], v[176:179], v[100:103]
	v_mfma_f32_16x16x32_bf16 v[84:87], v[164:167], v[180:183], v[84:87]
	v_mfma_f32_16x16x32_bf16 v[84:87], v[168:171], v[184:187], v[84:87]
	v_mfma_f32_16x16x32_bf16 v[92:95], v[156:159], v[180:183], v[92:95]
	v_mfma_f32_16x16x32_bf16 v[92:95], v[160:163], v[184:187], v[92:95]
	v_mfma_f32_16x16x32_bf16 v[112:115], v[148:151], v[180:183], v[112:115]
	v_mfma_f32_16x16x32_bf16 v[112:115], v[152:155], v[184:187], v[112:115]
	v_mfma_f32_16x16x32_bf16 v[116:119], v[140:143], v[180:183], v[116:119]
	v_mfma_f32_16x16x32_bf16 v[116:119], v[144:147], v[184:187], v[116:119]
	v_mfma_f32_16x16x32_bf16 v[104:107], v[140:143], v[188:191], v[104:107]
	v_mfma_f32_16x16x32_bf16 v[104:107], v[144:147], v[192:195], v[104:107]
	v_mfma_f32_16x16x32_bf16 v[96:99], v[148:151], v[188:191], v[96:99]
	v_mfma_f32_16x16x32_bf16 v[96:99], v[152:155], v[192:195], v[96:99]
	v_mfma_f32_16x16x32_bf16 v[76:79], v[156:159], v[188:191], v[76:79]
	v_mfma_f32_16x16x32_bf16 v[76:79], v[160:163], v[192:195], v[76:79]
	v_mfma_f32_16x16x32_bf16 v[72:75], v[164:167], v[188:191], v[72:75]
	v_mfma_f32_16x16x32_bf16 v[72:75], v[168:171], v[192:195], v[72:75]
	v_mfma_f32_16x16x32_bf16 v[64:67], v[164:167], v[196:199], v[64:67]
	v_mfma_f32_16x16x32_bf16 v[64:67], v[168:171], v[200:203], v[64:67]
	v_mfma_f32_16x16x32_bf16 v[68:71], v[156:159], v[196:199], v[68:71]
	v_mfma_f32_16x16x32_bf16 v[68:71], v[160:163], v[200:203], v[68:71]
	v_mfma_f32_16x16x32_bf16 v[80:83], v[148:151], v[196:199], v[80:83]
	v_mfma_f32_16x16x32_bf16 v[80:83], v[152:155], v[200:203], v[80:83]
	v_mfma_f32_16x16x32_bf16 v[88:91], v[140:143], v[196:199], v[88:91]
	v_mfma_f32_16x16x32_bf16 v[88:91], v[144:147], v[200:203], v[88:91]
	s_setprio 0
	s_barrier
	s_add_i32 s63, s50, s37
	v_lshl_add_u64 v[204:205], s[28:29], 0, v[128:129]
	s_mov_b32 m0, s63
	ds_read_b128 v[172:175], v224 offset:16384
	ds_read_b128 v[176:179], v224 offset:17408
	ds_read_b128 v[180:183], v224 offset:18432
	ds_read_b128 v[184:187], v224 offset:19456
	ds_read_b128 v[188:191], v224 offset:20480
	ds_read_b128 v[192:195], v224 offset:21504
	ds_read_b128 v[196:199], v224 offset:22528
	ds_read_b128 v[200:203], v224 offset:23552
	global_load_lds_dwordx4 v[204:205], off
	s_add_i32 m0, s63, 0x2000
	s_add_u32 s64, s28, 0x4000
	v_lshl_add_u64 v[204:205], s[28:29], 0, v[130:131]
	s_addc_u32 s65, s29, 0
	s_add_i32 s63, s51, s37
	global_load_lds_dwordx4 v[204:205], off
	v_lshl_add_u64 v[204:205], s[64:65], 0, v[128:129]
	s_mov_b32 m0, s63
	s_nop 0
	global_load_lds_dwordx4 v[204:205], off
	v_lshl_add_u64 v[204:205], s[64:65], 0, v[130:131]
	s_add_i32 m0, s63, 0x2000
	s_nop 0
	global_load_lds_dwordx4 v[204:205], off
	v_lshl_add_u64 v[204:205], s[30:31], 0, v[128:129]
	s_mov_b32 m0, s38
	s_nop 0
	global_load_lds_dwordx4 v[204:205], off
	v_lshl_add_u64 v[204:205], s[30:31], 0, v[130:131]
	s_mov_b32 m0, s39
	s_nop 0
	global_load_lds_dwordx4 v[204:205], off
	s_waitcnt vmcnt(8)
	s_waitcnt lgkmcnt(0)
	s_barrier
	s_setprio 1
	s_waitcnt lgkmcnt(0)
	v_mfma_f32_16x16x32_bf16 v[60:63], v[140:143], v[172:175], v[60:63]
	v_mfma_f32_16x16x32_bf16 v[60:63], v[144:147], v[176:179], v[60:63]
	v_mfma_f32_16x16x32_bf16 v[56:59], v[148:151], v[172:175], v[56:59]
	v_mfma_f32_16x16x32_bf16 v[56:59], v[152:155], v[176:179], v[56:59]
	v_mfma_f32_16x16x32_bf16 v[44:47], v[156:159], v[172:175], v[44:47]
	v_mfma_f32_16x16x32_bf16 v[44:47], v[160:163], v[176:179], v[44:47]
	v_mfma_f32_16x16x32_bf16 v[36:39], v[164:167], v[172:175], v[36:39]
	v_mfma_f32_16x16x32_bf16 v[36:39], v[168:171], v[176:179], v[36:39]
	v_mfma_f32_16x16x32_bf16 v[20:23], v[164:167], v[180:183], v[20:23]
	v_mfma_f32_16x16x32_bf16 v[20:23], v[168:171], v[184:187], v[20:23]
	v_mfma_f32_16x16x32_bf16 v[28:31], v[156:159], v[180:183], v[28:31]
	v_mfma_f32_16x16x32_bf16 v[28:31], v[160:163], v[184:187], v[28:31]
	v_mfma_f32_16x16x32_bf16 v[48:51], v[148:151], v[180:183], v[48:51]
	v_mfma_f32_16x16x32_bf16 v[48:51], v[152:155], v[184:187], v[48:51]
	v_mfma_f32_16x16x32_bf16 v[52:55], v[140:143], v[180:183], v[52:55]
	v_mfma_f32_16x16x32_bf16 v[52:55], v[144:147], v[184:187], v[52:55]
	v_mfma_f32_16x16x32_bf16 v[40:43], v[140:143], v[188:191], v[40:43]
	v_mfma_f32_16x16x32_bf16 v[40:43], v[144:147], v[192:195], v[40:43]
	v_mfma_f32_16x16x32_bf16 v[32:35], v[148:151], v[188:191], v[32:35]
	v_mfma_f32_16x16x32_bf16 v[32:35], v[152:155], v[192:195], v[32:35]
	v_mfma_f32_16x16x32_bf16 v[12:15], v[156:159], v[188:191], v[12:15]
	v_mfma_f32_16x16x32_bf16 v[12:15], v[160:163], v[192:195], v[12:15]
	v_mfma_f32_16x16x32_bf16 v[8:11], v[164:167], v[188:191], v[8:11]
	v_mfma_f32_16x16x32_bf16 v[8:11], v[168:171], v[192:195], v[8:11]
	v_mfma_f32_16x16x32_bf16 v[0:3], v[164:167], v[196:199], v[0:3]
	v_mfma_f32_16x16x32_bf16 v[0:3], v[168:171], v[200:203], v[0:3]
	v_mfma_f32_16x16x32_bf16 v[4:7], v[156:159], v[196:199], v[4:7]
	v_mfma_f32_16x16x32_bf16 v[4:7], v[160:163], v[200:203], v[4:7]
	v_mfma_f32_16x16x32_bf16 v[16:19], v[148:151], v[196:199], v[16:19]
	v_mfma_f32_16x16x32_bf16 v[16:19], v[152:155], v[200:203], v[16:19]
	v_mfma_f32_16x16x32_bf16 v[24:27], v[140:143], v[196:199], v[24:27]
	v_mfma_f32_16x16x32_bf16 v[24:27], v[144:147], v[200:203], v[24:27]
	s_setprio 0
	s_barrier
	s_add_i32 s63, 0, 0x18000
	s_add_i32 s64, 0, 0x1c000
	v_add_u32_e32 v152, s63, v219
	v_add_u32_e32 v168, s64, v219
	ds_read_b128 v[140:143], v152
	ds_read_b128 v[144:147], v152 offset:1024
	ds_read_b128 v[148:151], v152 offset:2048
	ds_read_b128 v[152:155], v152 offset:3072
	ds_read_b128 v[156:159], v168
	ds_read_b128 v[160:163], v168 offset:1024
	ds_read_b128 v[164:167], v168 offset:2048
	ds_read_b128 v[168:171], v168 offset:3072
	s_add_u32 s30, s30, 0x4000
	s_addc_u32 s31, s31, 0
	s_mov_b32 m0, s40
	v_lshl_add_u64 v[204:205], s[30:31], 0, v[128:129]
	ds_read_b128 v[172:175], v224 offset:32768
	ds_read_b128 v[176:179], v224 offset:33792
	ds_read_b128 v[180:183], v224 offset:34816
	ds_read_b128 v[184:187], v224 offset:35840
	ds_read_b128 v[188:191], v224 offset:36864
	ds_read_b128 v[192:195], v224 offset:37888
	ds_read_b128 v[196:199], v224 offset:38912
	ds_read_b128 v[200:203], v224 offset:39936
	global_load_lds_dwordx4 v[204:205], off
	v_lshl_add_u64 v[204:205], s[30:31], 0, v[130:131]
	s_mov_b32 m0, s41
	s_nop 0
	global_load_lds_dwordx4 v[204:205], off
	s_waitcnt vmcnt(8)
	s_waitcnt lgkmcnt(0)
	s_barrier
	s_setprio 1
	s_waitcnt lgkmcnt(0)
	v_mfma_f32_16x16x32_bf16 v[124:127], v[140:143], v[172:175], v[124:127]
	v_mfma_f32_16x16x32_bf16 v[124:127], v[144:147], v[176:179], v[124:127]
	v_mfma_f32_16x16x32_bf16 v[120:123], v[148:151], v[172:175], v[120:123]
	v_mfma_f32_16x16x32_bf16 v[120:123], v[152:155], v[176:179], v[120:123]
	v_mfma_f32_16x16x32_bf16 v[108:111], v[156:159], v[172:175], v[108:111]
	v_mfma_f32_16x16x32_bf16 v[108:111], v[160:163], v[176:179], v[108:111]
	v_mfma_f32_16x16x32_bf16 v[100:103], v[164:167], v[172:175], v[100:103]
	v_mfma_f32_16x16x32_bf16 v[100:103], v[168:171], v[176:179], v[100:103]
	v_mfma_f32_16x16x32_bf16 v[84:87], v[164:167], v[180:183], v[84:87]
	v_mfma_f32_16x16x32_bf16 v[84:87], v[168:171], v[184:187], v[84:87]
	v_mfma_f32_16x16x32_bf16 v[92:95], v[156:159], v[180:183], v[92:95]
	v_mfma_f32_16x16x32_bf16 v[92:95], v[160:163], v[184:187], v[92:95]
	v_mfma_f32_16x16x32_bf16 v[112:115], v[148:151], v[180:183], v[112:115]
	v_mfma_f32_16x16x32_bf16 v[112:115], v[152:155], v[184:187], v[112:115]
	v_mfma_f32_16x16x32_bf16 v[116:119], v[140:143], v[180:183], v[116:119]
	v_mfma_f32_16x16x32_bf16 v[116:119], v[144:147], v[184:187], v[116:119]
	v_mfma_f32_16x16x32_bf16 v[104:107], v[140:143], v[188:191], v[104:107]
	v_mfma_f32_16x16x32_bf16 v[104:107], v[144:147], v[192:195], v[104:107]
	v_mfma_f32_16x16x32_bf16 v[96:99], v[148:151], v[188:191], v[96:99]
	v_mfma_f32_16x16x32_bf16 v[96:99], v[152:155], v[192:195], v[96:99]
	v_mfma_f32_16x16x32_bf16 v[76:79], v[156:159], v[188:191], v[76:79]
	v_mfma_f32_16x16x32_bf16 v[76:79], v[160:163], v[192:195], v[76:79]
	v_mfma_f32_16x16x32_bf16 v[72:75], v[164:167], v[188:191], v[72:75]
	v_mfma_f32_16x16x32_bf16 v[72:75], v[168:171], v[192:195], v[72:75]
	v_mfma_f32_16x16x32_bf16 v[64:67], v[164:167], v[196:199], v[64:67]
	v_mfma_f32_16x16x32_bf16 v[64:67], v[168:171], v[200:203], v[64:67]
	v_mfma_f32_16x16x32_bf16 v[68:71], v[156:159], v[196:199], v[68:71]
	v_mfma_f32_16x16x32_bf16 v[68:71], v[160:163], v[200:203], v[68:71]
	v_mfma_f32_16x16x32_bf16 v[80:83], v[148:151], v[196:199], v[80:83]
	v_mfma_f32_16x16x32_bf16 v[80:83], v[152:155], v[200:203], v[80:83]
	v_mfma_f32_16x16x32_bf16 v[88:91], v[140:143], v[196:199], v[88:91]
	v_mfma_f32_16x16x32_bf16 v[88:91], v[144:147], v[200:203], v[88:91]
	s_setprio 0
	s_barrier
	s_add_u32 s30, s28, 0x8000
	s_addc_u32 s31, s29, 0
	s_add_i32 s63, s63, s37
	v_lshl_add_u64 v[204:205], s[30:31], 0, v[128:129]
	s_mov_b32 m0, s63
	ds_read_b128 v[172:175], v224 offset:49152
	ds_read_b128 v[176:179], v224 offset:50176
	ds_read_b128 v[180:183], v224 offset:51200
	ds_read_b128 v[184:187], v224 offset:52224
	ds_read_b128 v[188:191], v224 offset:53248
	ds_read_b128 v[192:195], v224 offset:54272
	ds_read_b128 v[196:199], v224 offset:55296
	ds_read_b128 v[200:203], v224 offset:56320
	global_load_lds_dwordx4 v[204:205], off
	s_add_i32 m0, s63, 0x2000
	s_add_u32 s28, s28, 0xc000
	v_lshl_add_u64 v[204:205], s[30:31], 0, v[130:131]
	s_addc_u32 s29, s29, 0
	s_add_i32 s30, s64, s37
	global_load_lds_dwordx4 v[204:205], off
	v_lshl_add_u64 v[204:205], s[28:29], 0, v[128:129]
	s_mov_b32 m0, s30
	s_nop 0
	global_load_lds_dwordx4 v[204:205], off
	v_lshl_add_u64 v[204:205], s[28:29], 0, v[130:131]
	s_add_i32 m0, s30, 0x2000
	s_nop 0
	global_load_lds_dwordx4 v[204:205], off
	v_lshl_add_u64 v[204:205], s[26:27], 0, v[128:129]
	s_mov_b32 m0, s44
	s_nop 0
	global_load_lds_dwordx4 v[204:205], off
	v_lshl_add_u64 v[204:205], s[26:27], 0, v[130:131]
	s_mov_b32 m0, s45
	s_nop 0
	global_load_lds_dwordx4 v[204:205], off
	s_waitcnt vmcnt(8)
	s_waitcnt lgkmcnt(0)
	s_barrier
	s_setprio 1
	s_waitcnt lgkmcnt(0)
	v_mfma_f32_16x16x32_bf16 v[60:63], v[140:143], v[172:175], v[60:63]
	v_mfma_f32_16x16x32_bf16 v[60:63], v[144:147], v[176:179], v[60:63]
	v_mfma_f32_16x16x32_bf16 v[56:59], v[148:151], v[172:175], v[56:59]
	v_mfma_f32_16x16x32_bf16 v[56:59], v[152:155], v[176:179], v[56:59]
	v_mfma_f32_16x16x32_bf16 v[44:47], v[156:159], v[172:175], v[44:47]
	v_mfma_f32_16x16x32_bf16 v[44:47], v[160:163], v[176:179], v[44:47]
	v_mfma_f32_16x16x32_bf16 v[36:39], v[164:167], v[172:175], v[36:39]
	v_mfma_f32_16x16x32_bf16 v[36:39], v[168:171], v[176:179], v[36:39]
	v_mfma_f32_16x16x32_bf16 v[20:23], v[164:167], v[180:183], v[20:23]
	v_mfma_f32_16x16x32_bf16 v[20:23], v[168:171], v[184:187], v[20:23]
	v_mfma_f32_16x16x32_bf16 v[28:31], v[156:159], v[180:183], v[28:31]
	v_mfma_f32_16x16x32_bf16 v[28:31], v[160:163], v[184:187], v[28:31]
	v_mfma_f32_16x16x32_bf16 v[48:51], v[148:151], v[180:183], v[48:51]
	v_mfma_f32_16x16x32_bf16 v[48:51], v[152:155], v[184:187], v[48:51]
	v_mfma_f32_16x16x32_bf16 v[52:55], v[140:143], v[180:183], v[52:55]
	v_mfma_f32_16x16x32_bf16 v[52:55], v[144:147], v[184:187], v[52:55]
	v_mfma_f32_16x16x32_bf16 v[40:43], v[140:143], v[188:191], v[40:43]
	v_mfma_f32_16x16x32_bf16 v[40:43], v[144:147], v[192:195], v[40:43]
	v_mfma_f32_16x16x32_bf16 v[32:35], v[148:151], v[188:191], v[32:35]
	v_mfma_f32_16x16x32_bf16 v[32:35], v[152:155], v[192:195], v[32:35]
	v_mfma_f32_16x16x32_bf16 v[12:15], v[156:159], v[188:191], v[12:15]
	v_mfma_f32_16x16x32_bf16 v[12:15], v[160:163], v[192:195], v[12:15]
	v_mfma_f32_16x16x32_bf16 v[8:11], v[164:167], v[188:191], v[8:11]
	v_mfma_f32_16x16x32_bf16 v[8:11], v[168:171], v[192:195], v[8:11]
	v_mfma_f32_16x16x32_bf16 v[0:3], v[164:167], v[196:199], v[0:3]
	v_mfma_f32_16x16x32_bf16 v[0:3], v[168:171], v[200:203], v[0:3]
	v_mfma_f32_16x16x32_bf16 v[4:7], v[156:159], v[196:199], v[4:7]
	v_mfma_f32_16x16x32_bf16 v[4:7], v[160:163], v[200:203], v[4:7]
	v_mfma_f32_16x16x32_bf16 v[16:19], v[148:151], v[196:199], v[16:19]
	v_mfma_f32_16x16x32_bf16 v[16:19], v[152:155], v[200:203], v[16:19]
	v_mfma_f32_16x16x32_bf16 v[24:27], v[140:143], v[196:199], v[24:27]
	v_mfma_f32_16x16x32_bf16 v[24:27], v[144:147], v[200:203], v[24:27]
	s_setprio 0
	s_barrier
	s_add_u32 s24, s24, 0x10000
	s_addc_u32 s25, s25, 0
	s_add_u32 s60, s60, 0x10000
	s_addc_u32 s61, s61, 0
	s_cmp_ge_i32 s62, s43
	s_mov_b32 s26, s62
	s_cbranch_scc0 .LBB0_1056
	v_pk_mul_f32 v[198:199], v[126:127], 0.5 op_sel_hi:[1,0]
	v_pk_mul_f32 v[200:201], v[124:125], 0.5 op_sel_hi:[1,0]
	v_pk_mul_f32 v[202:203], v[122:123], 0.5 op_sel_hi:[1,0]
	v_pk_mul_f32 v[204:205], v[120:121], 0.5 op_sel_hi:[1,0]
	v_pk_mul_f32 v[208:209], v[110:111], 0.5 op_sel_hi:[1,0]
	v_pk_mul_f32 v[206:207], v[108:109], 0.5 op_sel_hi:[1,0]
	v_pk_mul_f32 v[196:197], v[102:103], 0.5 op_sel_hi:[1,0]
	v_pk_mul_f32 v[194:195], v[100:101], 0.5 op_sel_hi:[1,0]
	v_pk_mul_f32 v[192:193], v[118:119], 0.5 op_sel_hi:[1,0]
	v_pk_mul_f32 v[190:191], v[116:117], 0.5 op_sel_hi:[1,0]
	v_pk_mul_f32 v[188:189], v[114:115], 0.5 op_sel_hi:[1,0]
	v_pk_mul_f32 v[186:187], v[112:113], 0.5 op_sel_hi:[1,0]
	v_pk_mul_f32 v[184:185], v[94:95], 0.5 op_sel_hi:[1,0]
	v_pk_mul_f32 v[182:183], v[92:93], 0.5 op_sel_hi:[1,0]
	v_pk_mul_f32 v[180:181], v[86:87], 0.5 op_sel_hi:[1,0]
	v_pk_mul_f32 v[178:179], v[84:85], 0.5 op_sel_hi:[1,0]
	v_pk_mul_f32 v[176:177], v[106:107], 0.5 op_sel_hi:[1,0]
	v_pk_mul_f32 v[174:175], v[104:105], 0.5 op_sel_hi:[1,0]
	v_pk_mul_f32 v[172:173], v[98:99], 0.5 op_sel_hi:[1,0]
	v_pk_mul_f32 v[170:171], v[96:97], 0.5 op_sel_hi:[1,0]
	v_pk_mul_f32 v[168:169], v[78:79], 0.5 op_sel_hi:[1,0]
	v_pk_mul_f32 v[166:167], v[76:77], 0.5 op_sel_hi:[1,0]
	v_pk_mul_f32 v[164:165], v[74:75], 0.5 op_sel_hi:[1,0]
	v_pk_mul_f32 v[162:163], v[72:73], 0.5 op_sel_hi:[1,0]
	v_pk_mul_f32 v[160:161], v[90:91], 0.5 op_sel_hi:[1,0]
	v_pk_mul_f32 v[158:159], v[88:89], 0.5 op_sel_hi:[1,0]
	v_pk_mul_f32 v[156:157], v[82:83], 0.5 op_sel_hi:[1,0]
	v_pk_mul_f32 v[154:155], v[80:81], 0.5 op_sel_hi:[1,0]
	v_pk_mul_f32 v[152:153], v[70:71], 0.5 op_sel_hi:[1,0]
	v_pk_mul_f32 v[150:151], v[68:69], 0.5 op_sel_hi:[1,0]
	v_pk_mul_f32 v[148:149], v[66:67], 0.5 op_sel_hi:[1,0]
	v_pk_mul_f32 v[146:147], v[64:65], 0.5 op_sel_hi:[1,0]
	v_pk_mul_f32 v[142:143], v[62:63], 0.5 op_sel_hi:[1,0]
	v_pk_mul_f32 v[140:141], v[60:61], 0.5 op_sel_hi:[1,0]
	v_pk_mul_f32 v[126:127], v[58:59], 0.5 op_sel_hi:[1,0]
	v_pk_mul_f32 v[124:125], v[56:57], 0.5 op_sel_hi:[1,0]
	v_pk_mul_f32 v[122:123], v[46:47], 0.5 op_sel_hi:[1,0]
	v_pk_mul_f32 v[120:121], v[44:45], 0.5 op_sel_hi:[1,0]
	v_pk_mul_f32 v[118:119], v[38:39], 0.5 op_sel_hi:[1,0]
	v_pk_mul_f32 v[116:117], v[36:37], 0.5 op_sel_hi:[1,0]
	v_pk_mul_f32 v[114:115], v[54:55], 0.5 op_sel_hi:[1,0]
	v_pk_mul_f32 v[112:113], v[52:53], 0.5 op_sel_hi:[1,0]
	v_pk_mul_f32 v[110:111], v[50:51], 0.5 op_sel_hi:[1,0]
	v_pk_mul_f32 v[108:109], v[48:49], 0.5 op_sel_hi:[1,0]
	v_pk_mul_f32 v[106:107], v[30:31], 0.5 op_sel_hi:[1,0]
	v_pk_mul_f32 v[104:105], v[28:29], 0.5 op_sel_hi:[1,0]
	v_pk_mul_f32 v[102:103], v[22:23], 0.5 op_sel_hi:[1,0]
	v_pk_mul_f32 v[100:101], v[20:21], 0.5 op_sel_hi:[1,0]
	v_pk_mul_f32 v[98:99], v[42:43], 0.5 op_sel_hi:[1,0]
	v_pk_mul_f32 v[96:97], v[40:41], 0.5 op_sel_hi:[1,0]
	v_pk_mul_f32 v[94:95], v[34:35], 0.5 op_sel_hi:[1,0]
	v_pk_mul_f32 v[92:93], v[32:33], 0.5 op_sel_hi:[1,0]
	v_pk_mul_f32 v[90:91], v[14:15], 0.5 op_sel_hi:[1,0]
	v_pk_mul_f32 v[88:89], v[12:13], 0.5 op_sel_hi:[1,0]
	v_pk_mul_f32 v[86:87], v[10:11], 0.5 op_sel_hi:[1,0]
	v_pk_mul_f32 v[84:85], v[8:9], 0.5 op_sel_hi:[1,0]
	v_pk_mul_f32 v[82:83], v[26:27], 0.5 op_sel_hi:[1,0]
	v_pk_mul_f32 v[80:81], v[24:25], 0.5 op_sel_hi:[1,0]
	v_pk_mul_f32 v[78:79], v[18:19], 0.5 op_sel_hi:[1,0]
	v_pk_mul_f32 v[76:77], v[16:17], 0.5 op_sel_hi:[1,0]
	v_pk_mul_f32 v[74:75], v[6:7], 0.5 op_sel_hi:[1,0]
	v_pk_mul_f32 v[72:73], v[4:5], 0.5 op_sel_hi:[1,0]
	v_pk_mul_f32 v[70:71], v[2:3], 0.5 op_sel_hi:[1,0]
	v_pk_mul_f32 v[68:69], v[0:1], 0.5 op_sel_hi:[1,0]

.LBB0_1159:
	ds_read_b128 v[128:131], v205
	ds_read_b128 v[132:135], v205 offset:1024
	ds_read_b128 v[136:139], v205 offset:2048
	ds_read_b128 v[140:143], v205 offset:3072
	ds_read_b128 v[144:147], v206
	ds_read_b128 v[160:163], v206 offset:1024
	ds_read_b128 v[164:167], v206 offset:2048
	ds_read_b128 v[168:171], v206 offset:3072
	s_add_i32 s41, s6, 2
	s_add_u32 s68, s0, 0x80
	s_addc_u32 s7, s1, 0
	s_cmp_eq_u32 s57, s6
	s_cselect_b32 s6, s34, s68
	s_cselect_b32 s7, s35, s7
	s_cselect_b32 s69, s37, s39
	s_cselect_b32 s68, s36, s38
	v_lshl_add_u64 v[200:201], s[0:1], 0, v[152:153]
	s_add_i32 m0, s47, 0xc000
	ds_read_b128 v[172:175], v207
	ds_read_b128 v[176:179], v207 offset:1024
	ds_read_b128 v[180:183], v207 offset:2048
	ds_read_b128 v[184:187], v207 offset:3072
	ds_read_b128 v[188:191], v207 offset:4096
	ds_read_b128 v[192:195], v207 offset:5120
	ds_read_b128 v[196:199], v207 offset:6144
	ds_read_b128 v[212:215], v207 offset:7168
	global_load_lds_dwordx4 v[200:201], off
	v_lshl_add_u64 v[200:201], s[0:1], 0, v[154:155]
	s_add_i32 m0, s47, 0xe000
	s_nop 0
	global_load_lds_dwordx4 v[200:201], off
	s_waitcnt vmcnt(8)
	s_waitcnt lgkmcnt(0)
	s_barrier
	s_setprio 1
	s_waitcnt lgkmcnt(0)
	v_mfma_f32_16x16x32_bf16 v[124:127], v[128:131], v[172:175], v[124:127]
	v_mfma_f32_16x16x32_bf16 v[124:127], v[132:135], v[176:179], v[124:127]
	v_mfma_f32_16x16x32_bf16 v[120:123], v[136:139], v[172:175], v[120:123]
	v_mfma_f32_16x16x32_bf16 v[120:123], v[140:143], v[176:179], v[120:123]
	v_mfma_f32_16x16x32_bf16 v[116:119], v[144:147], v[172:175], v[116:119]
	v_mfma_f32_16x16x32_bf16 v[116:119], v[160:163], v[176:179], v[116:119]
	v_mfma_f32_16x16x32_bf16 v[112:115], v[164:167], v[172:175], v[112:115]
	v_mfma_f32_16x16x32_bf16 v[112:115], v[168:171], v[176:179], v[112:115]
	v_mfma_f32_16x16x32_bf16 v[96:99], v[164:167], v[180:183], v[96:99]
	v_mfma_f32_16x16x32_bf16 v[96:99], v[168:171], v[184:187], v[96:99]
	v_mfma_f32_16x16x32_bf16 v[100:103], v[144:147], v[180:183], v[100:103]
	v_mfma_f32_16x16x32_bf16 v[100:103], v[160:163], v[184:187], v[100:103]
	v_mfma_f32_16x16x32_bf16 v[104:107], v[136:139], v[180:183], v[104:107]
	v_mfma_f32_16x16x32_bf16 v[104:107], v[140:143], v[184:187], v[104:107]
	v_mfma_f32_16x16x32_bf16 v[108:111], v[128:131], v[180:183], v[108:111]
	v_mfma_f32_16x16x32_bf16 v[108:111], v[132:135], v[184:187], v[108:111]
	v_mfma_f32_16x16x32_bf16 v[92:95], v[128:131], v[188:191], v[92:95]
	v_mfma_f32_16x16x32_bf16 v[92:95], v[132:135], v[192:195], v[92:95]
	v_mfma_f32_16x16x32_bf16 v[88:91], v[136:139], v[188:191], v[88:91]
	v_mfma_f32_16x16x32_bf16 v[88:91], v[140:143], v[192:195], v[88:91]
	v_mfma_f32_16x16x32_bf16 v[84:87], v[144:147], v[188:191], v[84:87]
	v_mfma_f32_16x16x32_bf16 v[84:87], v[160:163], v[192:195], v[84:87]
	v_mfma_f32_16x16x32_bf16 v[80:83], v[164:167], v[188:191], v[80:83]
	v_mfma_f32_16x16x32_bf16 v[80:83], v[168:171], v[192:195], v[80:83]
	v_mfma_f32_16x16x32_bf16 v[64:67], v[164:167], v[196:199], v[64:67]
	v_mfma_f32_16x16x32_bf16 v[64:67], v[168:171], v[212:215], v[64:67]
	v_mfma_f32_16x16x32_bf16 v[68:71], v[144:147], v[196:199], v[68:71]
	v_mfma_f32_16x16x32_bf16 v[68:71], v[160:163], v[212:215], v[68:71]
	v_mfma_f32_16x16x32_bf16 v[72:75], v[136:139], v[196:199], v[72:75]
	v_mfma_f32_16x16x32_bf16 v[72:75], v[140:143], v[212:215], v[72:75]
	v_mfma_f32_16x16x32_bf16 v[76:79], v[128:131], v[196:199], v[76:79]
	v_mfma_f32_16x16x32_bf16 v[76:79], v[132:135], v[212:215], v[76:79]
	s_setprio 0
	s_barrier
	s_add_i32 s70, s60, s46
	v_lshl_add_u64 v[200:201], s[68:69], 0, v[148:149]
	s_mov_b32 m0, s70
	ds_read_b128 v[172:175], v207 offset:16384
	ds_read_b128 v[176:179], v207 offset:17408
	ds_read_b128 v[180:183], v207 offset:18432
	ds_read_b128 v[184:187], v207 offset:19456
	ds_read_b128 v[188:191], v207 offset:20480
	ds_read_b128 v[192:195], v207 offset:21504
	ds_read_b128 v[196:199], v207 offset:22528
	ds_read_b128 v[212:215], v207 offset:23552
	global_load_lds_dwordx4 v[200:201], off
	s_add_i32 m0, s70, 0x2000
	v_lshl_add_u64 v[216:217], s[68:69], 0, v[150:151]
	s_add_u32 s68, s68, s10
	s_addc_u32 s69, s69, s11
	s_add_i32 s70, s61, s46
	global_load_lds_dwordx4 v[216:217], off
	v_lshl_add_u64 v[218:219], s[68:69], 0, v[148:149]
	s_mov_b32 m0, s70
	v_lshl_add_u64 v[220:221], s[68:69], 0, v[150:151]
	global_load_lds_dwordx4 v[218:219], off
	s_add_i32 m0, s70, 0x2000
	v_lshl_add_u64 v[222:223], s[6:7], 0, v[148:149]
	global_load_lds_dwordx4 v[220:221], off
	s_mov_b32 m0, s47
	v_lshl_add_u64 v[224:225], s[6:7], 0, v[150:151]
	global_load_lds_dwordx4 v[222:223], off
	s_mov_b32 m0, s48
	s_nop 0
	global_load_lds_dwordx4 v[224:225], off
	s_waitcnt vmcnt(8)
	s_waitcnt lgkmcnt(0)
	s_barrier
	s_setprio 1
	s_waitcnt lgkmcnt(0)
	v_mfma_f32_16x16x32_bf16 v[60:63], v[128:131], v[172:175], v[60:63]
	v_mfma_f32_16x16x32_bf16 v[60:63], v[132:135], v[176:179], v[60:63]
	v_mfma_f32_16x16x32_bf16 v[56:59], v[136:139], v[172:175], v[56:59]
	v_mfma_f32_16x16x32_bf16 v[56:59], v[140:143], v[176:179], v[56:59]
	v_mfma_f32_16x16x32_bf16 v[52:55], v[144:147], v[172:175], v[52:55]
	v_mfma_f32_16x16x32_bf16 v[52:55], v[160:163], v[176:179], v[52:55]
	v_mfma_f32_16x16x32_bf16 v[48:51], v[164:167], v[172:175], v[48:51]
	v_mfma_f32_16x16x32_bf16 v[48:51], v[168:171], v[176:179], v[48:51]
	v_mfma_f32_16x16x32_bf16 v[32:35], v[164:167], v[180:183], v[32:35]
	v_mfma_f32_16x16x32_bf16 v[32:35], v[168:171], v[184:187], v[32:35]
	v_mfma_f32_16x16x32_bf16 v[36:39], v[144:147], v[180:183], v[36:39]
	v_mfma_f32_16x16x32_bf16 v[36:39], v[160:163], v[184:187], v[36:39]
	v_mfma_f32_16x16x32_bf16 v[40:43], v[136:139], v[180:183], v[40:43]
	v_mfma_f32_16x16x32_bf16 v[40:43], v[140:143], v[184:187], v[40:43]
	v_mfma_f32_16x16x32_bf16 v[44:47], v[128:131], v[180:183], v[44:47]
	v_mfma_f32_16x16x32_bf16 v[44:47], v[132:135], v[184:187], v[44:47]
	v_mfma_f32_16x16x32_bf16 v[28:31], v[128:131], v[188:191], v[28:31]
	v_mfma_f32_16x16x32_bf16 v[28:31], v[132:135], v[192:195], v[28:31]
	v_mfma_f32_16x16x32_bf16 v[24:27], v[136:139], v[188:191], v[24:27]
	v_mfma_f32_16x16x32_bf16 v[24:27], v[140:143], v[192:195], v[24:27]
	v_mfma_f32_16x16x32_bf16 v[20:23], v[144:147], v[188:191], v[20:23]
	v_mfma_f32_16x16x32_bf16 v[20:23], v[160:163], v[192:195], v[20:23]
	v_mfma_f32_16x16x32_bf16 v[16:19], v[164:167], v[188:191], v[16:19]
	v_mfma_f32_16x16x32_bf16 v[16:19], v[168:171], v[192:195], v[16:19]
	v_mfma_f32_16x16x32_bf16 v[0:3], v[164:167], v[196:199], v[0:3]
	v_mfma_f32_16x16x32_bf16 v[0:3], v[168:171], v[212:215], v[0:3]
	v_mfma_f32_16x16x32_bf16 v[4:7], v[144:147], v[196:199], v[4:7]
	v_mfma_f32_16x16x32_bf16 v[4:7], v[160:163], v[212:215], v[4:7]
	v_mfma_f32_16x16x32_bf16 v[8:11], v[136:139], v[196:199], v[8:11]
	v_mfma_f32_16x16x32_bf16 v[8:11], v[140:143], v[212:215], v[8:11]
	v_mfma_f32_16x16x32_bf16 v[12:15], v[128:131], v[196:199], v[12:15]
	v_mfma_f32_16x16x32_bf16 v[12:15], v[132:135], v[212:215], v[12:15]
	s_setprio 0
	s_barrier
	s_add_i32 s68, 0, 0x18000
	s_add_i32 s69, 0, 0x1c000
	v_add_u32_e32 v140, s68, v203
	v_add_u32_e32 v168, s69, v203
	ds_read_b128 v[128:131], v140
	ds_read_b128 v[132:135], v140 offset:1024
	ds_read_b128 v[136:139], v140 offset:2048
	ds_read_b128 v[140:143], v140 offset:3072
	ds_read_b128 v[144:147], v168
	ds_read_b128 v[160:163], v168 offset:1024
	ds_read_b128 v[164:167], v168 offset:2048
	ds_read_b128 v[168:171], v168 offset:3072
	s_add_u32 s6, s6, s10
	s_addc_u32 s7, s7, s11
	s_mov_b32 m0, s49
	v_lshl_add_u64 v[226:227], s[6:7], 0, v[148:149]
	ds_read_b128 v[172:175], v207 offset:32768
	ds_read_b128 v[176:179], v207 offset:33792
	ds_read_b128 v[180:183], v207 offset:34816
	ds_read_b128 v[184:187], v207 offset:35840
	ds_read_b128 v[188:191], v207 offset:36864
	ds_read_b128 v[192:195], v207 offset:37888
	ds_read_b128 v[196:199], v207 offset:38912
	ds_read_b128 v[212:215], v207 offset:39936
	global_load_lds_dwordx4 v[226:227], off
	v_lshl_add_u64 v[226:227], s[6:7], 0, v[150:151]
	s_mov_b32 m0, s50
	s_nop 0
	global_load_lds_dwordx4 v[226:227], off
	s_waitcnt vmcnt(8)
	s_waitcnt lgkmcnt(0)
	s_barrier
	s_setprio 1
	s_waitcnt lgkmcnt(0)
	v_mfma_f32_16x16x32_bf16 v[124:127], v[128:131], v[172:175], v[124:127]
	v_mfma_f32_16x16x32_bf16 v[124:127], v[132:135], v[176:179], v[124:127]
	v_mfma_f32_16x16x32_bf16 v[120:123], v[136:139], v[172:175], v[120:123]
	v_mfma_f32_16x16x32_bf16 v[120:123], v[140:143], v[176:179], v[120:123]
	v_mfma_f32_16x16x32_bf16 v[116:119], v[144:147], v[172:175], v[116:119]
	v_mfma_f32_16x16x32_bf16 v[116:119], v[160:163], v[176:179], v[116:119]
	v_mfma_f32_16x16x32_bf16 v[112:115], v[164:167], v[172:175], v[112:115]
	v_mfma_f32_16x16x32_bf16 v[112:115], v[168:171], v[176:179], v[112:115]
	v_mfma_f32_16x16x32_bf16 v[96:99], v[164:167], v[180:183], v[96:99]
	v_mfma_f32_16x16x32_bf16 v[96:99], v[168:171], v[184:187], v[96:99]
	v_mfma_f32_16x16x32_bf16 v[100:103], v[144:147], v[180:183], v[100:103]
	v_mfma_f32_16x16x32_bf16 v[100:103], v[160:163], v[184:187], v[100:103]
	v_mfma_f32_16x16x32_bf16 v[104:107], v[136:139], v[180:183], v[104:107]
	v_mfma_f32_16x16x32_bf16 v[104:107], v[140:143], v[184:187], v[104:107]
	v_mfma_f32_16x16x32_bf16 v[108:111], v[128:131], v[180:183], v[108:111]
	v_mfma_f32_16x16x32_bf16 v[108:111], v[132:135], v[184:187], v[108:111]
	v_mfma_f32_16x16x32_bf16 v[92:95], v[128:131], v[188:191], v[92:95]
	v_mfma_f32_16x16x32_bf16 v[92:95], v[132:135], v[192:195], v[92:95]
	v_mfma_f32_16x16x32_bf16 v[88:91], v[136:139], v[188:191], v[88:91]
	v_mfma_f32_16x16x32_bf16 v[88:91], v[140:143], v[192:195], v[88:91]
	v_mfma_f32_16x16x32_bf16 v[84:87], v[144:147], v[188:191], v[84:87]
	v_mfma_f32_16x16x32_bf16 v[84:87], v[160:163], v[192:195], v[84:87]
	v_mfma_f32_16x16x32_bf16 v[80:83], v[164:167], v[188:191], v[80:83]
	v_mfma_f32_16x16x32_bf16 v[80:83], v[168:171], v[192:195], v[80:83]
	v_mfma_f32_16x16x32_bf16 v[64:67], v[164:167], v[196:199], v[64:67]
	v_mfma_f32_16x16x32_bf16 v[64:67], v[168:171], v[212:215], v[64:67]
	v_mfma_f32_16x16x32_bf16 v[68:71], v[144:147], v[196:199], v[68:71]
	v_mfma_f32_16x16x32_bf16 v[68:71], v[160:163], v[212:215], v[68:71]
	v_mfma_f32_16x16x32_bf16 v[72:75], v[136:139], v[196:199], v[72:75]
	v_mfma_f32_16x16x32_bf16 v[72:75], v[140:143], v[212:215], v[72:75]
	v_mfma_f32_16x16x32_bf16 v[76:79], v[128:131], v[196:199], v[76:79]
	v_mfma_f32_16x16x32_bf16 v[76:79], v[132:135], v[212:215], v[76:79]
	s_setprio 0
	s_barrier
	s_add_i32 s6, s68, s46
	v_lshl_add_u64 v[200:201], v[200:201], 0, s[20:21]
	s_mov_b32 m0, s6
	ds_read_b128 v[172:175], v207 offset:49152
	ds_read_b128 v[176:179], v207 offset:50176
	ds_read_b128 v[180:183], v207 offset:51200
	ds_read_b128 v[184:187], v207 offset:52224
	ds_read_b128 v[188:191], v207 offset:53248
	ds_read_b128 v[192:195], v207 offset:54272
	ds_read_b128 v[196:199], v207 offset:55296
	ds_read_b128 v[212:215], v207 offset:56320
	global_load_lds_dwordx4 v[200:201], off
	v_lshl_add_u64 v[200:201], v[216:217], 0, s[20:21]
	s_add_i32 m0, s6, 0x2000
	s_add_i32 s6, s69, s46
	global_load_lds_dwordx4 v[200:201], off
	v_lshl_add_u64 v[200:201], v[218:219], 0, s[20:21]
	s_mov_b32 m0, s6
	s_nop 0
	global_load_lds_dwordx4 v[200:201], off
	v_lshl_add_u64 v[200:201], v[220:221], 0, s[20:21]
	s_add_i32 m0, s6, 0x2000
	s_nop 0
	global_load_lds_dwordx4 v[200:201], off
	v_lshl_add_u64 v[200:201], v[222:223], 0, s[20:21]
	s_mov_b32 m0, s54
	s_nop 0
	global_load_lds_dwordx4 v[200:201], off
	v_lshl_add_u64 v[200:201], v[224:225], 0, s[20:21]
	s_mov_b32 m0, s55
	s_nop 0
	global_load_lds_dwordx4 v[200:201], off
	s_waitcnt vmcnt(8)
	s_waitcnt lgkmcnt(0)
	s_barrier
	s_setprio 1
	s_waitcnt lgkmcnt(0)
	v_mfma_f32_16x16x32_bf16 v[60:63], v[128:131], v[172:175], v[60:63]
	v_mfma_f32_16x16x32_bf16 v[60:63], v[132:135], v[176:179], v[60:63]
	v_mfma_f32_16x16x32_bf16 v[56:59], v[136:139], v[172:175], v[56:59]
	v_mfma_f32_16x16x32_bf16 v[56:59], v[140:143], v[176:179], v[56:59]
	v_mfma_f32_16x16x32_bf16 v[52:55], v[144:147], v[172:175], v[52:55]
	v_mfma_f32_16x16x32_bf16 v[52:55], v[160:163], v[176:179], v[52:55]
	v_mfma_f32_16x16x32_bf16 v[48:51], v[164:167], v[172:175], v[48:51]
	v_mfma_f32_16x16x32_bf16 v[48:51], v[168:171], v[176:179], v[48:51]
	v_mfma_f32_16x16x32_bf16 v[32:35], v[164:167], v[180:183], v[32:35]
	v_mfma_f32_16x16x32_bf16 v[32:35], v[168:171], v[184:187], v[32:35]
	v_mfma_f32_16x16x32_bf16 v[36:39], v[144:147], v[180:183], v[36:39]
	v_mfma_f32_16x16x32_bf16 v[36:39], v[160:163], v[184:187], v[36:39]
	v_mfma_f32_16x16x32_bf16 v[40:43], v[136:139], v[180:183], v[40:43]
	v_mfma_f32_16x16x32_bf16 v[40:43], v[140:143], v[184:187], v[40:43]
	v_mfma_f32_16x16x32_bf16 v[44:47], v[128:131], v[180:183], v[44:47]
	v_mfma_f32_16x16x32_bf16 v[44:47], v[132:135], v[184:187], v[44:47]
	v_mfma_f32_16x16x32_bf16 v[28:31], v[128:131], v[188:191], v[28:31]
	v_mfma_f32_16x16x32_bf16 v[28:31], v[132:135], v[192:195], v[28:31]
	v_mfma_f32_16x16x32_bf16 v[24:27], v[136:139], v[188:191], v[24:27]
	v_mfma_f32_16x16x32_bf16 v[24:27], v[140:143], v[192:195], v[24:27]
	v_mfma_f32_16x16x32_bf16 v[20:23], v[144:147], v[188:191], v[20:23]
	v_mfma_f32_16x16x32_bf16 v[20:23], v[160:163], v[192:195], v[20:23]
	v_mfma_f32_16x16x32_bf16 v[16:19], v[164:167], v[188:191], v[16:19]
	v_mfma_f32_16x16x32_bf16 v[16:19], v[168:171], v[192:195], v[16:19]
	v_mfma_f32_16x16x32_bf16 v[0:3], v[164:167], v[196:199], v[0:3]
	v_mfma_f32_16x16x32_bf16 v[0:3], v[168:171], v[212:215], v[0:3]
	v_mfma_f32_16x16x32_bf16 v[4:7], v[144:147], v[196:199], v[4:7]
	v_mfma_f32_16x16x32_bf16 v[4:7], v[160:163], v[212:215], v[4:7]
	v_mfma_f32_16x16x32_bf16 v[8:11], v[136:139], v[196:199], v[8:11]
	v_mfma_f32_16x16x32_bf16 v[8:11], v[140:143], v[212:215], v[8:11]
	v_mfma_f32_16x16x32_bf16 v[12:15], v[128:131], v[196:199], v[12:15]
	v_mfma_f32_16x16x32_bf16 v[12:15], v[132:135], v[212:215], v[12:15]
	s_setprio 0
	s_barrier
	s_add_u32 s0, s0, 0x100
	s_addc_u32 s1, s1, 0
	s_add_u32 s38, s38, 0x100
	s_addc_u32 s39, s39, 0
	s_cmp_ge_i32 s41, s56
	s_mov_b32 s6, s41
	s_cbranch_scc0 .LBB0_1159
